# GEMM mainloop: A-fragment LDS reads moved into the MFMA segments (A-major order, in-place register reuse), on top of mixing edits
# baseline (speedup 1.0000x reference)
.LBB0_40:
	s_ashr_i32 s17, s16, 31
	s_lshl_b64 s[18:19], s[16:17], 19
	s_add_u32 s18, s42, s18
	s_addc_u32 s19, s43, s19
	s_and_b64 s[26:27], s[6:7], exec
	s_cselect_b32 s17, s19, s37
	s_cselect_b32 s68, s18, s36
	s_ashr_i32 s15, s14, 31
	s_lshl_b64 s[26:27], s[14:15], 19
	s_add_u32 s26, s48, s26
	s_addc_u32 s27, s49, s27
	s_and_b64 s[46:47], s[6:7], exec
	s_cselect_b32 s15, s27, s45
	s_cselect_b32 s69, s26, s44
	s_add_u32 s36, s36, 0x40080
	s_addc_u32 s37, s37, 0
	s_add_u32 s88, s44, 0x100
	v_mov_b32_e32 v4, 0
	s_addc_u32 s89, s45, 0
	s_mov_b32 s90, -2
	v_mov_b32_e32 v5, v4
	v_mov_b32_e32 v6, v4
	v_mov_b32_e32 v7, v4
	v_mov_b32_e32 v16, v4
	v_mov_b32_e32 v17, v4
	v_mov_b32_e32 v18, v4
	v_mov_b32_e32 v19, v4
	v_mov_b32_e32 v24, v4
	v_mov_b32_e32 v25, v4
	v_mov_b32_e32 v26, v4
	v_mov_b32_e32 v27, v4
	v_mov_b32_e32 v32, v4
	v_mov_b32_e32 v33, v4
	v_mov_b32_e32 v34, v4
	v_mov_b32_e32 v35, v4
	v_mov_b32_e32 v40, v4
	v_mov_b32_e32 v41, v4
	v_mov_b32_e32 v42, v4
	v_mov_b32_e32 v43, v4
	v_mov_b32_e32 v48, v4
	v_mov_b32_e32 v49, v4
	v_mov_b32_e32 v50, v4
	v_mov_b32_e32 v51, v4
	v_mov_b32_e32 v56, v4
	v_mov_b32_e32 v57, v4
	v_mov_b32_e32 v58, v4
	v_mov_b32_e32 v59, v4
	v_mov_b32_e32 v64, v4
	v_mov_b32_e32 v65, v4
	v_mov_b32_e32 v66, v4
	v_mov_b32_e32 v67, v4
	v_mov_b32_e32 v8, v4
	v_mov_b32_e32 v9, v4
	v_mov_b32_e32 v10, v4
	v_mov_b32_e32 v11, v4
	v_mov_b32_e32 v12, v4
	v_mov_b32_e32 v13, v4
	v_mov_b32_e32 v14, v4
	v_mov_b32_e32 v15, v4
	v_mov_b32_e32 v20, v4
	v_mov_b32_e32 v21, v4
	v_mov_b32_e32 v22, v4
	v_mov_b32_e32 v23, v4
	v_mov_b32_e32 v28, v4
	v_mov_b32_e32 v29, v4
	v_mov_b32_e32 v30, v4
	v_mov_b32_e32 v31, v4
	v_mov_b32_e32 v36, v4
	v_mov_b32_e32 v37, v4
	v_mov_b32_e32 v38, v4
	v_mov_b32_e32 v39, v4
	v_mov_b32_e32 v44, v4
	v_mov_b32_e32 v45, v4
	v_mov_b32_e32 v46, v4
	v_mov_b32_e32 v47, v4
	v_mov_b32_e32 v52, v4
	v_mov_b32_e32 v53, v4
	v_mov_b32_e32 v54, v4
	v_mov_b32_e32 v55, v4
	v_mov_b32_e32 v60, v4
	v_mov_b32_e32 v61, v4
	v_mov_b32_e32 v62, v4
	v_mov_b32_e32 v63, v4
	v_mov_b32_e32 v72, v4
	v_mov_b32_e32 v73, v4
	v_mov_b32_e32 v74, v4
	v_mov_b32_e32 v75, v4
	v_mov_b32_e32 v80, v4
	v_mov_b32_e32 v81, v4
	v_mov_b32_e32 v82, v4
	v_mov_b32_e32 v83, v4
	v_mov_b32_e32 v88, v4
	v_mov_b32_e32 v89, v4
	v_mov_b32_e32 v90, v4
	v_mov_b32_e32 v91, v4
	v_mov_b32_e32 v96, v4
	v_mov_b32_e32 v97, v4
	v_mov_b32_e32 v98, v4
	v_mov_b32_e32 v99, v4
	v_mov_b32_e32 v104, v4
	v_mov_b32_e32 v105, v4
	v_mov_b32_e32 v106, v4
	v_mov_b32_e32 v107, v4
	v_mov_b32_e32 v112, v4
	v_mov_b32_e32 v113, v4
	v_mov_b32_e32 v114, v4
	v_mov_b32_e32 v115, v4
	v_mov_b32_e32 v120, v4
	v_mov_b32_e32 v121, v4
	v_mov_b32_e32 v122, v4
	v_mov_b32_e32 v123, v4
	v_mov_b32_e32 v128, v4
	v_mov_b32_e32 v129, v4
	v_mov_b32_e32 v130, v4
	v_mov_b32_e32 v131, v4
	v_mov_b32_e32 v68, v4
	v_mov_b32_e32 v69, v4
	v_mov_b32_e32 v70, v4
	v_mov_b32_e32 v71, v4
	v_mov_b32_e32 v76, v4
	v_mov_b32_e32 v77, v4
	v_mov_b32_e32 v78, v4
	v_mov_b32_e32 v79, v4
	v_mov_b32_e32 v84, v4
	v_mov_b32_e32 v85, v4
	v_mov_b32_e32 v86, v4
	v_mov_b32_e32 v87, v4
	v_mov_b32_e32 v92, v4
	v_mov_b32_e32 v93, v4
	v_mov_b32_e32 v94, v4
	v_mov_b32_e32 v95, v4
	v_mov_b32_e32 v100, v4
	v_mov_b32_e32 v101, v4
	v_mov_b32_e32 v102, v4
	v_mov_b32_e32 v103, v4
	v_mov_b32_e32 v108, v4
	v_mov_b32_e32 v109, v4
	v_mov_b32_e32 v110, v4
	v_mov_b32_e32 v111, v4
	v_mov_b32_e32 v116, v4
	v_mov_b32_e32 v117, v4
	v_mov_b32_e32 v118, v4
	v_mov_b32_e32 v119, v4
	v_mov_b32_e32 v124, v4
	v_mov_b32_e32 v125, v4
	v_mov_b32_e32 v126, v4
	v_mov_b32_e32 v127, v4
	ds_read_b128 v[190:193], v145
	ds_read_b128 v[194:197], v145 offset:1024
	ds_read_b128 v[198:201], v145 offset:2048
	ds_read_b128 v[202:205], v145 offset:3072
	ds_read_b128 v[206:209], v145 offset:4096
	ds_read_b128 v[228:231], v145 offset:5120
	ds_read_b128 v[232:235], v145 offset:6144
	ds_read_b128 v[236:239], v145 offset:7168
.LBB0_41:
	s_add_u32 s40, s36, 0xfffc0080
	s_addc_u32 s41, s37, -1
	s_add_i32 s97, 0, 0x10000
	s_cmp_eq_u32 s90, 12
	s_cselect_b32 s47, s17, s41
	s_cselect_b32 s46, s68, s40
	v_add_u32_e32 v140, s97, v142
	s_cselect_b32 s45, s15, s89
	s_cselect_b32 s44, s69, s88
	s_add_i32 s40, 0, 0x14000
	ds_read_b128 v[146:149], v140
	ds_read_b128 v[150:153], v140 offset:1024
	ds_read_b128 v[154:157], v140 offset:2048
	ds_read_b128 v[158:161], v140 offset:3072
	v_add_u32_e32 v140, s40, v142
	ds_read_b128 v[162:165], v140
	ds_read_b128 v[166:169], v140 offset:1024
	ds_read_b128 v[170:173], v140 offset:2048
	ds_read_b128 v[174:177], v140 offset:3072
	v_lshl_add_u64 v[140:141], s[36:37], 0, v[136:137]
	s_add_i32 m0, s51, 0xc000
	global_load_lds_dwordx4 v[140:141], off
	v_lshl_add_u64 v[140:141], s[36:37], 0, v[138:139]
	s_add_i32 m0, s51, 0xe000
	s_nop 0
	global_load_lds_dwordx4 v[140:141], off
	s_waitcnt vmcnt(8)
	s_waitcnt lgkmcnt(0)
	s_barrier
	s_setprio 1
	s_waitcnt lgkmcnt(0)
	v_mfma_f32_16x16x32_bf16 v[124:127], v[146:149], v[190:193], v[124:127]
	v_mfma_f32_16x16x32_bf16 v[116:119], v[154:157], v[190:193], v[116:119]
	v_mfma_f32_16x16x32_bf16 v[128:131], v[162:165], v[190:193], v[128:131]
	v_mfma_f32_16x16x32_bf16 v[120:123], v[170:173], v[190:193], v[120:123]
	ds_read_b128 v[190:193], v145 offset:16384
	v_mfma_f32_16x16x32_bf16 v[108:111], v[146:149], v[198:201], v[108:111]
	v_mfma_f32_16x16x32_bf16 v[100:103], v[154:157], v[198:201], v[100:103]
	v_mfma_f32_16x16x32_bf16 v[112:115], v[162:165], v[198:201], v[112:115]
	v_mfma_f32_16x16x32_bf16 v[104:107], v[170:173], v[198:201], v[104:107]
	ds_read_b128 v[198:201], v145 offset:18432
	v_mfma_f32_16x16x32_bf16 v[92:95], v[146:149], v[206:209], v[92:95]
	v_mfma_f32_16x16x32_bf16 v[84:87], v[154:157], v[206:209], v[84:87]
	v_mfma_f32_16x16x32_bf16 v[96:99], v[162:165], v[206:209], v[96:99]
	v_mfma_f32_16x16x32_bf16 v[88:91], v[170:173], v[206:209], v[88:91]
	ds_read_b128 v[206:209], v145 offset:20480
	v_mfma_f32_16x16x32_bf16 v[76:79], v[146:149], v[232:235], v[76:79]
	v_mfma_f32_16x16x32_bf16 v[68:71], v[154:157], v[232:235], v[68:71]
	v_mfma_f32_16x16x32_bf16 v[80:83], v[162:165], v[232:235], v[80:83]
	v_mfma_f32_16x16x32_bf16 v[72:75], v[170:173], v[232:235], v[72:75]
	ds_read_b128 v[232:235], v145 offset:22528
	v_mfma_f32_16x16x32_bf16 v[124:127], v[150:153], v[194:197], v[124:127]
	v_mfma_f32_16x16x32_bf16 v[116:119], v[158:161], v[194:197], v[116:119]
	v_mfma_f32_16x16x32_bf16 v[128:131], v[166:169], v[194:197], v[128:131]
	v_mfma_f32_16x16x32_bf16 v[120:123], v[174:177], v[194:197], v[120:123]
	ds_read_b128 v[194:197], v145 offset:17408
	v_mfma_f32_16x16x32_bf16 v[108:111], v[150:153], v[202:205], v[108:111]
	v_mfma_f32_16x16x32_bf16 v[100:103], v[158:161], v[202:205], v[100:103]
	v_mfma_f32_16x16x32_bf16 v[112:115], v[166:169], v[202:205], v[112:115]
	v_mfma_f32_16x16x32_bf16 v[104:107], v[174:177], v[202:205], v[104:107]
	ds_read_b128 v[202:205], v145 offset:19456
	v_mfma_f32_16x16x32_bf16 v[92:95], v[150:153], v[228:231], v[92:95]
	v_mfma_f32_16x16x32_bf16 v[84:87], v[158:161], v[228:231], v[84:87]
	v_mfma_f32_16x16x32_bf16 v[96:99], v[166:169], v[228:231], v[96:99]
	v_mfma_f32_16x16x32_bf16 v[88:91], v[174:177], v[228:231], v[88:91]
	ds_read_b128 v[228:231], v145 offset:21504
	v_mfma_f32_16x16x32_bf16 v[76:79], v[150:153], v[236:239], v[76:79]
	v_mfma_f32_16x16x32_bf16 v[68:71], v[158:161], v[236:239], v[68:71]
	v_mfma_f32_16x16x32_bf16 v[80:83], v[166:169], v[236:239], v[80:83]
	v_mfma_f32_16x16x32_bf16 v[72:75], v[174:177], v[236:239], v[72:75]
	ds_read_b128 v[236:239], v145 offset:23552
	s_setprio 0
	s_waitcnt vmcnt(2)
	s_barrier
	s_add_i32 s41, s97, s50
	v_lshl_add_u64 v[140:141], s[44:45], 0, v[180:181]
	s_mov_b32 m0, s41
	global_load_lds_dwordx4 v[140:141], off
	s_add_i32 m0, s41, 0x2000
	s_add_u32 vcc_lo, s44, 0x40000
	v_lshl_add_u64 v[178:179], s[44:45], 0, v[134:135]
	s_addc_u32 vcc_hi, s45, 0
	s_add_i32 s40, s40, s50
	global_load_lds_dwordx4 v[178:179], off
	v_lshl_add_u64 v[210:211], vcc, 0, v[180:181]
	s_mov_b32 m0, s40
	v_lshl_add_u64 v[218:219], s[46:47], 0, v[132:133]
	global_load_lds_dwordx4 v[210:211], off
	v_lshl_add_u64 v[210:211], vcc, 0, v[134:135]
	s_add_i32 m0, s40, 0x2000
	s_nop 0
	global_load_lds_dwordx4 v[210:211], off
	v_lshl_add_u64 v[210:211], s[46:47], 0, v[0:1]
	s_mov_b32 m0, s51
	s_nop 0
	global_load_lds_dwordx4 v[210:211], off
	s_mov_b32 m0, s52
	s_nop 0
	global_load_lds_dwordx4 v[218:219], off
	s_waitcnt vmcnt(8)
	s_waitcnt lgkmcnt(0)
	s_barrier
	s_setprio 1
	s_waitcnt lgkmcnt(0)
	v_mfma_f32_16x16x32_bf16 v[60:63], v[146:149], v[190:193], v[60:63]
	v_mfma_f32_16x16x32_bf16 v[52:55], v[154:157], v[190:193], v[52:55]
	v_mfma_f32_16x16x32_bf16 v[64:67], v[162:165], v[190:193], v[64:67]
	v_mfma_f32_16x16x32_bf16 v[56:59], v[170:173], v[190:193], v[56:59]
	ds_read_b128 v[190:193], v145 offset:32768
	v_mfma_f32_16x16x32_bf16 v[44:47], v[146:149], v[198:201], v[44:47]
	v_mfma_f32_16x16x32_bf16 v[36:39], v[154:157], v[198:201], v[36:39]
	v_mfma_f32_16x16x32_bf16 v[48:51], v[162:165], v[198:201], v[48:51]
	v_mfma_f32_16x16x32_bf16 v[40:43], v[170:173], v[198:201], v[40:43]
	ds_read_b128 v[198:201], v145 offset:34816
	v_mfma_f32_16x16x32_bf16 v[28:31], v[146:149], v[206:209], v[28:31]
	v_mfma_f32_16x16x32_bf16 v[20:23], v[154:157], v[206:209], v[20:23]
	v_mfma_f32_16x16x32_bf16 v[32:35], v[162:165], v[206:209], v[32:35]
	v_mfma_f32_16x16x32_bf16 v[24:27], v[170:173], v[206:209], v[24:27]
	ds_read_b128 v[206:209], v145 offset:36864
	v_mfma_f32_16x16x32_bf16 v[12:15], v[146:149], v[232:235], v[12:15]
	v_mfma_f32_16x16x32_bf16 v[8:11], v[154:157], v[232:235], v[8:11]
	v_mfma_f32_16x16x32_bf16 v[16:19], v[162:165], v[232:235], v[16:19]
	v_mfma_f32_16x16x32_bf16 v[4:7], v[170:173], v[232:235], v[4:7]
	ds_read_b128 v[232:235], v145 offset:38912
	v_mfma_f32_16x16x32_bf16 v[60:63], v[150:153], v[194:197], v[60:63]
	v_mfma_f32_16x16x32_bf16 v[52:55], v[158:161], v[194:197], v[52:55]
	v_mfma_f32_16x16x32_bf16 v[64:67], v[166:169], v[194:197], v[64:67]
	v_mfma_f32_16x16x32_bf16 v[56:59], v[174:177], v[194:197], v[56:59]
	ds_read_b128 v[194:197], v145 offset:33792
	v_mfma_f32_16x16x32_bf16 v[44:47], v[150:153], v[202:205], v[44:47]
	v_mfma_f32_16x16x32_bf16 v[36:39], v[158:161], v[202:205], v[36:39]
	v_mfma_f32_16x16x32_bf16 v[48:51], v[166:169], v[202:205], v[48:51]
	v_mfma_f32_16x16x32_bf16 v[40:43], v[174:177], v[202:205], v[40:43]
	ds_read_b128 v[202:205], v145 offset:35840
	v_mfma_f32_16x16x32_bf16 v[28:31], v[150:153], v[228:231], v[28:31]
	v_mfma_f32_16x16x32_bf16 v[20:23], v[158:161], v[228:231], v[20:23]
	v_mfma_f32_16x16x32_bf16 v[32:35], v[166:169], v[228:231], v[32:35]
	v_mfma_f32_16x16x32_bf16 v[24:27], v[174:177], v[228:231], v[24:27]
	ds_read_b128 v[228:231], v145 offset:37888
	v_mfma_f32_16x16x32_bf16 v[12:15], v[150:153], v[236:239], v[12:15]
	v_mfma_f32_16x16x32_bf16 v[8:11], v[158:161], v[236:239], v[8:11]
	v_mfma_f32_16x16x32_bf16 v[16:19], v[166:169], v[236:239], v[16:19]
	v_mfma_f32_16x16x32_bf16 v[4:7], v[174:177], v[236:239], v[4:7]
	ds_read_b128 v[236:239], v145 offset:39936
	s_setprio 0
	s_waitcnt vmcnt(6)
	s_barrier
	s_add_i32 s40, 0, 0x18000
	s_add_i32 s41, 0, 0x1c000
	v_add_u32_e32 v158, s40, v142
	v_add_u32_e32 v174, s41, v142
	ds_read_b128 v[146:149], v158
	ds_read_b128 v[150:153], v158 offset:1024
	ds_read_b128 v[154:157], v158 offset:2048
	ds_read_b128 v[158:161], v158 offset:3072
	ds_read_b128 v[162:165], v174
	ds_read_b128 v[166:169], v174 offset:1024
	ds_read_b128 v[170:173], v174 offset:2048
	ds_read_b128 v[174:177], v174 offset:3072
	s_add_u32 s46, s46, 0x40000
	s_addc_u32 s47, s47, 0
	s_mov_b32 m0, s53
	v_lshl_add_u64 v[220:221], s[46:47], 0, v[0:1]
	global_load_lds_dwordx4 v[220:221], off
	v_lshl_add_u64 v[220:221], s[46:47], 0, v[132:133]
	s_mov_b32 m0, s54
	s_nop 0
	global_load_lds_dwordx4 v[220:221], off
	s_waitcnt vmcnt(8)
	s_waitcnt lgkmcnt(0)
	s_barrier
	s_setprio 1
	s_waitcnt lgkmcnt(0)
	v_mfma_f32_16x16x32_bf16 v[124:127], v[146:149], v[190:193], v[124:127]
	v_mfma_f32_16x16x32_bf16 v[116:119], v[154:157], v[190:193], v[116:119]
	v_mfma_f32_16x16x32_bf16 v[128:131], v[162:165], v[190:193], v[128:131]
	v_mfma_f32_16x16x32_bf16 v[120:123], v[170:173], v[190:193], v[120:123]
	ds_read_b128 v[190:193], v145 offset:49152
	v_mfma_f32_16x16x32_bf16 v[108:111], v[146:149], v[198:201], v[108:111]
	v_mfma_f32_16x16x32_bf16 v[100:103], v[154:157], v[198:201], v[100:103]
	v_mfma_f32_16x16x32_bf16 v[112:115], v[162:165], v[198:201], v[112:115]
	v_mfma_f32_16x16x32_bf16 v[104:107], v[170:173], v[198:201], v[104:107]
	ds_read_b128 v[198:201], v145 offset:51200
	v_mfma_f32_16x16x32_bf16 v[92:95], v[146:149], v[206:209], v[92:95]
	v_mfma_f32_16x16x32_bf16 v[84:87], v[154:157], v[206:209], v[84:87]
	v_mfma_f32_16x16x32_bf16 v[96:99], v[162:165], v[206:209], v[96:99]
	v_mfma_f32_16x16x32_bf16 v[88:91], v[170:173], v[206:209], v[88:91]
	ds_read_b128 v[206:209], v145 offset:53248
	v_mfma_f32_16x16x32_bf16 v[76:79], v[146:149], v[232:235], v[76:79]
	v_mfma_f32_16x16x32_bf16 v[68:71], v[154:157], v[232:235], v[68:71]
	v_mfma_f32_16x16x32_bf16 v[80:83], v[162:165], v[232:235], v[80:83]
	v_mfma_f32_16x16x32_bf16 v[72:75], v[170:173], v[232:235], v[72:75]
	ds_read_b128 v[232:235], v145 offset:55296
	v_mfma_f32_16x16x32_bf16 v[124:127], v[150:153], v[194:197], v[124:127]
	v_mfma_f32_16x16x32_bf16 v[116:119], v[158:161], v[194:197], v[116:119]
	v_mfma_f32_16x16x32_bf16 v[128:131], v[166:169], v[194:197], v[128:131]
	v_mfma_f32_16x16x32_bf16 v[120:123], v[174:177], v[194:197], v[120:123]
	ds_read_b128 v[194:197], v145 offset:50176
	v_mfma_f32_16x16x32_bf16 v[108:111], v[150:153], v[202:205], v[108:111]
	v_mfma_f32_16x16x32_bf16 v[100:103], v[158:161], v[202:205], v[100:103]
	v_mfma_f32_16x16x32_bf16 v[112:115], v[166:169], v[202:205], v[112:115]
	v_mfma_f32_16x16x32_bf16 v[104:107], v[174:177], v[202:205], v[104:107]
	ds_read_b128 v[202:205], v145 offset:52224
	v_mfma_f32_16x16x32_bf16 v[92:95], v[150:153], v[228:231], v[92:95]
	v_mfma_f32_16x16x32_bf16 v[84:87], v[158:161], v[228:231], v[84:87]
	v_mfma_f32_16x16x32_bf16 v[96:99], v[166:169], v[228:231], v[96:99]
	v_mfma_f32_16x16x32_bf16 v[88:91], v[174:177], v[228:231], v[88:91]
	ds_read_b128 v[228:231], v145 offset:54272
	v_mfma_f32_16x16x32_bf16 v[76:79], v[150:153], v[236:239], v[76:79]
	v_mfma_f32_16x16x32_bf16 v[68:71], v[158:161], v[236:239], v[68:71]
	v_mfma_f32_16x16x32_bf16 v[80:83], v[166:169], v[236:239], v[80:83]
	v_mfma_f32_16x16x32_bf16 v[72:75], v[174:177], v[236:239], v[72:75]
	ds_read_b128 v[236:239], v145 offset:56320
	s_setprio 0
	s_waitcnt vmcnt(2)
	s_barrier
	s_add_i32 s40, s40, s50
	v_lshl_add_u64 v[140:141], v[140:141], 0, s[94:95]
	s_mov_b32 m0, s40
	global_load_lds_dwordx4 v[140:141], off
	s_add_i32 m0, s40, 0x2000
	s_add_u32 s44, s44, 0x40080
	v_lshl_add_u64 v[140:141], v[178:179], 0, s[94:95]
	s_addc_u32 s45, s45, 0
	s_add_i32 s40, s41, s50
	global_load_lds_dwordx4 v[140:141], off
	v_lshl_add_u64 v[140:141], s[44:45], 0, v[180:181]
	s_mov_b32 m0, s40
	s_nop 0
	global_load_lds_dwordx4 v[140:141], off
	v_lshl_add_u64 v[140:141], s[44:45], 0, v[134:135]
	s_add_i32 m0, s40, 0x2000
	s_nop 0
	global_load_lds_dwordx4 v[140:141], off
	v_lshl_add_u64 v[140:141], v[210:211], 0, s[94:95]
	s_mov_b32 m0, s55
	s_nop 0
	global_load_lds_dwordx4 v[140:141], off
	v_lshl_add_u64 v[140:141], v[218:219], 0, s[94:95]
	s_mov_b32 m0, s58
	s_nop 0
	global_load_lds_dwordx4 v[140:141], off
	s_waitcnt vmcnt(8)
	s_waitcnt lgkmcnt(0)
	s_barrier
	s_setprio 1
	s_waitcnt lgkmcnt(0)
	v_mfma_f32_16x16x32_bf16 v[60:63], v[146:149], v[190:193], v[60:63]
	v_mfma_f32_16x16x32_bf16 v[52:55], v[154:157], v[190:193], v[52:55]
	v_mfma_f32_16x16x32_bf16 v[64:67], v[162:165], v[190:193], v[64:67]
	v_mfma_f32_16x16x32_bf16 v[56:59], v[170:173], v[190:193], v[56:59]
	ds_read_b128 v[190:193], v145
	v_mfma_f32_16x16x32_bf16 v[44:47], v[146:149], v[198:201], v[44:47]
	v_mfma_f32_16x16x32_bf16 v[36:39], v[154:157], v[198:201], v[36:39]
	v_mfma_f32_16x16x32_bf16 v[48:51], v[162:165], v[198:201], v[48:51]
	v_mfma_f32_16x16x32_bf16 v[40:43], v[170:173], v[198:201], v[40:43]
	ds_read_b128 v[198:201], v145 offset:2048
	v_mfma_f32_16x16x32_bf16 v[28:31], v[146:149], v[206:209], v[28:31]
	v_mfma_f32_16x16x32_bf16 v[20:23], v[154:157], v[206:209], v[20:23]
	v_mfma_f32_16x16x32_bf16 v[32:35], v[162:165], v[206:209], v[32:35]
	v_mfma_f32_16x16x32_bf16 v[24:27], v[170:173], v[206:209], v[24:27]
	ds_read_b128 v[206:209], v145 offset:4096
	v_mfma_f32_16x16x32_bf16 v[12:15], v[146:149], v[232:235], v[12:15]
	v_mfma_f32_16x16x32_bf16 v[8:11], v[154:157], v[232:235], v[8:11]
	v_mfma_f32_16x16x32_bf16 v[16:19], v[162:165], v[232:235], v[16:19]
	v_mfma_f32_16x16x32_bf16 v[4:7], v[170:173], v[232:235], v[4:7]
	ds_read_b128 v[232:235], v145 offset:6144
	v_mfma_f32_16x16x32_bf16 v[60:63], v[150:153], v[194:197], v[60:63]
	v_mfma_f32_16x16x32_bf16 v[52:55], v[158:161], v[194:197], v[52:55]
	v_mfma_f32_16x16x32_bf16 v[64:67], v[166:169], v[194:197], v[64:67]
	v_mfma_f32_16x16x32_bf16 v[56:59], v[174:177], v[194:197], v[56:59]
	ds_read_b128 v[194:197], v145 offset:1024
	v_mfma_f32_16x16x32_bf16 v[44:47], v[150:153], v[202:205], v[44:47]
	v_mfma_f32_16x16x32_bf16 v[36:39], v[158:161], v[202:205], v[36:39]
	v_mfma_f32_16x16x32_bf16 v[48:51], v[166:169], v[202:205], v[48:51]
	v_mfma_f32_16x16x32_bf16 v[40:43], v[174:177], v[202:205], v[40:43]
	ds_read_b128 v[202:205], v145 offset:3072
	v_mfma_f32_16x16x32_bf16 v[28:31], v[150:153], v[228:231], v[28:31]
	v_mfma_f32_16x16x32_bf16 v[20:23], v[158:161], v[228:231], v[20:23]
	v_mfma_f32_16x16x32_bf16 v[32:35], v[166:169], v[228:231], v[32:35]
	v_mfma_f32_16x16x32_bf16 v[24:27], v[174:177], v[228:231], v[24:27]
	ds_read_b128 v[228:231], v145 offset:5120
	v_mfma_f32_16x16x32_bf16 v[12:15], v[150:153], v[236:239], v[12:15]
	v_mfma_f32_16x16x32_bf16 v[8:11], v[158:161], v[236:239], v[8:11]
	v_mfma_f32_16x16x32_bf16 v[16:19], v[166:169], v[236:239], v[16:19]
	v_mfma_f32_16x16x32_bf16 v[4:7], v[174:177], v[236:239], v[4:7]
	ds_read_b128 v[236:239], v145 offset:7168
	s_setprio 0
	s_waitcnt vmcnt(6)
	s_barrier
	s_add_i32 s90, s90, 2
	s_add_u32 s36, s36, 0x100
	s_addc_u32 s37, s37, 0
	s_add_u32 s88, s88, 0x100
	s_addc_u32 s89, s89, 0
	s_cmp_gt_u32 s90, 13
	s_cbranch_scc0 .LBB0_41
	s_waitcnt lgkmcnt(0)
	s_and_b64 vcc, exec, s[10:11]
	s_cbranch_vccz .LBB0_44
	s_barrier

.LBB0_82:
	s_ashr_i32 s27, s26, 31
	s_lshl_b64 s[44:45], s[26:27], 19
	v_readlane_b32 s19, v250, 16
	s_add_u32 s44, s19, s44
	v_readlane_b32 s19, v250, 17
	s_addc_u32 s45, s19, s45
	s_and_b64 s[46:47], s[36:37], exec
	s_cselect_b32 s27, s45, s9
	s_cselect_b32 s89, s44, s8
	s_ashr_i32 s19, s18, 31
	s_lshl_b64 s[46:47], s[18:19], 19
	v_readlane_b32 s19, v250, 18
	s_add_u32 s46, s19, s46
	v_readlane_b32 s19, v250, 19
	s_addc_u32 s47, s19, s47
	s_and_b64 s[52:53], s[36:37], exec
	s_cselect_b32 s19, s47, s11
	s_cselect_b32 s90, s46, s10
	s_add_u32 s8, s8, 0x40080
	s_addc_u32 s9, s9, 0
	s_add_u32 s97, s10, 0x100
	v_mov_b32_e32 v4, 0
	v_mov_b64_e32 v[186:187], 0xff
	v_mov_b64_e32 v[188:189], 0x100
	s_addc_u32 vcc_lo, s11, 0
	s_mov_b32 vcc_hi, -2
	v_mov_b32_e32 v5, v4
	v_mov_b32_e32 v6, v4
	v_mov_b32_e32 v7, v4
	v_mov_b32_e32 v8, v4
	v_mov_b32_e32 v9, v4
	v_mov_b32_e32 v10, v4
	v_mov_b32_e32 v11, v4
	v_mov_b32_e32 v20, v4
	v_mov_b32_e32 v21, v4
	v_mov_b32_e32 v22, v4
	v_mov_b32_e32 v23, v4
	v_mov_b32_e32 v24, v4
	v_mov_b32_e32 v25, v4
	v_mov_b32_e32 v26, v4
	v_mov_b32_e32 v27, v4
	v_mov_b32_e32 v36, v4
	v_mov_b32_e32 v37, v4
	v_mov_b32_e32 v38, v4
	v_mov_b32_e32 v39, v4
	v_mov_b32_e32 v40, v4
	v_mov_b32_e32 v41, v4
	v_mov_b32_e32 v42, v4
	v_mov_b32_e32 v43, v4
	v_mov_b32_e32 v52, v4
	v_mov_b32_e32 v53, v4
	v_mov_b32_e32 v54, v4
	v_mov_b32_e32 v55, v4
	v_mov_b32_e32 v56, v4
	v_mov_b32_e32 v57, v4
	v_mov_b32_e32 v58, v4
	v_mov_b32_e32 v59, v4
	v_mov_b32_e32 v12, v4
	v_mov_b32_e32 v13, v4
	v_mov_b32_e32 v14, v4
	v_mov_b32_e32 v15, v4
	v_mov_b32_e32 v16, v4
	v_mov_b32_e32 v17, v4
	v_mov_b32_e32 v18, v4
	v_mov_b32_e32 v19, v4
	v_mov_b32_e32 v28, v4
	v_mov_b32_e32 v29, v4
	v_mov_b32_e32 v30, v4
	v_mov_b32_e32 v31, v4
	v_mov_b32_e32 v32, v4
	v_mov_b32_e32 v33, v4
	v_mov_b32_e32 v34, v4
	v_mov_b32_e32 v35, v4
	v_mov_b32_e32 v44, v4
	v_mov_b32_e32 v45, v4
	v_mov_b32_e32 v46, v4
	v_mov_b32_e32 v47, v4
	v_mov_b32_e32 v48, v4
	v_mov_b32_e32 v49, v4
	v_mov_b32_e32 v50, v4
	v_mov_b32_e32 v51, v4
	v_mov_b32_e32 v60, v4
	v_mov_b32_e32 v61, v4
	v_mov_b32_e32 v62, v4
	v_mov_b32_e32 v63, v4
	v_mov_b32_e32 v64, v4
	v_mov_b32_e32 v65, v4
	v_mov_b32_e32 v66, v4
	v_mov_b32_e32 v67, v4
	v_mov_b32_e32 v68, v4
	v_mov_b32_e32 v69, v4
	v_mov_b32_e32 v70, v4
	v_mov_b32_e32 v71, v4
	v_mov_b32_e32 v72, v4
	v_mov_b32_e32 v73, v4
	v_mov_b32_e32 v74, v4
	v_mov_b32_e32 v75, v4
	v_mov_b32_e32 v84, v4
	v_mov_b32_e32 v85, v4
	v_mov_b32_e32 v86, v4
	v_mov_b32_e32 v87, v4
	v_mov_b32_e32 v88, v4
	v_mov_b32_e32 v89, v4
	v_mov_b32_e32 v90, v4
	v_mov_b32_e32 v91, v4
	v_mov_b32_e32 v100, v4
	v_mov_b32_e32 v101, v4
	v_mov_b32_e32 v102, v4
	v_mov_b32_e32 v103, v4
	v_mov_b32_e32 v104, v4
	v_mov_b32_e32 v105, v4
	v_mov_b32_e32 v106, v4
	v_mov_b32_e32 v107, v4
	v_mov_b32_e32 v116, v4
	v_mov_b32_e32 v117, v4
	v_mov_b32_e32 v118, v4
	v_mov_b32_e32 v119, v4
	v_mov_b32_e32 v120, v4
	v_mov_b32_e32 v121, v4
	v_mov_b32_e32 v122, v4
	v_mov_b32_e32 v123, v4
	v_mov_b32_e32 v76, v4
	v_mov_b32_e32 v77, v4
	v_mov_b32_e32 v78, v4
	v_mov_b32_e32 v79, v4
	v_mov_b32_e32 v80, v4
	v_mov_b32_e32 v81, v4
	v_mov_b32_e32 v82, v4
	v_mov_b32_e32 v83, v4
	v_mov_b32_e32 v92, v4
	v_mov_b32_e32 v93, v4
	v_mov_b32_e32 v94, v4
	v_mov_b32_e32 v95, v4
	v_mov_b32_e32 v96, v4
	v_mov_b32_e32 v97, v4
	v_mov_b32_e32 v98, v4
	v_mov_b32_e32 v99, v4
	v_mov_b32_e32 v108, v4
	v_mov_b32_e32 v109, v4
	v_mov_b32_e32 v110, v4
	v_mov_b32_e32 v111, v4
	v_mov_b32_e32 v112, v4
	v_mov_b32_e32 v113, v4
	v_mov_b32_e32 v114, v4
	v_mov_b32_e32 v115, v4
	v_mov_b32_e32 v124, v4
	v_mov_b32_e32 v125, v4
	v_mov_b32_e32 v126, v4
	v_mov_b32_e32 v127, v4
	v_mov_b32_e32 v128, v4
	v_mov_b32_e32 v129, v4
	v_mov_b32_e32 v130, v4
	v_mov_b32_e32 v131, v4
	ds_read_b128 v[206:209], v179
	ds_read_b128 v[228:231], v179 offset:1024
	ds_read_b128 v[232:235], v179 offset:2048
	ds_read_b128 v[236:239], v179 offset:3072
	ds_read_b128 v[240:243], v179 offset:4096
	ds_read_b128 v[244:247], v179 offset:5120
	ds_read_b128 v[224:227], v179 offset:6144
	ds_read_b128 v[218:221], v179 offset:7168
.LBB0_83:
	s_add_u32 s10, s8, 0xfffc0080
	s_addc_u32 s11, s9, -1
	s_add_i32 s40, 0, 0x10000
	s_cmp_eq_u32 vcc_hi, 12
	s_cselect_b32 s53, s27, s11
	s_cselect_b32 s52, s89, s10
	s_cselect_b32 s11, s19, vcc_lo
	s_cselect_b32 s10, s90, s97
	s_add_i32 s25, 0, 0x14000
	v_add_u32_e32 v144, s40, v159
	v_add_u32_e32 v158, s25, v159
	ds_read_b128 v[132:135], v144
	ds_read_b128 v[136:139], v144 offset:1024
	ds_read_b128 v[140:143], v144 offset:2048
	ds_read_b128 v[144:147], v144 offset:3072
	ds_read_b128 v[190:193], v158
	ds_read_b128 v[194:197], v158 offset:1024
	ds_read_b128 v[198:201], v158 offset:2048
	ds_read_b128 v[202:205], v158 offset:3072
	v_lshl_add_u64 v[174:175], s[8:9], 0, v[154:155]
	s_add_i32 m0, s49, 0xc000
	global_load_lds_dwordx4 v[174:175], off
	v_lshl_add_u64 v[174:175], s[8:9], 0, v[156:157]
	s_add_i32 m0, s49, 0xe000
	s_nop 0
	global_load_lds_dwordx4 v[174:175], off
	s_waitcnt vmcnt(8)
	s_waitcnt lgkmcnt(0)
	s_barrier
	s_setprio 1
	s_waitcnt lgkmcnt(0)
	v_mfma_f32_16x16x32_bf16 v[128:131], v[132:135], v[206:209], v[128:131]
	v_mfma_f32_16x16x32_bf16 v[124:127], v[140:143], v[206:209], v[124:127]
	v_mfma_f32_16x16x32_bf16 v[120:123], v[190:193], v[206:209], v[120:123]
	v_mfma_f32_16x16x32_bf16 v[116:119], v[198:201], v[206:209], v[116:119]
	ds_read_b128 v[206:209], v179 offset:16384
	v_mfma_f32_16x16x32_bf16 v[112:115], v[132:135], v[232:235], v[112:115]
	v_mfma_f32_16x16x32_bf16 v[108:111], v[140:143], v[232:235], v[108:111]
	v_mfma_f32_16x16x32_bf16 v[104:107], v[190:193], v[232:235], v[104:107]
	v_mfma_f32_16x16x32_bf16 v[100:103], v[198:201], v[232:235], v[100:103]
	ds_read_b128 v[232:235], v179 offset:20480
	v_mfma_f32_16x16x32_bf16 v[96:99], v[132:135], v[240:243], v[96:99]
	v_mfma_f32_16x16x32_bf16 v[92:95], v[140:143], v[240:243], v[92:95]
	v_mfma_f32_16x16x32_bf16 v[88:91], v[190:193], v[240:243], v[88:91]
	v_mfma_f32_16x16x32_bf16 v[84:87], v[198:201], v[240:243], v[84:87]
	ds_read_b128 v[240:243], v179 offset:22528
	v_mfma_f32_16x16x32_bf16 v[80:83], v[132:135], v[224:227], v[80:83]
	v_mfma_f32_16x16x32_bf16 v[76:79], v[140:143], v[224:227], v[76:79]
	v_mfma_f32_16x16x32_bf16 v[72:75], v[190:193], v[224:227], v[72:75]
	v_mfma_f32_16x16x32_bf16 v[68:71], v[198:201], v[224:227], v[68:71]
	ds_read_b128 v[224:227], v179 offset:18432
	v_mfma_f32_16x16x32_bf16 v[128:131], v[136:139], v[228:231], v[128:131]
	v_mfma_f32_16x16x32_bf16 v[124:127], v[144:147], v[228:231], v[124:127]
	v_mfma_f32_16x16x32_bf16 v[120:123], v[194:197], v[228:231], v[120:123]
	v_mfma_f32_16x16x32_bf16 v[116:119], v[202:205], v[228:231], v[116:119]
	ds_read_b128 v[228:231], v179 offset:19456
	v_mfma_f32_16x16x32_bf16 v[112:115], v[136:139], v[236:239], v[112:115]
	v_mfma_f32_16x16x32_bf16 v[108:111], v[144:147], v[236:239], v[108:111]
	v_mfma_f32_16x16x32_bf16 v[104:107], v[194:197], v[236:239], v[104:107]
	v_mfma_f32_16x16x32_bf16 v[100:103], v[202:205], v[236:239], v[100:103]
	ds_read_b128 v[236:239], v179 offset:21504
	v_mfma_f32_16x16x32_bf16 v[96:99], v[136:139], v[244:247], v[96:99]
	v_mfma_f32_16x16x32_bf16 v[92:95], v[144:147], v[244:247], v[92:95]
	v_mfma_f32_16x16x32_bf16 v[88:91], v[194:197], v[244:247], v[88:91]
	v_mfma_f32_16x16x32_bf16 v[84:87], v[202:205], v[244:247], v[84:87]
	ds_read_b128 v[244:247], v179 offset:23552
	v_mfma_f32_16x16x32_bf16 v[80:83], v[136:139], v[218:221], v[80:83]
	v_mfma_f32_16x16x32_bf16 v[76:79], v[144:147], v[218:221], v[76:79]
	v_mfma_f32_16x16x32_bf16 v[72:75], v[194:197], v[218:221], v[72:75]
	v_mfma_f32_16x16x32_bf16 v[68:71], v[202:205], v[218:221], v[68:71]
	ds_read_b128 v[218:221], v179 offset:17408
	s_setprio 0
	s_waitcnt vmcnt(2)
	s_barrier
	s_add_i32 s40, s40, s55
	v_lshl_add_u64 v[174:175], s[10:11], 0, v[180:181]
	s_mov_b32 m0, s40
	global_load_lds_dwordx4 v[174:175], off
	s_add_i32 m0, s40, 0x2000
	s_add_u32 s40, s10, 0x40000
	v_lshl_add_u64 v[210:211], s[10:11], 0, v[150:151]
	s_addc_u32 s41, s11, 0
	s_add_i32 s25, s25, s55
	global_load_lds_dwordx4 v[210:211], off
	v_lshl_add_u64 v[248:249], s[40:41], 0, v[180:181]
	s_mov_b32 m0, s25
	v_lshl_add_u64 v[182:183], s[52:53], 0, v[148:149]
	global_load_lds_dwordx4 v[248:249], off
	v_lshl_add_u64 v[248:249], s[40:41], 0, v[150:151]
	s_add_i32 m0, s25, 0x2000
	s_nop 0
	global_load_lds_dwordx4 v[248:249], off
	v_lshl_add_u64 v[248:249], s[52:53], 0, v[0:1]
	s_mov_b32 m0, s49
	s_nop 0
	global_load_lds_dwordx4 v[248:249], off
	s_mov_b32 m0, s51
	s_nop 0
	global_load_lds_dwordx4 v[182:183], off
	s_waitcnt vmcnt(8)
	s_waitcnt lgkmcnt(0)
	s_barrier
	s_setprio 1
	s_waitcnt lgkmcnt(0)
	v_mfma_f32_16x16x32_bf16 v[64:67], v[132:135], v[206:209], v[64:67]
	v_mfma_f32_16x16x32_bf16 v[60:63], v[140:143], v[206:209], v[60:63]
	v_mfma_f32_16x16x32_bf16 v[56:59], v[190:193], v[206:209], v[56:59]
	v_mfma_f32_16x16x32_bf16 v[52:55], v[198:201], v[206:209], v[52:55]
	ds_read_b128 v[206:209], v179 offset:32768
	v_mfma_f32_16x16x32_bf16 v[48:51], v[132:135], v[224:227], v[48:51]
	v_mfma_f32_16x16x32_bf16 v[44:47], v[140:143], v[224:227], v[44:47]
	v_mfma_f32_16x16x32_bf16 v[40:43], v[190:193], v[224:227], v[40:43]
	v_mfma_f32_16x16x32_bf16 v[36:39], v[198:201], v[224:227], v[36:39]
	ds_read_b128 v[224:227], v179 offset:34816
	v_mfma_f32_16x16x32_bf16 v[32:35], v[132:135], v[232:235], v[32:35]
	v_mfma_f32_16x16x32_bf16 v[28:31], v[140:143], v[232:235], v[28:31]
	v_mfma_f32_16x16x32_bf16 v[24:27], v[190:193], v[232:235], v[24:27]
	v_mfma_f32_16x16x32_bf16 v[20:23], v[198:201], v[232:235], v[20:23]
	ds_read_b128 v[232:235], v179 offset:36864
	v_mfma_f32_16x16x32_bf16 v[16:19], v[132:135], v[240:243], v[16:19]
	v_mfma_f32_16x16x32_bf16 v[12:15], v[140:143], v[240:243], v[12:15]
	v_mfma_f32_16x16x32_bf16 v[8:11], v[190:193], v[240:243], v[8:11]
	v_mfma_f32_16x16x32_bf16 v[4:7], v[198:201], v[240:243], v[4:7]
	ds_read_b128 v[240:243], v179 offset:38912
	v_mfma_f32_16x16x32_bf16 v[64:67], v[136:139], v[218:221], v[64:67]
	v_mfma_f32_16x16x32_bf16 v[60:63], v[144:147], v[218:221], v[60:63]
	v_mfma_f32_16x16x32_bf16 v[56:59], v[194:197], v[218:221], v[56:59]
	v_mfma_f32_16x16x32_bf16 v[52:55], v[202:205], v[218:221], v[52:55]
	ds_read_b128 v[218:221], v179 offset:33792
	v_mfma_f32_16x16x32_bf16 v[48:51], v[136:139], v[228:231], v[48:51]
	v_mfma_f32_16x16x32_bf16 v[44:47], v[144:147], v[228:231], v[44:47]
	v_mfma_f32_16x16x32_bf16 v[40:43], v[194:197], v[228:231], v[40:43]
	v_mfma_f32_16x16x32_bf16 v[36:39], v[202:205], v[228:231], v[36:39]
	ds_read_b128 v[228:231], v179 offset:35840
	v_mfma_f32_16x16x32_bf16 v[32:35], v[136:139], v[236:239], v[32:35]
	v_mfma_f32_16x16x32_bf16 v[28:31], v[144:147], v[236:239], v[28:31]
	v_mfma_f32_16x16x32_bf16 v[24:27], v[194:197], v[236:239], v[24:27]
	v_mfma_f32_16x16x32_bf16 v[20:23], v[202:205], v[236:239], v[20:23]
	ds_read_b128 v[236:239], v179 offset:37888
	v_mfma_f32_16x16x32_bf16 v[16:19], v[136:139], v[244:247], v[16:19]
	v_mfma_f32_16x16x32_bf16 v[12:15], v[144:147], v[244:247], v[12:15]
	v_mfma_f32_16x16x32_bf16 v[8:11], v[194:197], v[244:247], v[8:11]
	v_mfma_f32_16x16x32_bf16 v[4:7], v[202:205], v[244:247], v[4:7]
	ds_read_b128 v[244:247], v179 offset:39936
	s_setprio 0
	s_waitcnt vmcnt(6)
	s_barrier
	s_add_i32 s25, 0, 0x18000
	s_add_i32 s70, 0, 0x1c000
	v_add_u32_e32 v144, s25, v159
	v_add_u32_e32 v158, s70, v159
	ds_read_b128 v[132:135], v144
	ds_read_b128 v[136:139], v144 offset:1024
	ds_read_b128 v[140:143], v144 offset:2048
	ds_read_b128 v[144:147], v144 offset:3072
	ds_read_b128 v[190:193], v158
	ds_read_b128 v[194:197], v158 offset:1024
	ds_read_b128 v[198:201], v158 offset:2048
	ds_read_b128 v[202:205], v158 offset:3072
	s_add_u32 s40, s52, 0x40000
	s_addc_u32 s41, s53, 0
	s_mov_b32 m0, s58
	v_lshl_add_u64 v[184:185], s[40:41], 0, v[0:1]
	global_load_lds_dwordx4 v[184:185], off
	v_lshl_add_u64 v[184:185], s[40:41], 0, v[148:149]
	s_mov_b32 m0, s59
	s_nop 0
	global_load_lds_dwordx4 v[184:185], off
	s_waitcnt vmcnt(8)
	s_waitcnt lgkmcnt(0)
	s_barrier
	s_setprio 1
	s_waitcnt lgkmcnt(0)
	v_mfma_f32_16x16x32_bf16 v[128:131], v[132:135], v[206:209], v[128:131]
	v_mfma_f32_16x16x32_bf16 v[124:127], v[140:143], v[206:209], v[124:127]
	v_mfma_f32_16x16x32_bf16 v[120:123], v[190:193], v[206:209], v[120:123]
	v_mfma_f32_16x16x32_bf16 v[116:119], v[198:201], v[206:209], v[116:119]
	ds_read_b128 v[206:209], v179 offset:49152
	v_mfma_f32_16x16x32_bf16 v[112:115], v[132:135], v[224:227], v[112:115]
	v_mfma_f32_16x16x32_bf16 v[108:111], v[140:143], v[224:227], v[108:111]
	v_mfma_f32_16x16x32_bf16 v[104:107], v[190:193], v[224:227], v[104:107]
	v_mfma_f32_16x16x32_bf16 v[100:103], v[198:201], v[224:227], v[100:103]
	ds_read_b128 v[224:227], v179 offset:51200
	v_mfma_f32_16x16x32_bf16 v[96:99], v[132:135], v[232:235], v[96:99]
	v_mfma_f32_16x16x32_bf16 v[92:95], v[140:143], v[232:235], v[92:95]
	v_mfma_f32_16x16x32_bf16 v[88:91], v[190:193], v[232:235], v[88:91]
	v_mfma_f32_16x16x32_bf16 v[84:87], v[198:201], v[232:235], v[84:87]
	ds_read_b128 v[232:235], v179 offset:53248
	v_mfma_f32_16x16x32_bf16 v[80:83], v[132:135], v[240:243], v[80:83]
	v_mfma_f32_16x16x32_bf16 v[76:79], v[140:143], v[240:243], v[76:79]
	v_mfma_f32_16x16x32_bf16 v[72:75], v[190:193], v[240:243], v[72:75]
	v_mfma_f32_16x16x32_bf16 v[68:71], v[198:201], v[240:243], v[68:71]
	ds_read_b128 v[240:243], v179 offset:55296
	v_mfma_f32_16x16x32_bf16 v[128:131], v[136:139], v[218:221], v[128:131]
	v_mfma_f32_16x16x32_bf16 v[124:127], v[144:147], v[218:221], v[124:127]
	v_mfma_f32_16x16x32_bf16 v[120:123], v[194:197], v[218:221], v[120:123]
	v_mfma_f32_16x16x32_bf16 v[116:119], v[202:205], v[218:221], v[116:119]
	ds_read_b128 v[218:221], v179 offset:50176
	v_mfma_f32_16x16x32_bf16 v[112:115], v[136:139], v[228:231], v[112:115]
	v_mfma_f32_16x16x32_bf16 v[108:111], v[144:147], v[228:231], v[108:111]
	v_mfma_f32_16x16x32_bf16 v[104:107], v[194:197], v[228:231], v[104:107]
	v_mfma_f32_16x16x32_bf16 v[100:103], v[202:205], v[228:231], v[100:103]
	ds_read_b128 v[228:231], v179 offset:52224
	v_mfma_f32_16x16x32_bf16 v[96:99], v[136:139], v[236:239], v[96:99]
	v_mfma_f32_16x16x32_bf16 v[92:95], v[144:147], v[236:239], v[92:95]
	v_mfma_f32_16x16x32_bf16 v[88:91], v[194:197], v[236:239], v[88:91]
	v_mfma_f32_16x16x32_bf16 v[84:87], v[202:205], v[236:239], v[84:87]
	ds_read_b128 v[236:239], v179 offset:54272
	v_mfma_f32_16x16x32_bf16 v[80:83], v[136:139], v[244:247], v[80:83]
	v_mfma_f32_16x16x32_bf16 v[76:79], v[144:147], v[244:247], v[76:79]
	v_mfma_f32_16x16x32_bf16 v[72:75], v[194:197], v[244:247], v[72:75]
	v_mfma_f32_16x16x32_bf16 v[68:71], v[202:205], v[244:247], v[68:71]
	ds_read_b128 v[244:247], v179 offset:56320
	s_setprio 0
	s_waitcnt vmcnt(2)
	s_barrier
	s_add_i32 s25, s25, s55
	v_lshl_add_u64 v[174:175], v[174:175], 0, s[94:95]
	s_mov_b32 m0, s25
	global_load_lds_dwordx4 v[174:175], off
	s_add_i32 m0, s25, 0x2000
	s_add_u32 s10, s10, 0x40080
	v_lshl_add_u64 v[174:175], v[210:211], 0, s[94:95]
	s_addc_u32 s11, s11, 0
	s_add_i32 s25, s70, s55
	global_load_lds_dwordx4 v[174:175], off
	v_lshl_add_u64 v[174:175], s[10:11], 0, v[180:181]
	s_mov_b32 m0, s25
	s_nop 0
	global_load_lds_dwordx4 v[174:175], off
	v_lshl_add_u64 v[174:175], s[10:11], 0, v[150:151]
	s_add_i32 m0, s25, 0x2000
	s_nop 0
	global_load_lds_dwordx4 v[174:175], off
	v_lshl_add_u64 v[174:175], v[248:249], 0, s[94:95]
	s_mov_b32 m0, s64
	s_nop 0
	global_load_lds_dwordx4 v[174:175], off
	v_lshl_add_u64 v[174:175], v[182:183], 0, s[94:95]
	s_mov_b32 m0, s65
	s_nop 0
	global_load_lds_dwordx4 v[174:175], off
	s_waitcnt vmcnt(8)
	s_waitcnt lgkmcnt(0)
	s_barrier
	s_setprio 1
	s_waitcnt lgkmcnt(0)
	v_mfma_f32_16x16x32_bf16 v[64:67], v[132:135], v[206:209], v[64:67]
	v_mfma_f32_16x16x32_bf16 v[60:63], v[140:143], v[206:209], v[60:63]
	v_mfma_f32_16x16x32_bf16 v[56:59], v[190:193], v[206:209], v[56:59]
	v_mfma_f32_16x16x32_bf16 v[52:55], v[198:201], v[206:209], v[52:55]
	ds_read_b128 v[206:209], v179
	v_mfma_f32_16x16x32_bf16 v[48:51], v[132:135], v[224:227], v[48:51]
	v_mfma_f32_16x16x32_bf16 v[44:47], v[140:143], v[224:227], v[44:47]
	v_mfma_f32_16x16x32_bf16 v[40:43], v[190:193], v[224:227], v[40:43]
	v_mfma_f32_16x16x32_bf16 v[36:39], v[198:201], v[224:227], v[36:39]
	ds_read_b128 v[224:227], v179 offset:6144
	v_mfma_f32_16x16x32_bf16 v[32:35], v[132:135], v[232:235], v[32:35]
	v_mfma_f32_16x16x32_bf16 v[28:31], v[140:143], v[232:235], v[28:31]
	v_mfma_f32_16x16x32_bf16 v[24:27], v[190:193], v[232:235], v[24:27]
	v_mfma_f32_16x16x32_bf16 v[20:23], v[198:201], v[232:235], v[20:23]
	ds_read_b128 v[232:235], v179 offset:2048
	v_mfma_f32_16x16x32_bf16 v[16:19], v[132:135], v[240:243], v[16:19]
	v_mfma_f32_16x16x32_bf16 v[12:15], v[140:143], v[240:243], v[12:15]
	v_mfma_f32_16x16x32_bf16 v[8:11], v[190:193], v[240:243], v[8:11]
	v_mfma_f32_16x16x32_bf16 v[4:7], v[198:201], v[240:243], v[4:7]
	ds_read_b128 v[240:243], v179 offset:4096
	v_mfma_f32_16x16x32_bf16 v[64:67], v[136:139], v[218:221], v[64:67]
	v_mfma_f32_16x16x32_bf16 v[60:63], v[144:147], v[218:221], v[60:63]
	v_mfma_f32_16x16x32_bf16 v[56:59], v[194:197], v[218:221], v[56:59]
	v_mfma_f32_16x16x32_bf16 v[52:55], v[202:205], v[218:221], v[52:55]
	ds_read_b128 v[218:221], v179 offset:7168
	v_mfma_f32_16x16x32_bf16 v[48:51], v[136:139], v[228:231], v[48:51]
	v_mfma_f32_16x16x32_bf16 v[44:47], v[144:147], v[228:231], v[44:47]
	v_mfma_f32_16x16x32_bf16 v[40:43], v[194:197], v[228:231], v[40:43]
	v_mfma_f32_16x16x32_bf16 v[36:39], v[202:205], v[228:231], v[36:39]
	ds_read_b128 v[228:231], v179 offset:1024
	v_mfma_f32_16x16x32_bf16 v[32:35], v[136:139], v[236:239], v[32:35]
	v_mfma_f32_16x16x32_bf16 v[28:31], v[144:147], v[236:239], v[28:31]
	v_mfma_f32_16x16x32_bf16 v[24:27], v[194:197], v[236:239], v[24:27]
	v_mfma_f32_16x16x32_bf16 v[20:23], v[202:205], v[236:239], v[20:23]
	ds_read_b128 v[236:239], v179 offset:3072
	v_mfma_f32_16x16x32_bf16 v[16:19], v[136:139], v[244:247], v[16:19]
	v_mfma_f32_16x16x32_bf16 v[12:15], v[144:147], v[244:247], v[12:15]
	v_mfma_f32_16x16x32_bf16 v[8:11], v[194:197], v[244:247], v[8:11]
	v_mfma_f32_16x16x32_bf16 v[4:7], v[202:205], v[244:247], v[4:7]
	ds_read_b128 v[244:247], v179 offset:5120
	s_setprio 0
	s_waitcnt vmcnt(6)
	s_barrier
	s_add_i32 vcc_hi, vcc_hi, 2
	s_add_u32 s8, s8, 0x100
	s_addc_u32 s9, s9, 0
	s_add_u32 s97, s97, 0x100
	s_addc_u32 vcc_lo, vcc_lo, 0
	s_cmp_gt_u32 vcc_hi, 13
	s_cbranch_scc0 .LBB0_83
	s_waitcnt lgkmcnt(0)
	s_and_b64 vcc, exec, s[16:17]
	s_cbranch_vccz .LBB0_86
	s_barrier

.LBB0_141:
	s_ashr_i32 s17, s16, 31
	s_lshl_b64 s[18:19], s[16:17], 19
	s_add_u32 s18, s42, s18
	s_addc_u32 s19, s43, s19
	s_and_b64 s[26:27], s[6:7], exec
	s_cselect_b32 s17, s19, s37
	s_cselect_b32 s64, s18, s36
	s_ashr_i32 s15, s14, 31
	s_lshl_b64 s[26:27], s[14:15], 19
	v_readlane_b32 s15, v253, 2
	s_add_u32 s26, s15, s26
	v_readlane_b32 s15, v253, 3
	s_addc_u32 s27, s15, s27
	s_and_b64 s[40:41], s[6:7], exec
	s_cselect_b32 s15, s27, s45
	s_cselect_b32 s65, s26, s44
	s_add_u32 s36, s36, 0x40080
	s_addc_u32 s37, s37, 0
	s_add_u32 s68, s44, 0x100
	v_mov_b32_e32 v4, 0
	s_addc_u32 s69, s45, 0
	s_mov_b32 s88, -2
	v_mov_b32_e32 v5, v4
	v_mov_b32_e32 v6, v4
	v_mov_b32_e32 v7, v4
	v_mov_b32_e32 v8, v4
	v_mov_b32_e32 v9, v4
	v_mov_b32_e32 v10, v4
	v_mov_b32_e32 v11, v4
	v_mov_b32_e32 v12, v4
	v_mov_b32_e32 v13, v4
	v_mov_b32_e32 v14, v4
	v_mov_b32_e32 v15, v4
	v_mov_b32_e32 v20, v4
	v_mov_b32_e32 v21, v4
	v_mov_b32_e32 v22, v4
	v_mov_b32_e32 v23, v4
	v_mov_b32_e32 v36, v4
	v_mov_b32_e32 v37, v4
	v_mov_b32_e32 v38, v4
	v_mov_b32_e32 v39, v4
	v_mov_b32_e32 v40, v4
	v_mov_b32_e32 v41, v4
	v_mov_b32_e32 v42, v4
	v_mov_b32_e32 v43, v4
	v_mov_b32_e32 v44, v4
	v_mov_b32_e32 v45, v4
	v_mov_b32_e32 v46, v4
	v_mov_b32_e32 v47, v4
	v_mov_b32_e32 v52, v4
	v_mov_b32_e32 v53, v4
	v_mov_b32_e32 v54, v4
	v_mov_b32_e32 v55, v4
	v_mov_b32_e32 v16, v4
	v_mov_b32_e32 v17, v4
	v_mov_b32_e32 v18, v4
	v_mov_b32_e32 v19, v4
	v_mov_b32_e32 v24, v4
	v_mov_b32_e32 v25, v4
	v_mov_b32_e32 v26, v4
	v_mov_b32_e32 v27, v4
	v_mov_b32_e32 v28, v4
	v_mov_b32_e32 v29, v4
	v_mov_b32_e32 v30, v4
	v_mov_b32_e32 v31, v4
	v_mov_b32_e32 v32, v4
	v_mov_b32_e32 v33, v4
	v_mov_b32_e32 v34, v4
	v_mov_b32_e32 v35, v4
	v_mov_b32_e32 v48, v4
	v_mov_b32_e32 v49, v4
	v_mov_b32_e32 v50, v4
	v_mov_b32_e32 v51, v4
	v_mov_b32_e32 v56, v4
	v_mov_b32_e32 v57, v4
	v_mov_b32_e32 v58, v4
	v_mov_b32_e32 v59, v4
	v_mov_b32_e32 v60, v4
	v_mov_b32_e32 v61, v4
	v_mov_b32_e32 v62, v4
	v_mov_b32_e32 v63, v4
	v_mov_b32_e32 v64, v4
	v_mov_b32_e32 v65, v4
	v_mov_b32_e32 v66, v4
	v_mov_b32_e32 v67, v4
	v_mov_b32_e32 v68, v4
	v_mov_b32_e32 v69, v4
	v_mov_b32_e32 v70, v4
	v_mov_b32_e32 v71, v4
	v_mov_b32_e32 v72, v4
	v_mov_b32_e32 v73, v4
	v_mov_b32_e32 v74, v4
	v_mov_b32_e32 v75, v4
	v_mov_b32_e32 v76, v4
	v_mov_b32_e32 v77, v4
	v_mov_b32_e32 v78, v4
	v_mov_b32_e32 v79, v4
	v_mov_b32_e32 v84, v4
	v_mov_b32_e32 v85, v4
	v_mov_b32_e32 v86, v4
	v_mov_b32_e32 v87, v4
	v_mov_b32_e32 v100, v4
	v_mov_b32_e32 v101, v4
	v_mov_b32_e32 v102, v4
	v_mov_b32_e32 v103, v4
	v_mov_b32_e32 v104, v4
	v_mov_b32_e32 v105, v4
	v_mov_b32_e32 v106, v4
	v_mov_b32_e32 v107, v4
	v_mov_b32_e32 v108, v4
	v_mov_b32_e32 v109, v4
	v_mov_b32_e32 v110, v4
	v_mov_b32_e32 v111, v4
	v_mov_b32_e32 v116, v4
	v_mov_b32_e32 v117, v4
	v_mov_b32_e32 v118, v4
	v_mov_b32_e32 v119, v4
	v_mov_b32_e32 v80, v4
	v_mov_b32_e32 v81, v4
	v_mov_b32_e32 v82, v4
	v_mov_b32_e32 v83, v4
	v_mov_b32_e32 v88, v4
	v_mov_b32_e32 v89, v4
	v_mov_b32_e32 v90, v4
	v_mov_b32_e32 v91, v4
	v_mov_b32_e32 v92, v4
	v_mov_b32_e32 v93, v4
	v_mov_b32_e32 v94, v4
	v_mov_b32_e32 v95, v4
	v_mov_b32_e32 v96, v4
	v_mov_b32_e32 v97, v4
	v_mov_b32_e32 v98, v4
	v_mov_b32_e32 v99, v4
	v_mov_b32_e32 v112, v4
	v_mov_b32_e32 v113, v4
	v_mov_b32_e32 v114, v4
	v_mov_b32_e32 v115, v4
	v_mov_b32_e32 v120, v4
	v_mov_b32_e32 v121, v4
	v_mov_b32_e32 v122, v4
	v_mov_b32_e32 v123, v4
	v_mov_b32_e32 v124, v4
	v_mov_b32_e32 v125, v4
	v_mov_b32_e32 v126, v4
	v_mov_b32_e32 v127, v4
	v_mov_b32_e32 v128, v4
	v_mov_b32_e32 v129, v4
	v_mov_b32_e32 v130, v4
	v_mov_b32_e32 v131, v4
	ds_read_b128 v[176:179], v143
	ds_read_b128 v[190:193], v143 offset:1024
	ds_read_b128 v[194:197], v143 offset:2048
	ds_read_b128 v[198:201], v143 offset:3072
	ds_read_b128 v[202:205], v143 offset:4096
	ds_read_b128 v[206:209], v143 offset:5120
	ds_read_b128 v[218:221], v143 offset:6144
	ds_read_b128 v[224:227], v143 offset:7168
.LBB0_142:
	s_add_u32 s25, s36, 0xfffc0080
	s_addc_u32 s40, s37, -1
	s_add_i32 s41, 0, 0x10000
	s_cmp_eq_u32 s88, 12
	s_cselect_b32 s47, s17, s40
	s_cselect_b32 s46, s64, s25
	s_cselect_b32 s45, s15, s69
	s_cselect_b32 s44, s65, s68
	s_add_i32 s25, 0, 0x14000
	v_add_u32_e32 v156, s41, v140
	v_add_u32_e32 v172, s25, v140
	ds_read_b128 v[144:147], v156
	ds_read_b128 v[148:151], v156 offset:1024
	ds_read_b128 v[152:155], v156 offset:2048
	ds_read_b128 v[156:159], v156 offset:3072
	ds_read_b128 v[160:163], v172
	ds_read_b128 v[164:167], v172 offset:1024
	ds_read_b128 v[168:171], v172 offset:2048
	ds_read_b128 v[172:175], v172 offset:3072
	v_lshl_add_u64 v[182:183], s[36:37], 0, v[136:137]
	s_add_i32 m0, s49, 0xc000
	global_load_lds_dwordx4 v[182:183], off
	v_lshl_add_u64 v[182:183], s[36:37], 0, v[138:139]
	s_add_i32 m0, s49, 0xe000
	s_nop 0
	global_load_lds_dwordx4 v[182:183], off
	s_waitcnt vmcnt(8)
	s_waitcnt lgkmcnt(0)
	s_barrier
	s_setprio 1
	s_waitcnt lgkmcnt(0)
	v_mfma_f32_16x16x32_bf16 v[128:131], v[144:147], v[176:179], v[128:131]
	v_mfma_f32_16x16x32_bf16 v[124:127], v[152:155], v[176:179], v[124:127]
	v_mfma_f32_16x16x32_bf16 v[116:119], v[160:163], v[176:179], v[116:119]
	v_mfma_f32_16x16x32_bf16 v[108:111], v[168:171], v[176:179], v[108:111]
	ds_read_b128 v[176:179], v143 offset:16384
	v_mfma_f32_16x16x32_bf16 v[120:123], v[144:147], v[194:197], v[120:123]
	v_mfma_f32_16x16x32_bf16 v[112:115], v[152:155], v[194:197], v[112:115]
	v_mfma_f32_16x16x32_bf16 v[104:107], v[160:163], v[194:197], v[104:107]
	v_mfma_f32_16x16x32_bf16 v[100:103], v[168:171], v[194:197], v[100:103]
	ds_read_b128 v[194:197], v143 offset:18432
	v_mfma_f32_16x16x32_bf16 v[96:99], v[144:147], v[202:205], v[96:99]
	v_mfma_f32_16x16x32_bf16 v[92:95], v[152:155], v[202:205], v[92:95]
	v_mfma_f32_16x16x32_bf16 v[84:87], v[160:163], v[202:205], v[84:87]
	v_mfma_f32_16x16x32_bf16 v[76:79], v[168:171], v[202:205], v[76:79]
	ds_read_b128 v[202:205], v143 offset:20480
	v_mfma_f32_16x16x32_bf16 v[88:91], v[144:147], v[218:221], v[88:91]
	v_mfma_f32_16x16x32_bf16 v[80:83], v[152:155], v[218:221], v[80:83]
	v_mfma_f32_16x16x32_bf16 v[72:75], v[160:163], v[218:221], v[72:75]
	v_mfma_f32_16x16x32_bf16 v[68:71], v[168:171], v[218:221], v[68:71]
	ds_read_b128 v[218:221], v143 offset:22528
	v_mfma_f32_16x16x32_bf16 v[128:131], v[148:151], v[190:193], v[128:131]
	v_mfma_f32_16x16x32_bf16 v[124:127], v[156:159], v[190:193], v[124:127]
	v_mfma_f32_16x16x32_bf16 v[116:119], v[164:167], v[190:193], v[116:119]
	v_mfma_f32_16x16x32_bf16 v[108:111], v[172:175], v[190:193], v[108:111]
	ds_read_b128 v[190:193], v143 offset:17408
	v_mfma_f32_16x16x32_bf16 v[120:123], v[148:151], v[198:201], v[120:123]
	v_mfma_f32_16x16x32_bf16 v[112:115], v[156:159], v[198:201], v[112:115]
	v_mfma_f32_16x16x32_bf16 v[104:107], v[164:167], v[198:201], v[104:107]
	v_mfma_f32_16x16x32_bf16 v[100:103], v[172:175], v[198:201], v[100:103]
	ds_read_b128 v[198:201], v143 offset:19456
	v_mfma_f32_16x16x32_bf16 v[96:99], v[148:151], v[206:209], v[96:99]
	v_mfma_f32_16x16x32_bf16 v[92:95], v[156:159], v[206:209], v[92:95]
	v_mfma_f32_16x16x32_bf16 v[84:87], v[164:167], v[206:209], v[84:87]
	v_mfma_f32_16x16x32_bf16 v[76:79], v[172:175], v[206:209], v[76:79]
	ds_read_b128 v[206:209], v143 offset:21504
	v_mfma_f32_16x16x32_bf16 v[88:91], v[148:151], v[224:227], v[88:91]
	v_mfma_f32_16x16x32_bf16 v[80:83], v[156:159], v[224:227], v[80:83]
	v_mfma_f32_16x16x32_bf16 v[72:75], v[164:167], v[224:227], v[72:75]
	v_mfma_f32_16x16x32_bf16 v[68:71], v[172:175], v[224:227], v[68:71]
	ds_read_b128 v[224:227], v143 offset:23552
	s_setprio 0
	s_waitcnt vmcnt(2)
	s_barrier
	s_add_i32 s40, s41, s48
	v_lshl_add_u64 v[182:183], s[44:45], 0, v[180:181]
	s_mov_b32 m0, s40
	global_load_lds_dwordx4 v[182:183], off
	s_add_i32 m0, s40, 0x2000
	s_add_u32 s40, s44, 0x40000
	v_lshl_add_u64 v[184:185], s[44:45], 0, v[134:135]
	s_addc_u32 s41, s45, 0
	s_add_i32 s25, s25, s48
	global_load_lds_dwordx4 v[184:185], off
	v_lshl_add_u64 v[210:211], s[40:41], 0, v[180:181]
	s_mov_b32 m0, s25
	v_lshl_add_u64 v[228:229], s[46:47], 0, v[132:133]
	global_load_lds_dwordx4 v[210:211], off
	v_lshl_add_u64 v[210:211], s[40:41], 0, v[134:135]
	s_add_i32 m0, s25, 0x2000
	s_nop 0
	global_load_lds_dwordx4 v[210:211], off
	v_lshl_add_u64 v[210:211], s[46:47], 0, v[0:1]
	s_mov_b32 m0, s49
	s_nop 0
	global_load_lds_dwordx4 v[210:211], off
	s_mov_b32 m0, s50
	s_nop 0
	global_load_lds_dwordx4 v[228:229], off
	s_waitcnt vmcnt(8)
	s_waitcnt lgkmcnt(0)
	s_barrier
	s_setprio 1
	s_waitcnt lgkmcnt(0)
	v_mfma_f32_16x16x32_bf16 v[64:67], v[144:147], v[176:179], v[64:67]
	v_mfma_f32_16x16x32_bf16 v[60:63], v[152:155], v[176:179], v[60:63]
	v_mfma_f32_16x16x32_bf16 v[52:55], v[160:163], v[176:179], v[52:55]
	v_mfma_f32_16x16x32_bf16 v[44:47], v[168:171], v[176:179], v[44:47]
	ds_read_b128 v[176:179], v143 offset:32768
	v_mfma_f32_16x16x32_bf16 v[56:59], v[144:147], v[194:197], v[56:59]
	v_mfma_f32_16x16x32_bf16 v[48:51], v[152:155], v[194:197], v[48:51]
	v_mfma_f32_16x16x32_bf16 v[40:43], v[160:163], v[194:197], v[40:43]
	v_mfma_f32_16x16x32_bf16 v[36:39], v[168:171], v[194:197], v[36:39]
	ds_read_b128 v[194:197], v143 offset:34816
	v_mfma_f32_16x16x32_bf16 v[32:35], v[144:147], v[202:205], v[32:35]
	v_mfma_f32_16x16x32_bf16 v[28:31], v[152:155], v[202:205], v[28:31]
	v_mfma_f32_16x16x32_bf16 v[20:23], v[160:163], v[202:205], v[20:23]
	v_mfma_f32_16x16x32_bf16 v[12:15], v[168:171], v[202:205], v[12:15]
	ds_read_b128 v[202:205], v143 offset:36864
	v_mfma_f32_16x16x32_bf16 v[24:27], v[144:147], v[218:221], v[24:27]
	v_mfma_f32_16x16x32_bf16 v[16:19], v[152:155], v[218:221], v[16:19]
	v_mfma_f32_16x16x32_bf16 v[8:11], v[160:163], v[218:221], v[8:11]
	v_mfma_f32_16x16x32_bf16 v[4:7], v[168:171], v[218:221], v[4:7]
	ds_read_b128 v[218:221], v143 offset:38912
	v_mfma_f32_16x16x32_bf16 v[64:67], v[148:151], v[190:193], v[64:67]
	v_mfma_f32_16x16x32_bf16 v[60:63], v[156:159], v[190:193], v[60:63]
	v_mfma_f32_16x16x32_bf16 v[52:55], v[164:167], v[190:193], v[52:55]
	v_mfma_f32_16x16x32_bf16 v[44:47], v[172:175], v[190:193], v[44:47]
	ds_read_b128 v[190:193], v143 offset:33792
	v_mfma_f32_16x16x32_bf16 v[56:59], v[148:151], v[198:201], v[56:59]
	v_mfma_f32_16x16x32_bf16 v[48:51], v[156:159], v[198:201], v[48:51]
	v_mfma_f32_16x16x32_bf16 v[40:43], v[164:167], v[198:201], v[40:43]
	v_mfma_f32_16x16x32_bf16 v[36:39], v[172:175], v[198:201], v[36:39]
	ds_read_b128 v[198:201], v143 offset:35840
	v_mfma_f32_16x16x32_bf16 v[32:35], v[148:151], v[206:209], v[32:35]
	v_mfma_f32_16x16x32_bf16 v[28:31], v[156:159], v[206:209], v[28:31]
	v_mfma_f32_16x16x32_bf16 v[20:23], v[164:167], v[206:209], v[20:23]
	v_mfma_f32_16x16x32_bf16 v[12:15], v[172:175], v[206:209], v[12:15]
	ds_read_b128 v[206:209], v143 offset:37888
	v_mfma_f32_16x16x32_bf16 v[24:27], v[148:151], v[224:227], v[24:27]
	v_mfma_f32_16x16x32_bf16 v[16:19], v[156:159], v[224:227], v[16:19]
	v_mfma_f32_16x16x32_bf16 v[8:11], v[164:167], v[224:227], v[8:11]
	v_mfma_f32_16x16x32_bf16 v[4:7], v[172:175], v[224:227], v[4:7]
	ds_read_b128 v[224:227], v143 offset:39936
	s_setprio 0
	s_waitcnt vmcnt(6)
	s_barrier
	s_add_i32 s25, 0, 0x18000
	s_add_i32 s70, 0, 0x1c000
	v_add_u32_e32 v156, s25, v140
	v_add_u32_e32 v172, s70, v140
	ds_read_b128 v[144:147], v156
	ds_read_b128 v[148:151], v156 offset:1024
	ds_read_b128 v[152:155], v156 offset:2048
	ds_read_b128 v[156:159], v156 offset:3072
	ds_read_b128 v[160:163], v172
	ds_read_b128 v[164:167], v172 offset:1024
	ds_read_b128 v[168:171], v172 offset:2048
	ds_read_b128 v[172:175], v172 offset:3072
	s_add_u32 s40, s46, 0x40000
	s_addc_u32 s41, s47, 0
	s_mov_b32 m0, s51
	v_lshl_add_u64 v[230:231], s[40:41], 0, v[0:1]
	global_load_lds_dwordx4 v[230:231], off
	v_lshl_add_u64 v[230:231], s[40:41], 0, v[132:133]
	s_mov_b32 m0, s52
	s_nop 0
	global_load_lds_dwordx4 v[230:231], off
	s_waitcnt vmcnt(8)
	s_waitcnt lgkmcnt(0)
	s_barrier
	s_setprio 1
	s_waitcnt lgkmcnt(0)
	v_mfma_f32_16x16x32_bf16 v[128:131], v[144:147], v[176:179], v[128:131]
	v_mfma_f32_16x16x32_bf16 v[124:127], v[152:155], v[176:179], v[124:127]
	v_mfma_f32_16x16x32_bf16 v[116:119], v[160:163], v[176:179], v[116:119]
	v_mfma_f32_16x16x32_bf16 v[108:111], v[168:171], v[176:179], v[108:111]
	ds_read_b128 v[176:179], v143 offset:49152
	v_mfma_f32_16x16x32_bf16 v[120:123], v[144:147], v[194:197], v[120:123]
	v_mfma_f32_16x16x32_bf16 v[112:115], v[152:155], v[194:197], v[112:115]
	v_mfma_f32_16x16x32_bf16 v[104:107], v[160:163], v[194:197], v[104:107]
	v_mfma_f32_16x16x32_bf16 v[100:103], v[168:171], v[194:197], v[100:103]
	ds_read_b128 v[194:197], v143 offset:51200
	v_mfma_f32_16x16x32_bf16 v[96:99], v[144:147], v[202:205], v[96:99]
	v_mfma_f32_16x16x32_bf16 v[92:95], v[152:155], v[202:205], v[92:95]
	v_mfma_f32_16x16x32_bf16 v[84:87], v[160:163], v[202:205], v[84:87]
	v_mfma_f32_16x16x32_bf16 v[76:79], v[168:171], v[202:205], v[76:79]
	ds_read_b128 v[202:205], v143 offset:53248
	v_mfma_f32_16x16x32_bf16 v[88:91], v[144:147], v[218:221], v[88:91]
	v_mfma_f32_16x16x32_bf16 v[80:83], v[152:155], v[218:221], v[80:83]
	v_mfma_f32_16x16x32_bf16 v[72:75], v[160:163], v[218:221], v[72:75]
	v_mfma_f32_16x16x32_bf16 v[68:71], v[168:171], v[218:221], v[68:71]
	ds_read_b128 v[218:221], v143 offset:55296
	v_mfma_f32_16x16x32_bf16 v[128:131], v[148:151], v[190:193], v[128:131]
	v_mfma_f32_16x16x32_bf16 v[124:127], v[156:159], v[190:193], v[124:127]
	v_mfma_f32_16x16x32_bf16 v[116:119], v[164:167], v[190:193], v[116:119]
	v_mfma_f32_16x16x32_bf16 v[108:111], v[172:175], v[190:193], v[108:111]
	ds_read_b128 v[190:193], v143 offset:50176
	v_mfma_f32_16x16x32_bf16 v[120:123], v[148:151], v[198:201], v[120:123]
	v_mfma_f32_16x16x32_bf16 v[112:115], v[156:159], v[198:201], v[112:115]
	v_mfma_f32_16x16x32_bf16 v[104:107], v[164:167], v[198:201], v[104:107]
	v_mfma_f32_16x16x32_bf16 v[100:103], v[172:175], v[198:201], v[100:103]
	ds_read_b128 v[198:201], v143 offset:52224
	v_mfma_f32_16x16x32_bf16 v[96:99], v[148:151], v[206:209], v[96:99]
	v_mfma_f32_16x16x32_bf16 v[92:95], v[156:159], v[206:209], v[92:95]
	v_mfma_f32_16x16x32_bf16 v[84:87], v[164:167], v[206:209], v[84:87]
	v_mfma_f32_16x16x32_bf16 v[76:79], v[172:175], v[206:209], v[76:79]
	ds_read_b128 v[206:209], v143 offset:54272
	v_mfma_f32_16x16x32_bf16 v[88:91], v[148:151], v[224:227], v[88:91]
	v_mfma_f32_16x16x32_bf16 v[80:83], v[156:159], v[224:227], v[80:83]
	v_mfma_f32_16x16x32_bf16 v[72:75], v[164:167], v[224:227], v[72:75]
	v_mfma_f32_16x16x32_bf16 v[68:71], v[172:175], v[224:227], v[68:71]
	ds_read_b128 v[224:227], v143 offset:56320
	s_setprio 0
	s_waitcnt vmcnt(2)
	s_barrier
	s_add_i32 s25, s25, s48
	v_lshl_add_u64 v[182:183], v[182:183], 0, s[94:95]
	s_mov_b32 m0, s25
	global_load_lds_dwordx4 v[182:183], off
	s_add_i32 m0, s25, 0x2000
	s_add_u32 s40, s44, 0x40080
	v_lshl_add_u64 v[182:183], v[184:185], 0, s[94:95]
	s_addc_u32 s41, s45, 0
	s_add_i32 s25, s70, s48
	global_load_lds_dwordx4 v[182:183], off
	v_lshl_add_u64 v[182:183], s[40:41], 0, v[180:181]
	s_mov_b32 m0, s25
	s_nop 0
	global_load_lds_dwordx4 v[182:183], off
	v_lshl_add_u64 v[182:183], s[40:41], 0, v[134:135]
	s_add_i32 m0, s25, 0x2000
	s_nop 0
	global_load_lds_dwordx4 v[182:183], off
	v_lshl_add_u64 v[182:183], v[210:211], 0, s[94:95]
	s_mov_b32 m0, s53
	s_nop 0
	global_load_lds_dwordx4 v[182:183], off
	v_lshl_add_u64 v[182:183], v[228:229], 0, s[94:95]
	s_mov_b32 m0, s54
	s_nop 0
	global_load_lds_dwordx4 v[182:183], off
	s_waitcnt vmcnt(8)
	s_waitcnt lgkmcnt(0)
	s_barrier
	s_setprio 1
	s_waitcnt lgkmcnt(0)
	v_mfma_f32_16x16x32_bf16 v[64:67], v[144:147], v[176:179], v[64:67]
	v_mfma_f32_16x16x32_bf16 v[60:63], v[152:155], v[176:179], v[60:63]
	v_mfma_f32_16x16x32_bf16 v[52:55], v[160:163], v[176:179], v[52:55]
	v_mfma_f32_16x16x32_bf16 v[44:47], v[168:171], v[176:179], v[44:47]
	ds_read_b128 v[176:179], v143
	v_mfma_f32_16x16x32_bf16 v[56:59], v[144:147], v[194:197], v[56:59]
	v_mfma_f32_16x16x32_bf16 v[48:51], v[152:155], v[194:197], v[48:51]
	v_mfma_f32_16x16x32_bf16 v[40:43], v[160:163], v[194:197], v[40:43]
	v_mfma_f32_16x16x32_bf16 v[36:39], v[168:171], v[194:197], v[36:39]
	ds_read_b128 v[194:197], v143 offset:2048
	v_mfma_f32_16x16x32_bf16 v[32:35], v[144:147], v[202:205], v[32:35]
	v_mfma_f32_16x16x32_bf16 v[28:31], v[152:155], v[202:205], v[28:31]
	v_mfma_f32_16x16x32_bf16 v[20:23], v[160:163], v[202:205], v[20:23]
	v_mfma_f32_16x16x32_bf16 v[12:15], v[168:171], v[202:205], v[12:15]
	ds_read_b128 v[202:205], v143 offset:4096
	v_mfma_f32_16x16x32_bf16 v[24:27], v[144:147], v[218:221], v[24:27]
	v_mfma_f32_16x16x32_bf16 v[16:19], v[152:155], v[218:221], v[16:19]
	v_mfma_f32_16x16x32_bf16 v[8:11], v[160:163], v[218:221], v[8:11]
	v_mfma_f32_16x16x32_bf16 v[4:7], v[168:171], v[218:221], v[4:7]
	ds_read_b128 v[218:221], v143 offset:6144
	v_mfma_f32_16x16x32_bf16 v[64:67], v[148:151], v[190:193], v[64:67]
	v_mfma_f32_16x16x32_bf16 v[60:63], v[156:159], v[190:193], v[60:63]
	v_mfma_f32_16x16x32_bf16 v[52:55], v[164:167], v[190:193], v[52:55]
	v_mfma_f32_16x16x32_bf16 v[44:47], v[172:175], v[190:193], v[44:47]
	ds_read_b128 v[190:193], v143 offset:1024
	v_mfma_f32_16x16x32_bf16 v[56:59], v[148:151], v[198:201], v[56:59]
	v_mfma_f32_16x16x32_bf16 v[48:51], v[156:159], v[198:201], v[48:51]
	v_mfma_f32_16x16x32_bf16 v[40:43], v[164:167], v[198:201], v[40:43]
	v_mfma_f32_16x16x32_bf16 v[36:39], v[172:175], v[198:201], v[36:39]
	ds_read_b128 v[198:201], v143 offset:3072
	v_mfma_f32_16x16x32_bf16 v[32:35], v[148:151], v[206:209], v[32:35]
	v_mfma_f32_16x16x32_bf16 v[28:31], v[156:159], v[206:209], v[28:31]
	v_mfma_f32_16x16x32_bf16 v[20:23], v[164:167], v[206:209], v[20:23]
	v_mfma_f32_16x16x32_bf16 v[12:15], v[172:175], v[206:209], v[12:15]
	ds_read_b128 v[206:209], v143 offset:5120
	v_mfma_f32_16x16x32_bf16 v[24:27], v[148:151], v[224:227], v[24:27]
	v_mfma_f32_16x16x32_bf16 v[16:19], v[156:159], v[224:227], v[16:19]
	v_mfma_f32_16x16x32_bf16 v[8:11], v[164:167], v[224:227], v[8:11]
	v_mfma_f32_16x16x32_bf16 v[4:7], v[172:175], v[224:227], v[4:7]
	ds_read_b128 v[224:227], v143 offset:7168
	s_setprio 0
	s_waitcnt vmcnt(6)
	s_barrier
	s_add_i32 s88, s88, 2
	s_add_u32 s36, s36, 0x100
	s_addc_u32 s37, s37, 0
	s_add_u32 s68, s68, 0x100
	s_addc_u32 s69, s69, 0
	s_cmp_gt_u32 s88, 13
	s_cbranch_scc0 .LBB0_142
	s_waitcnt lgkmcnt(0)
	s_and_b64 vcc, exec, s[12:13]
	s_cbranch_vccz .LBB0_145
	s_barrier

.LBB0_180:
	s_ashr_i32 s19, s18, 31
	s_lshl_b64 s[40:41], s[18:19], 19
	v_readlane_b32 s19, v253, 33
	s_add_u32 s44, s19, s40
	v_readlane_b32 s19, v253, 34
	s_addc_u32 s45, s19, s41
	s_and_b64 s[10:11], s[10:11], exec
	s_cselect_b32 s19, s45, s47
	s_cselect_b32 s27, s44, s46
	s_add_u32 s10, s48, 0x40080
	s_addc_u32 s11, s49, 0
	s_add_u32 s64, s46, 0x100
	v_mov_b32_e32 v4, 0
	s_addc_u32 s65, s47, 0
	s_mov_b32 s68, -2
	s_waitcnt lgkmcnt(0)
	v_mov_b32_e32 v5, v4
	v_mov_b32_e32 v6, v4
	v_mov_b32_e32 v7, v4
	v_mov_b32_e32 v8, v4
	v_mov_b32_e32 v9, v4
	v_mov_b32_e32 v10, v4
	v_mov_b32_e32 v11, v4
	v_mov_b32_e32 v20, v4
	v_mov_b32_e32 v21, v4
	v_mov_b32_e32 v22, v4
	v_mov_b32_e32 v23, v4
	v_mov_b32_e32 v24, v4
	v_mov_b32_e32 v25, v4
	v_mov_b32_e32 v26, v4
	v_mov_b32_e32 v27, v4
	v_mov_b32_e32 v36, v4
	v_mov_b32_e32 v37, v4
	v_mov_b32_e32 v38, v4
	v_mov_b32_e32 v39, v4
	v_mov_b32_e32 v40, v4
	v_mov_b32_e32 v41, v4
	v_mov_b32_e32 v42, v4
	v_mov_b32_e32 v43, v4
	v_mov_b32_e32 v52, v4
	v_mov_b32_e32 v53, v4
	v_mov_b32_e32 v54, v4
	v_mov_b32_e32 v55, v4
	v_mov_b32_e32 v56, v4
	v_mov_b32_e32 v57, v4
	v_mov_b32_e32 v58, v4
	v_mov_b32_e32 v59, v4
	v_mov_b32_e32 v12, v4
	v_mov_b32_e32 v13, v4
	v_mov_b32_e32 v14, v4
	v_mov_b32_e32 v15, v4
	v_mov_b32_e32 v16, v4
	v_mov_b32_e32 v17, v4
	v_mov_b32_e32 v18, v4
	v_mov_b32_e32 v19, v4
	v_mov_b32_e32 v28, v4
	v_mov_b32_e32 v29, v4
	v_mov_b32_e32 v30, v4
	v_mov_b32_e32 v31, v4
	v_mov_b32_e32 v32, v4
	v_mov_b32_e32 v33, v4
	v_mov_b32_e32 v34, v4
	v_mov_b32_e32 v35, v4
	v_mov_b32_e32 v44, v4
	v_mov_b32_e32 v45, v4
	v_mov_b32_e32 v46, v4
	v_mov_b32_e32 v47, v4
	v_mov_b32_e32 v48, v4
	v_mov_b32_e32 v49, v4
	v_mov_b32_e32 v50, v4
	v_mov_b32_e32 v51, v4
	v_mov_b32_e32 v60, v4
	v_mov_b32_e32 v61, v4
	v_mov_b32_e32 v62, v4
	v_mov_b32_e32 v63, v4
	v_mov_b32_e32 v64, v4
	v_mov_b32_e32 v65, v4
	v_mov_b32_e32 v66, v4
	v_mov_b32_e32 v67, v4
	v_mov_b32_e32 v68, v4
	v_mov_b32_e32 v69, v4
	v_mov_b32_e32 v70, v4
	v_mov_b32_e32 v71, v4
	v_mov_b32_e32 v72, v4
	v_mov_b32_e32 v73, v4
	v_mov_b32_e32 v74, v4
	v_mov_b32_e32 v75, v4
	v_mov_b32_e32 v84, v4
	v_mov_b32_e32 v85, v4
	v_mov_b32_e32 v86, v4
	v_mov_b32_e32 v87, v4
	v_mov_b32_e32 v88, v4
	v_mov_b32_e32 v89, v4
	v_mov_b32_e32 v90, v4
	v_mov_b32_e32 v91, v4
	v_mov_b32_e32 v100, v4
	v_mov_b32_e32 v101, v4
	v_mov_b32_e32 v102, v4
	v_mov_b32_e32 v103, v4
	v_mov_b32_e32 v104, v4
	v_mov_b32_e32 v105, v4
	v_mov_b32_e32 v106, v4
	v_mov_b32_e32 v107, v4
	v_mov_b32_e32 v116, v4
	v_mov_b32_e32 v117, v4
	v_mov_b32_e32 v118, v4
	v_mov_b32_e32 v119, v4
	v_mov_b32_e32 v120, v4
	v_mov_b32_e32 v121, v4
	v_mov_b32_e32 v122, v4
	v_mov_b32_e32 v123, v4
	v_mov_b32_e32 v76, v4
	v_mov_b32_e32 v77, v4
	v_mov_b32_e32 v78, v4
	v_mov_b32_e32 v79, v4
	v_mov_b32_e32 v80, v4
	v_mov_b32_e32 v81, v4
	v_mov_b32_e32 v82, v4
	v_mov_b32_e32 v83, v4
	v_mov_b32_e32 v92, v4
	v_mov_b32_e32 v93, v4
	v_mov_b32_e32 v94, v4
	v_mov_b32_e32 v95, v4
	v_mov_b32_e32 v96, v4
	v_mov_b32_e32 v97, v4
	v_mov_b32_e32 v98, v4
	v_mov_b32_e32 v99, v4
	v_mov_b32_e32 v108, v4
	v_mov_b32_e32 v109, v4
	v_mov_b32_e32 v110, v4
	v_mov_b32_e32 v111, v4
	v_mov_b32_e32 v112, v4
	v_mov_b32_e32 v113, v4
	v_mov_b32_e32 v114, v4
	v_mov_b32_e32 v115, v4
	v_mov_b32_e32 v124, v4
	v_mov_b32_e32 v125, v4
	v_mov_b32_e32 v126, v4
	v_mov_b32_e32 v127, v4
	v_mov_b32_e32 v128, v4
	v_mov_b32_e32 v129, v4
	v_mov_b32_e32 v130, v4
	v_mov_b32_e32 v131, v4
	ds_read_b128 v[174:177], v194
	ds_read_b128 v[196:199], v194 offset:1024
	ds_read_b128 v[200:203], v194 offset:2048
	ds_read_b128 v[204:207], v194 offset:3072
	ds_read_b128 v[208:211], v194 offset:4096
	ds_read_b128 v[218:221], v194 offset:5120
	ds_read_b128 v[224:227], v194 offset:6144
	ds_read_b128 v[228:231], v194 offset:7168
.LBB0_181:
	s_add_u32 s25, s10, 0xfffc0080
	s_addc_u32 s40, s11, -1
	s_add_i32 s41, 0, 0x10000
	s_cmp_eq_u32 s68, 12
	s_cselect_b32 s49, s37, s40
	s_cselect_b32 s48, s36, s25
	s_cselect_b32 s47, s19, s65
	s_cselect_b32 s46, s27, s64
	s_add_i32 s25, 0, 0x14000
	v_add_u32_e32 v144, s41, v187
	v_add_u32_e32 v170, s25, v187
	ds_read_b128 v[132:135], v144
	ds_read_b128 v[136:139], v144 offset:1024
	ds_read_b128 v[140:143], v144 offset:2048
	ds_read_b128 v[144:147], v144 offset:3072
	ds_read_b128 v[148:151], v170
	ds_read_b128 v[152:155], v170 offset:1024
	ds_read_b128 v[156:159], v170 offset:2048
	ds_read_b128 v[170:173], v170 offset:3072
	v_lshl_add_u64 v[178:179], s[10:11], 0, v[166:167]
	s_add_i32 m0, s51, 0xc000
	global_load_lds_dwordx4 v[178:179], off
	v_lshl_add_u64 v[178:179], s[10:11], 0, v[168:169]
	s_add_i32 m0, s51, 0xe000
	s_nop 0
	global_load_lds_dwordx4 v[178:179], off
	s_waitcnt vmcnt(8)
	s_waitcnt lgkmcnt(0)
	s_barrier
	s_setprio 1
	s_waitcnt lgkmcnt(0)
	v_mfma_f32_16x16x32_bf16 v[128:131], v[132:135], v[174:177], v[128:131]
	v_mfma_f32_16x16x32_bf16 v[124:127], v[140:143], v[174:177], v[124:127]
	v_mfma_f32_16x16x32_bf16 v[120:123], v[148:151], v[174:177], v[120:123]
	v_mfma_f32_16x16x32_bf16 v[116:119], v[156:159], v[174:177], v[116:119]
	ds_read_b128 v[174:177], v194 offset:16384
	v_mfma_f32_16x16x32_bf16 v[112:115], v[132:135], v[200:203], v[112:115]
	v_mfma_f32_16x16x32_bf16 v[108:111], v[140:143], v[200:203], v[108:111]
	v_mfma_f32_16x16x32_bf16 v[104:107], v[148:151], v[200:203], v[104:107]
	v_mfma_f32_16x16x32_bf16 v[100:103], v[156:159], v[200:203], v[100:103]
	ds_read_b128 v[200:203], v194 offset:18432
	v_mfma_f32_16x16x32_bf16 v[96:99], v[132:135], v[208:211], v[96:99]
	v_mfma_f32_16x16x32_bf16 v[92:95], v[140:143], v[208:211], v[92:95]
	v_mfma_f32_16x16x32_bf16 v[88:91], v[148:151], v[208:211], v[88:91]
	v_mfma_f32_16x16x32_bf16 v[84:87], v[156:159], v[208:211], v[84:87]
	ds_read_b128 v[208:211], v194 offset:20480
	v_mfma_f32_16x16x32_bf16 v[80:83], v[132:135], v[224:227], v[80:83]
	v_mfma_f32_16x16x32_bf16 v[76:79], v[140:143], v[224:227], v[76:79]
	v_mfma_f32_16x16x32_bf16 v[72:75], v[148:151], v[224:227], v[72:75]
	v_mfma_f32_16x16x32_bf16 v[68:71], v[156:159], v[224:227], v[68:71]
	ds_read_b128 v[224:227], v194 offset:22528
	v_mfma_f32_16x16x32_bf16 v[128:131], v[136:139], v[196:199], v[128:131]
	v_mfma_f32_16x16x32_bf16 v[124:127], v[144:147], v[196:199], v[124:127]
	v_mfma_f32_16x16x32_bf16 v[120:123], v[152:155], v[196:199], v[120:123]
	v_mfma_f32_16x16x32_bf16 v[116:119], v[170:173], v[196:199], v[116:119]
	ds_read_b128 v[196:199], v194 offset:17408
	v_mfma_f32_16x16x32_bf16 v[112:115], v[136:139], v[204:207], v[112:115]
	v_mfma_f32_16x16x32_bf16 v[108:111], v[144:147], v[204:207], v[108:111]
	v_mfma_f32_16x16x32_bf16 v[104:107], v[152:155], v[204:207], v[104:107]
	v_mfma_f32_16x16x32_bf16 v[100:103], v[170:173], v[204:207], v[100:103]
	ds_read_b128 v[204:207], v194 offset:19456
	v_mfma_f32_16x16x32_bf16 v[96:99], v[136:139], v[218:221], v[96:99]
	v_mfma_f32_16x16x32_bf16 v[92:95], v[144:147], v[218:221], v[92:95]
	v_mfma_f32_16x16x32_bf16 v[88:91], v[152:155], v[218:221], v[88:91]
	v_mfma_f32_16x16x32_bf16 v[84:87], v[170:173], v[218:221], v[84:87]
	ds_read_b128 v[218:221], v194 offset:21504
	v_mfma_f32_16x16x32_bf16 v[80:83], v[136:139], v[228:231], v[80:83]
	v_mfma_f32_16x16x32_bf16 v[76:79], v[144:147], v[228:231], v[76:79]
	v_mfma_f32_16x16x32_bf16 v[72:75], v[152:155], v[228:231], v[72:75]
	v_mfma_f32_16x16x32_bf16 v[68:71], v[170:173], v[228:231], v[68:71]
	ds_read_b128 v[228:231], v194 offset:23552
	s_setprio 0
	s_waitcnt vmcnt(2)
	s_barrier
	s_add_i32 s40, s41, s50
	v_lshl_add_u64 v[178:179], s[46:47], 0, v[162:163]
	s_mov_b32 m0, s40
	global_load_lds_dwordx4 v[178:179], off
	s_add_i32 m0, s40, 0x2000
	s_add_u32 s40, s46, 0x40000
	v_lshl_add_u64 v[182:183], s[46:47], 0, v[0:1]
	s_addc_u32 s41, s47, 0
	s_add_i32 s25, s25, s50
	global_load_lds_dwordx4 v[182:183], off
	v_lshl_add_u64 v[184:185], s[40:41], 0, v[162:163]
	s_mov_b32 m0, s25
	v_lshl_add_u64 v[190:191], s[48:49], 0, v[160:161]
	global_load_lds_dwordx4 v[184:185], off
	v_lshl_add_u64 v[184:185], s[40:41], 0, v[0:1]
	s_add_i32 m0, s25, 0x2000
	s_nop 0
	global_load_lds_dwordx4 v[184:185], off
	v_lshl_add_u64 v[184:185], s[48:49], 0, v[164:165]
	s_mov_b32 m0, s51
	s_nop 0
	global_load_lds_dwordx4 v[184:185], off
	s_mov_b32 m0, s52
	s_nop 0
	global_load_lds_dwordx4 v[190:191], off
	s_waitcnt vmcnt(8)
	s_waitcnt lgkmcnt(0)
	s_barrier
	s_setprio 1
	s_waitcnt lgkmcnt(0)
	v_mfma_f32_16x16x32_bf16 v[64:67], v[132:135], v[174:177], v[64:67]
	v_mfma_f32_16x16x32_bf16 v[60:63], v[140:143], v[174:177], v[60:63]
	v_mfma_f32_16x16x32_bf16 v[56:59], v[148:151], v[174:177], v[56:59]
	v_mfma_f32_16x16x32_bf16 v[52:55], v[156:159], v[174:177], v[52:55]
	ds_read_b128 v[174:177], v194 offset:32768
	v_mfma_f32_16x16x32_bf16 v[48:51], v[132:135], v[200:203], v[48:51]
	v_mfma_f32_16x16x32_bf16 v[44:47], v[140:143], v[200:203], v[44:47]
	v_mfma_f32_16x16x32_bf16 v[40:43], v[148:151], v[200:203], v[40:43]
	v_mfma_f32_16x16x32_bf16 v[36:39], v[156:159], v[200:203], v[36:39]
	ds_read_b128 v[200:203], v194 offset:34816
	v_mfma_f32_16x16x32_bf16 v[32:35], v[132:135], v[208:211], v[32:35]
	v_mfma_f32_16x16x32_bf16 v[28:31], v[140:143], v[208:211], v[28:31]
	v_mfma_f32_16x16x32_bf16 v[24:27], v[148:151], v[208:211], v[24:27]
	v_mfma_f32_16x16x32_bf16 v[20:23], v[156:159], v[208:211], v[20:23]
	ds_read_b128 v[208:211], v194 offset:36864
	v_mfma_f32_16x16x32_bf16 v[16:19], v[132:135], v[224:227], v[16:19]
	v_mfma_f32_16x16x32_bf16 v[12:15], v[140:143], v[224:227], v[12:15]
	v_mfma_f32_16x16x32_bf16 v[8:11], v[148:151], v[224:227], v[8:11]
	v_mfma_f32_16x16x32_bf16 v[4:7], v[156:159], v[224:227], v[4:7]
	ds_read_b128 v[224:227], v194 offset:38912
	v_mfma_f32_16x16x32_bf16 v[64:67], v[136:139], v[196:199], v[64:67]
	v_mfma_f32_16x16x32_bf16 v[60:63], v[144:147], v[196:199], v[60:63]
	v_mfma_f32_16x16x32_bf16 v[56:59], v[152:155], v[196:199], v[56:59]
	v_mfma_f32_16x16x32_bf16 v[52:55], v[170:173], v[196:199], v[52:55]
	ds_read_b128 v[196:199], v194 offset:33792
	v_mfma_f32_16x16x32_bf16 v[48:51], v[136:139], v[204:207], v[48:51]
	v_mfma_f32_16x16x32_bf16 v[44:47], v[144:147], v[204:207], v[44:47]
	v_mfma_f32_16x16x32_bf16 v[40:43], v[152:155], v[204:207], v[40:43]
	v_mfma_f32_16x16x32_bf16 v[36:39], v[170:173], v[204:207], v[36:39]
	ds_read_b128 v[204:207], v194 offset:35840
	v_mfma_f32_16x16x32_bf16 v[32:35], v[136:139], v[218:221], v[32:35]
	v_mfma_f32_16x16x32_bf16 v[28:31], v[144:147], v[218:221], v[28:31]
	v_mfma_f32_16x16x32_bf16 v[24:27], v[152:155], v[218:221], v[24:27]
	v_mfma_f32_16x16x32_bf16 v[20:23], v[170:173], v[218:221], v[20:23]
	ds_read_b128 v[218:221], v194 offset:37888
	v_mfma_f32_16x16x32_bf16 v[16:19], v[136:139], v[228:231], v[16:19]
	v_mfma_f32_16x16x32_bf16 v[12:15], v[144:147], v[228:231], v[12:15]
	v_mfma_f32_16x16x32_bf16 v[8:11], v[152:155], v[228:231], v[8:11]
	v_mfma_f32_16x16x32_bf16 v[4:7], v[170:173], v[228:231], v[4:7]
	ds_read_b128 v[228:231], v194 offset:39936
	s_setprio 0
	s_waitcnt vmcnt(6)
	s_barrier
	s_add_i32 s25, 0, 0x18000
	s_add_i32 s69, 0, 0x1c000
	v_add_u32_e32 v144, s25, v187
	v_add_u32_e32 v170, s69, v187
	ds_read_b128 v[132:135], v144
	ds_read_b128 v[136:139], v144 offset:1024
	ds_read_b128 v[140:143], v144 offset:2048
	ds_read_b128 v[144:147], v144 offset:3072
	ds_read_b128 v[148:151], v170
	ds_read_b128 v[152:155], v170 offset:1024
	ds_read_b128 v[156:159], v170 offset:2048
	ds_read_b128 v[170:173], v170 offset:3072
	s_add_u32 s40, s48, 0x40000
	s_addc_u32 s41, s49, 0
	s_mov_b32 m0, s53
	v_lshl_add_u64 v[232:233], s[40:41], 0, v[164:165]
	global_load_lds_dwordx4 v[232:233], off
	v_lshl_add_u64 v[232:233], s[40:41], 0, v[160:161]
	s_mov_b32 m0, s54
	s_nop 0
	global_load_lds_dwordx4 v[232:233], off
	s_waitcnt vmcnt(8)
	s_waitcnt lgkmcnt(0)
	s_barrier
	s_setprio 1
	s_waitcnt lgkmcnt(0)
	v_mfma_f32_16x16x32_bf16 v[128:131], v[132:135], v[174:177], v[128:131]
	v_mfma_f32_16x16x32_bf16 v[124:127], v[140:143], v[174:177], v[124:127]
	v_mfma_f32_16x16x32_bf16 v[120:123], v[148:151], v[174:177], v[120:123]
	v_mfma_f32_16x16x32_bf16 v[116:119], v[156:159], v[174:177], v[116:119]
	ds_read_b128 v[174:177], v194 offset:49152
	v_mfma_f32_16x16x32_bf16 v[112:115], v[132:135], v[200:203], v[112:115]
	v_mfma_f32_16x16x32_bf16 v[108:111], v[140:143], v[200:203], v[108:111]
	v_mfma_f32_16x16x32_bf16 v[104:107], v[148:151], v[200:203], v[104:107]
	v_mfma_f32_16x16x32_bf16 v[100:103], v[156:159], v[200:203], v[100:103]
	ds_read_b128 v[200:203], v194 offset:51200
	v_mfma_f32_16x16x32_bf16 v[96:99], v[132:135], v[208:211], v[96:99]
	v_mfma_f32_16x16x32_bf16 v[92:95], v[140:143], v[208:211], v[92:95]
	v_mfma_f32_16x16x32_bf16 v[88:91], v[148:151], v[208:211], v[88:91]
	v_mfma_f32_16x16x32_bf16 v[84:87], v[156:159], v[208:211], v[84:87]
	ds_read_b128 v[208:211], v194 offset:53248
	v_mfma_f32_16x16x32_bf16 v[80:83], v[132:135], v[224:227], v[80:83]
	v_mfma_f32_16x16x32_bf16 v[76:79], v[140:143], v[224:227], v[76:79]
	v_mfma_f32_16x16x32_bf16 v[72:75], v[148:151], v[224:227], v[72:75]
	v_mfma_f32_16x16x32_bf16 v[68:71], v[156:159], v[224:227], v[68:71]
	ds_read_b128 v[224:227], v194 offset:55296
	v_mfma_f32_16x16x32_bf16 v[128:131], v[136:139], v[196:199], v[128:131]
	v_mfma_f32_16x16x32_bf16 v[124:127], v[144:147], v[196:199], v[124:127]
	v_mfma_f32_16x16x32_bf16 v[120:123], v[152:155], v[196:199], v[120:123]
	v_mfma_f32_16x16x32_bf16 v[116:119], v[170:173], v[196:199], v[116:119]
	ds_read_b128 v[196:199], v194 offset:50176
	v_mfma_f32_16x16x32_bf16 v[112:115], v[136:139], v[204:207], v[112:115]
	v_mfma_f32_16x16x32_bf16 v[108:111], v[144:147], v[204:207], v[108:111]
	v_mfma_f32_16x16x32_bf16 v[104:107], v[152:155], v[204:207], v[104:107]
	v_mfma_f32_16x16x32_bf16 v[100:103], v[170:173], v[204:207], v[100:103]
	ds_read_b128 v[204:207], v194 offset:52224
	v_mfma_f32_16x16x32_bf16 v[96:99], v[136:139], v[218:221], v[96:99]
	v_mfma_f32_16x16x32_bf16 v[92:95], v[144:147], v[218:221], v[92:95]
	v_mfma_f32_16x16x32_bf16 v[88:91], v[152:155], v[218:221], v[88:91]
	v_mfma_f32_16x16x32_bf16 v[84:87], v[170:173], v[218:221], v[84:87]
	ds_read_b128 v[218:221], v194 offset:54272
	v_mfma_f32_16x16x32_bf16 v[80:83], v[136:139], v[228:231], v[80:83]
	v_mfma_f32_16x16x32_bf16 v[76:79], v[144:147], v[228:231], v[76:79]
	v_mfma_f32_16x16x32_bf16 v[72:75], v[152:155], v[228:231], v[72:75]
	v_mfma_f32_16x16x32_bf16 v[68:71], v[170:173], v[228:231], v[68:71]
	ds_read_b128 v[228:231], v194 offset:56320
	s_setprio 0
	s_waitcnt vmcnt(2)
	s_barrier
	s_add_i32 s25, s25, s50
	v_lshl_add_u64 v[178:179], v[178:179], 0, s[94:95]
	s_mov_b32 m0, s25
	global_load_lds_dwordx4 v[178:179], off
	s_add_i32 m0, s25, 0x2000
	s_add_u32 s40, s46, 0x40080
	v_lshl_add_u64 v[178:179], v[182:183], 0, s[94:95]
	s_addc_u32 s41, s47, 0
	s_add_i32 s25, s69, s50
	global_load_lds_dwordx4 v[178:179], off
	v_lshl_add_u64 v[178:179], s[40:41], 0, v[162:163]
	s_mov_b32 m0, s25
	s_nop 0
	global_load_lds_dwordx4 v[178:179], off
	v_lshl_add_u64 v[178:179], s[40:41], 0, v[0:1]
	s_add_i32 m0, s25, 0x2000
	s_nop 0
	global_load_lds_dwordx4 v[178:179], off
	v_lshl_add_u64 v[178:179], v[184:185], 0, s[94:95]
	s_mov_b32 m0, s55
	s_nop 0
	global_load_lds_dwordx4 v[178:179], off
	v_lshl_add_u64 v[178:179], v[190:191], 0, s[94:95]
	s_mov_b32 m0, s58
	s_nop 0
	global_load_lds_dwordx4 v[178:179], off
	s_waitcnt vmcnt(8)
	s_waitcnt lgkmcnt(0)
	s_barrier
	s_setprio 1
	s_waitcnt lgkmcnt(0)
	v_mfma_f32_16x16x32_bf16 v[64:67], v[132:135], v[174:177], v[64:67]
	v_mfma_f32_16x16x32_bf16 v[60:63], v[140:143], v[174:177], v[60:63]
	v_mfma_f32_16x16x32_bf16 v[56:59], v[148:151], v[174:177], v[56:59]
	v_mfma_f32_16x16x32_bf16 v[52:55], v[156:159], v[174:177], v[52:55]
	ds_read_b128 v[174:177], v194
	v_mfma_f32_16x16x32_bf16 v[48:51], v[132:135], v[200:203], v[48:51]
	v_mfma_f32_16x16x32_bf16 v[44:47], v[140:143], v[200:203], v[44:47]
	v_mfma_f32_16x16x32_bf16 v[40:43], v[148:151], v[200:203], v[40:43]
	v_mfma_f32_16x16x32_bf16 v[36:39], v[156:159], v[200:203], v[36:39]
	ds_read_b128 v[200:203], v194 offset:2048
	v_mfma_f32_16x16x32_bf16 v[32:35], v[132:135], v[208:211], v[32:35]
	v_mfma_f32_16x16x32_bf16 v[28:31], v[140:143], v[208:211], v[28:31]
	v_mfma_f32_16x16x32_bf16 v[24:27], v[148:151], v[208:211], v[24:27]
	v_mfma_f32_16x16x32_bf16 v[20:23], v[156:159], v[208:211], v[20:23]
	ds_read_b128 v[208:211], v194 offset:4096
	v_mfma_f32_16x16x32_bf16 v[16:19], v[132:135], v[224:227], v[16:19]
	v_mfma_f32_16x16x32_bf16 v[12:15], v[140:143], v[224:227], v[12:15]
	v_mfma_f32_16x16x32_bf16 v[8:11], v[148:151], v[224:227], v[8:11]
	v_mfma_f32_16x16x32_bf16 v[4:7], v[156:159], v[224:227], v[4:7]
	ds_read_b128 v[224:227], v194 offset:6144
	v_mfma_f32_16x16x32_bf16 v[64:67], v[136:139], v[196:199], v[64:67]
	v_mfma_f32_16x16x32_bf16 v[60:63], v[144:147], v[196:199], v[60:63]
	v_mfma_f32_16x16x32_bf16 v[56:59], v[152:155], v[196:199], v[56:59]
	v_mfma_f32_16x16x32_bf16 v[52:55], v[170:173], v[196:199], v[52:55]
	ds_read_b128 v[196:199], v194 offset:1024
	v_mfma_f32_16x16x32_bf16 v[48:51], v[136:139], v[204:207], v[48:51]
	v_mfma_f32_16x16x32_bf16 v[44:47], v[144:147], v[204:207], v[44:47]
	v_mfma_f32_16x16x32_bf16 v[40:43], v[152:155], v[204:207], v[40:43]
	v_mfma_f32_16x16x32_bf16 v[36:39], v[170:173], v[204:207], v[36:39]
	ds_read_b128 v[204:207], v194 offset:3072
	v_mfma_f32_16x16x32_bf16 v[32:35], v[136:139], v[218:221], v[32:35]
	v_mfma_f32_16x16x32_bf16 v[28:31], v[144:147], v[218:221], v[28:31]
	v_mfma_f32_16x16x32_bf16 v[24:27], v[152:155], v[218:221], v[24:27]
	v_mfma_f32_16x16x32_bf16 v[20:23], v[170:173], v[218:221], v[20:23]
	ds_read_b128 v[218:221], v194 offset:5120
	v_mfma_f32_16x16x32_bf16 v[16:19], v[136:139], v[228:231], v[16:19]
	v_mfma_f32_16x16x32_bf16 v[12:15], v[144:147], v[228:231], v[12:15]
	v_mfma_f32_16x16x32_bf16 v[8:11], v[152:155], v[228:231], v[8:11]
	v_mfma_f32_16x16x32_bf16 v[4:7], v[170:173], v[228:231], v[4:7]
	ds_read_b128 v[228:231], v194 offset:7168
	s_setprio 0
	s_waitcnt vmcnt(6)
	s_barrier
	s_add_i32 s68, s68, 2
	s_add_u32 s10, s10, 0x100
	s_addc_u32 s11, s11, 0
	s_add_u32 s64, s64, 0x100
	s_addc_u32 s65, s65, 0
	s_cmp_gt_u32 s68, 13
	s_cbranch_scc0 .LBB0_181
	s_waitcnt lgkmcnt(0)
	s_and_b64 vcc, exec, s[14:15]
	s_cbranch_vccz .LBB0_184
	s_barrier

.LBB0_230:
	s_ashr_i32 s27, s26, 31
	s_lshl_b64 s[36:37], s[26:27], 19
	s_add_u32 s36, s42, s36
	s_addc_u32 s37, s43, s37
	s_and_b64 s[40:41], s[8:9], exec
	s_cselect_b32 s27, s37, s11
	s_cselect_b32 s69, s36, s10
	s_ashr_i32 s19, s18, 31
	s_lshl_b64 s[40:41], s[18:19], 19
	v_readlane_b32 s19, v253, 21
	s_add_u32 s44, s19, s40
	v_readlane_b32 s19, v253, 22
	s_addc_u32 s45, s19, s41
	s_and_b64 s[40:41], s[8:9], exec
	s_cselect_b32 s19, s45, s13
	s_cselect_b32 s88, s44, s12
	s_add_u32 s10, s10, 0x40080
	s_addc_u32 s11, s11, 0
	s_add_u32 s89, s12, 0x100
	v_mov_b32_e32 v4, 0
	v_mov_b64_e32 v[186:187], 0xff
	v_mov_b64_e32 v[162:163], 0x100
	s_addc_u32 s90, s13, 0
	s_mov_b32 s97, -2
	v_mov_b32_e32 v5, v4
	v_mov_b32_e32 v6, v4
	v_mov_b32_e32 v7, v4
	v_mov_b32_e32 v8, v4
	v_mov_b32_e32 v9, v4
	v_mov_b32_e32 v10, v4
	v_mov_b32_e32 v11, v4
	v_mov_b32_e32 v20, v4
	v_mov_b32_e32 v21, v4
	v_mov_b32_e32 v22, v4
	v_mov_b32_e32 v23, v4
	v_mov_b32_e32 v24, v4
	v_mov_b32_e32 v25, v4
	v_mov_b32_e32 v26, v4
	v_mov_b32_e32 v27, v4
	v_mov_b32_e32 v36, v4
	v_mov_b32_e32 v37, v4
	v_mov_b32_e32 v38, v4
	v_mov_b32_e32 v39, v4
	v_mov_b32_e32 v40, v4
	v_mov_b32_e32 v41, v4
	v_mov_b32_e32 v42, v4
	v_mov_b32_e32 v43, v4
	v_mov_b32_e32 v52, v4
	v_mov_b32_e32 v53, v4
	v_mov_b32_e32 v54, v4
	v_mov_b32_e32 v55, v4
	v_mov_b32_e32 v56, v4
	v_mov_b32_e32 v57, v4
	v_mov_b32_e32 v58, v4
	v_mov_b32_e32 v59, v4
	v_mov_b32_e32 v12, v4
	v_mov_b32_e32 v13, v4
	v_mov_b32_e32 v14, v4
	v_mov_b32_e32 v15, v4
	v_mov_b32_e32 v16, v4
	v_mov_b32_e32 v17, v4
	v_mov_b32_e32 v18, v4
	v_mov_b32_e32 v19, v4
	v_mov_b32_e32 v28, v4
	v_mov_b32_e32 v29, v4
	v_mov_b32_e32 v30, v4
	v_mov_b32_e32 v31, v4
	v_mov_b32_e32 v32, v4
	v_mov_b32_e32 v33, v4
	v_mov_b32_e32 v34, v4
	v_mov_b32_e32 v35, v4
	v_mov_b32_e32 v44, v4
	v_mov_b32_e32 v45, v4
	v_mov_b32_e32 v46, v4
	v_mov_b32_e32 v47, v4
	v_mov_b32_e32 v48, v4
	v_mov_b32_e32 v49, v4
	v_mov_b32_e32 v50, v4
	v_mov_b32_e32 v51, v4
	v_mov_b32_e32 v60, v4
	v_mov_b32_e32 v61, v4
	v_mov_b32_e32 v62, v4
	v_mov_b32_e32 v63, v4
	v_mov_b32_e32 v64, v4
	v_mov_b32_e32 v65, v4
	v_mov_b32_e32 v66, v4
	v_mov_b32_e32 v67, v4
	v_mov_b32_e32 v68, v4
	v_mov_b32_e32 v69, v4
	v_mov_b32_e32 v70, v4
	v_mov_b32_e32 v71, v4
	v_mov_b32_e32 v72, v4
	v_mov_b32_e32 v73, v4
	v_mov_b32_e32 v74, v4
	v_mov_b32_e32 v75, v4
	v_mov_b32_e32 v84, v4
	v_mov_b32_e32 v85, v4
	v_mov_b32_e32 v86, v4
	v_mov_b32_e32 v87, v4
	v_mov_b32_e32 v88, v4
	v_mov_b32_e32 v89, v4
	v_mov_b32_e32 v90, v4
	v_mov_b32_e32 v91, v4
	v_mov_b32_e32 v100, v4
	v_mov_b32_e32 v101, v4
	v_mov_b32_e32 v102, v4
	v_mov_b32_e32 v103, v4
	v_mov_b32_e32 v104, v4
	v_mov_b32_e32 v105, v4
	v_mov_b32_e32 v106, v4
	v_mov_b32_e32 v107, v4
	v_mov_b32_e32 v116, v4
	v_mov_b32_e32 v117, v4
	v_mov_b32_e32 v118, v4
	v_mov_b32_e32 v119, v4
	v_mov_b32_e32 v120, v4
	v_mov_b32_e32 v121, v4
	v_mov_b32_e32 v122, v4
	v_mov_b32_e32 v123, v4
	v_mov_b32_e32 v76, v4
	v_mov_b32_e32 v77, v4
	v_mov_b32_e32 v78, v4
	v_mov_b32_e32 v79, v4
	v_mov_b32_e32 v80, v4
	v_mov_b32_e32 v81, v4
	v_mov_b32_e32 v82, v4
	v_mov_b32_e32 v83, v4
	v_mov_b32_e32 v92, v4
	v_mov_b32_e32 v93, v4
	v_mov_b32_e32 v94, v4
	v_mov_b32_e32 v95, v4
	v_mov_b32_e32 v96, v4
	v_mov_b32_e32 v97, v4
	v_mov_b32_e32 v98, v4
	v_mov_b32_e32 v99, v4
	v_mov_b32_e32 v108, v4
	v_mov_b32_e32 v109, v4
	v_mov_b32_e32 v110, v4
	v_mov_b32_e32 v111, v4
	v_mov_b32_e32 v112, v4
	v_mov_b32_e32 v113, v4
	v_mov_b32_e32 v114, v4
	v_mov_b32_e32 v115, v4
	v_mov_b32_e32 v124, v4
	v_mov_b32_e32 v125, v4
	v_mov_b32_e32 v126, v4
	v_mov_b32_e32 v127, v4
	v_mov_b32_e32 v128, v4
	v_mov_b32_e32 v129, v4
	v_mov_b32_e32 v130, v4
	v_mov_b32_e32 v131, v4
	ds_read_b128 v[206:209], v179
	ds_read_b128 v[218:221], v179 offset:1024
	ds_read_b128 v[224:227], v179 offset:2048
	ds_read_b128 v[228:231], v179 offset:3072
	ds_read_b128 v[232:235], v179 offset:4096
	ds_read_b128 v[236:239], v179 offset:5120
	ds_read_b128 v[240:243], v179 offset:6144
	ds_read_b128 v[244:247], v179 offset:7168
.LBB0_231:
	s_add_u32 s12, s10, 0xfffc0080
	s_addc_u32 s13, s11, -1
	s_add_i32 s25, 0, 0x10000
	s_cmp_eq_u32 s97, 12
	s_cselect_b32 s47, s27, s13
	s_cselect_b32 s46, s69, s12
	s_cselect_b32 s13, s19, s90
	s_cselect_b32 s12, s88, s89
	s_add_i32 s50, 0, 0x14000
	v_add_u32_e32 v144, s25, v159
	v_add_u32_e32 v158, s50, v159
	ds_read_b128 v[132:135], v144
	ds_read_b128 v[136:139], v144 offset:1024
	ds_read_b128 v[140:143], v144 offset:2048
	ds_read_b128 v[144:147], v144 offset:3072
	ds_read_b128 v[190:193], v158
	ds_read_b128 v[194:197], v158 offset:1024
	ds_read_b128 v[198:201], v158 offset:2048
	ds_read_b128 v[202:205], v158 offset:3072
	v_lshl_add_u64 v[174:175], s[10:11], 0, v[154:155]
	s_add_i32 m0, s49, 0xc000
	global_load_lds_dwordx4 v[174:175], off
	v_lshl_add_u64 v[174:175], s[10:11], 0, v[156:157]
	s_add_i32 m0, s49, 0xe000
	s_nop 0
	global_load_lds_dwordx4 v[174:175], off
	s_waitcnt vmcnt(8)
	s_waitcnt lgkmcnt(0)
	s_barrier
	s_setprio 1
	s_waitcnt lgkmcnt(0)
	v_mfma_f32_16x16x32_bf16 v[128:131], v[132:135], v[206:209], v[128:131]
	v_mfma_f32_16x16x32_bf16 v[124:127], v[140:143], v[206:209], v[124:127]
	v_mfma_f32_16x16x32_bf16 v[120:123], v[190:193], v[206:209], v[120:123]
	v_mfma_f32_16x16x32_bf16 v[116:119], v[198:201], v[206:209], v[116:119]
	ds_read_b128 v[206:209], v179 offset:16384
	v_mfma_f32_16x16x32_bf16 v[112:115], v[132:135], v[224:227], v[112:115]
	v_mfma_f32_16x16x32_bf16 v[108:111], v[140:143], v[224:227], v[108:111]
	v_mfma_f32_16x16x32_bf16 v[104:107], v[190:193], v[224:227], v[104:107]
	v_mfma_f32_16x16x32_bf16 v[100:103], v[198:201], v[224:227], v[100:103]
	ds_read_b128 v[224:227], v179 offset:18432
	v_mfma_f32_16x16x32_bf16 v[96:99], v[132:135], v[232:235], v[96:99]
	v_mfma_f32_16x16x32_bf16 v[92:95], v[140:143], v[232:235], v[92:95]
	v_mfma_f32_16x16x32_bf16 v[88:91], v[190:193], v[232:235], v[88:91]
	v_mfma_f32_16x16x32_bf16 v[84:87], v[198:201], v[232:235], v[84:87]
	ds_read_b128 v[232:235], v179 offset:20480
	v_mfma_f32_16x16x32_bf16 v[80:83], v[132:135], v[240:243], v[80:83]
	v_mfma_f32_16x16x32_bf16 v[76:79], v[140:143], v[240:243], v[76:79]
	v_mfma_f32_16x16x32_bf16 v[72:75], v[190:193], v[240:243], v[72:75]
	v_mfma_f32_16x16x32_bf16 v[68:71], v[198:201], v[240:243], v[68:71]
	ds_read_b128 v[240:243], v179 offset:22528
	v_mfma_f32_16x16x32_bf16 v[128:131], v[136:139], v[218:221], v[128:131]
	v_mfma_f32_16x16x32_bf16 v[124:127], v[144:147], v[218:221], v[124:127]
	v_mfma_f32_16x16x32_bf16 v[120:123], v[194:197], v[218:221], v[120:123]
	v_mfma_f32_16x16x32_bf16 v[116:119], v[202:205], v[218:221], v[116:119]
	ds_read_b128 v[218:221], v179 offset:17408
	v_mfma_f32_16x16x32_bf16 v[112:115], v[136:139], v[228:231], v[112:115]
	v_mfma_f32_16x16x32_bf16 v[108:111], v[144:147], v[228:231], v[108:111]
	v_mfma_f32_16x16x32_bf16 v[104:107], v[194:197], v[228:231], v[104:107]
	v_mfma_f32_16x16x32_bf16 v[100:103], v[202:205], v[228:231], v[100:103]
	ds_read_b128 v[228:231], v179 offset:19456
	v_mfma_f32_16x16x32_bf16 v[96:99], v[136:139], v[236:239], v[96:99]
	v_mfma_f32_16x16x32_bf16 v[92:95], v[144:147], v[236:239], v[92:95]
	v_mfma_f32_16x16x32_bf16 v[88:91], v[194:197], v[236:239], v[88:91]
	v_mfma_f32_16x16x32_bf16 v[84:87], v[202:205], v[236:239], v[84:87]
	ds_read_b128 v[236:239], v179 offset:21504
	v_mfma_f32_16x16x32_bf16 v[80:83], v[136:139], v[244:247], v[80:83]
	v_mfma_f32_16x16x32_bf16 v[76:79], v[144:147], v[244:247], v[76:79]
	v_mfma_f32_16x16x32_bf16 v[72:75], v[194:197], v[244:247], v[72:75]
	v_mfma_f32_16x16x32_bf16 v[68:71], v[202:205], v[244:247], v[68:71]
	ds_read_b128 v[244:247], v179 offset:23552
	s_setprio 0
	s_waitcnt vmcnt(2)
	s_barrier
	s_add_i32 s25, s25, s48
	v_lshl_add_u64 v[174:175], s[12:13], 0, v[180:181]
	s_mov_b32 m0, s25
	global_load_lds_dwordx4 v[174:175], off
	s_add_i32 m0, s25, 0x2000
	s_add_u32 s40, s12, 0x40000
	v_lshl_add_u64 v[182:183], s[12:13], 0, v[150:151]
	s_addc_u32 s41, s13, 0
	s_add_i32 s25, s50, s48
	global_load_lds_dwordx4 v[182:183], off
	v_lshl_add_u64 v[184:185], s[40:41], 0, v[180:181]
	s_mov_b32 m0, s25
	v_lshl_add_u64 v[210:211], s[46:47], 0, v[148:149]
	global_load_lds_dwordx4 v[184:185], off
	v_lshl_add_u64 v[184:185], s[40:41], 0, v[150:151]
	s_add_i32 m0, s25, 0x2000
	s_nop 0
	global_load_lds_dwordx4 v[184:185], off
	v_lshl_add_u64 v[184:185], s[46:47], 0, v[0:1]
	s_mov_b32 m0, s49
	s_nop 0
	global_load_lds_dwordx4 v[184:185], off
	s_mov_b32 m0, s52
	s_nop 0
	global_load_lds_dwordx4 v[210:211], off
	s_waitcnt vmcnt(8)
	s_waitcnt lgkmcnt(0)
	s_barrier
	s_setprio 1
	s_waitcnt lgkmcnt(0)
	v_mfma_f32_16x16x32_bf16 v[64:67], v[132:135], v[206:209], v[64:67]
	v_mfma_f32_16x16x32_bf16 v[60:63], v[140:143], v[206:209], v[60:63]
	v_mfma_f32_16x16x32_bf16 v[56:59], v[190:193], v[206:209], v[56:59]
	v_mfma_f32_16x16x32_bf16 v[52:55], v[198:201], v[206:209], v[52:55]
	ds_read_b128 v[206:209], v179 offset:32768
	v_mfma_f32_16x16x32_bf16 v[48:51], v[132:135], v[224:227], v[48:51]
	v_mfma_f32_16x16x32_bf16 v[44:47], v[140:143], v[224:227], v[44:47]
	v_mfma_f32_16x16x32_bf16 v[40:43], v[190:193], v[224:227], v[40:43]
	v_mfma_f32_16x16x32_bf16 v[36:39], v[198:201], v[224:227], v[36:39]
	ds_read_b128 v[224:227], v179 offset:34816
	v_mfma_f32_16x16x32_bf16 v[32:35], v[132:135], v[232:235], v[32:35]
	v_mfma_f32_16x16x32_bf16 v[28:31], v[140:143], v[232:235], v[28:31]
	v_mfma_f32_16x16x32_bf16 v[24:27], v[190:193], v[232:235], v[24:27]
	v_mfma_f32_16x16x32_bf16 v[20:23], v[198:201], v[232:235], v[20:23]
	ds_read_b128 v[232:235], v179 offset:36864
	v_mfma_f32_16x16x32_bf16 v[16:19], v[132:135], v[240:243], v[16:19]
	v_mfma_f32_16x16x32_bf16 v[12:15], v[140:143], v[240:243], v[12:15]
	v_mfma_f32_16x16x32_bf16 v[8:11], v[190:193], v[240:243], v[8:11]
	v_mfma_f32_16x16x32_bf16 v[4:7], v[198:201], v[240:243], v[4:7]
	ds_read_b128 v[240:243], v179 offset:38912
	v_mfma_f32_16x16x32_bf16 v[64:67], v[136:139], v[218:221], v[64:67]
	v_mfma_f32_16x16x32_bf16 v[60:63], v[144:147], v[218:221], v[60:63]
	v_mfma_f32_16x16x32_bf16 v[56:59], v[194:197], v[218:221], v[56:59]
	v_mfma_f32_16x16x32_bf16 v[52:55], v[202:205], v[218:221], v[52:55]
	ds_read_b128 v[218:221], v179 offset:33792
	v_mfma_f32_16x16x32_bf16 v[48:51], v[136:139], v[228:231], v[48:51]
	v_mfma_f32_16x16x32_bf16 v[44:47], v[144:147], v[228:231], v[44:47]
	v_mfma_f32_16x16x32_bf16 v[40:43], v[194:197], v[228:231], v[40:43]
	v_mfma_f32_16x16x32_bf16 v[36:39], v[202:205], v[228:231], v[36:39]
	ds_read_b128 v[228:231], v179 offset:35840
	v_mfma_f32_16x16x32_bf16 v[32:35], v[136:139], v[236:239], v[32:35]
	v_mfma_f32_16x16x32_bf16 v[28:31], v[144:147], v[236:239], v[28:31]
	v_mfma_f32_16x16x32_bf16 v[24:27], v[194:197], v[236:239], v[24:27]
	v_mfma_f32_16x16x32_bf16 v[20:23], v[202:205], v[236:239], v[20:23]
	ds_read_b128 v[236:239], v179 offset:37888
	v_mfma_f32_16x16x32_bf16 v[16:19], v[136:139], v[244:247], v[16:19]
	v_mfma_f32_16x16x32_bf16 v[12:15], v[144:147], v[244:247], v[12:15]
	v_mfma_f32_16x16x32_bf16 v[8:11], v[194:197], v[244:247], v[8:11]
	v_mfma_f32_16x16x32_bf16 v[4:7], v[202:205], v[244:247], v[4:7]
	ds_read_b128 v[244:247], v179 offset:39936
	s_setprio 0
	s_waitcnt vmcnt(6)
	s_barrier
	s_add_i32 s25, 0, 0x18000
	s_add_i32 s50, 0, 0x1c000
	v_add_u32_e32 v144, s25, v159
	v_add_u32_e32 v158, s50, v159
	ds_read_b128 v[132:135], v144
	ds_read_b128 v[136:139], v144 offset:1024
	ds_read_b128 v[140:143], v144 offset:2048
	ds_read_b128 v[144:147], v144 offset:3072
	ds_read_b128 v[190:193], v158
	ds_read_b128 v[194:197], v158 offset:1024
	ds_read_b128 v[198:201], v158 offset:2048
	ds_read_b128 v[202:205], v158 offset:3072
	s_add_u32 s40, s46, 0x40000
	s_addc_u32 s41, s47, 0
	s_mov_b32 m0, s53
	v_lshl_add_u64 v[248:249], s[40:41], 0, v[0:1]
	global_load_lds_dwordx4 v[248:249], off
	v_lshl_add_u64 v[248:249], s[40:41], 0, v[148:149]
	s_mov_b32 m0, s54
	s_nop 0
	global_load_lds_dwordx4 v[248:249], off
	s_waitcnt vmcnt(8)
	s_waitcnt lgkmcnt(0)
	s_barrier
	s_setprio 1
	s_waitcnt lgkmcnt(0)
	v_mfma_f32_16x16x32_bf16 v[128:131], v[132:135], v[206:209], v[128:131]
	v_mfma_f32_16x16x32_bf16 v[124:127], v[140:143], v[206:209], v[124:127]
	v_mfma_f32_16x16x32_bf16 v[120:123], v[190:193], v[206:209], v[120:123]
	v_mfma_f32_16x16x32_bf16 v[116:119], v[198:201], v[206:209], v[116:119]
	ds_read_b128 v[206:209], v179 offset:49152
	v_mfma_f32_16x16x32_bf16 v[112:115], v[132:135], v[224:227], v[112:115]
	v_mfma_f32_16x16x32_bf16 v[108:111], v[140:143], v[224:227], v[108:111]
	v_mfma_f32_16x16x32_bf16 v[104:107], v[190:193], v[224:227], v[104:107]
	v_mfma_f32_16x16x32_bf16 v[100:103], v[198:201], v[224:227], v[100:103]
	ds_read_b128 v[224:227], v179 offset:51200
	v_mfma_f32_16x16x32_bf16 v[96:99], v[132:135], v[232:235], v[96:99]
	v_mfma_f32_16x16x32_bf16 v[92:95], v[140:143], v[232:235], v[92:95]
	v_mfma_f32_16x16x32_bf16 v[88:91], v[190:193], v[232:235], v[88:91]
	v_mfma_f32_16x16x32_bf16 v[84:87], v[198:201], v[232:235], v[84:87]
	ds_read_b128 v[232:235], v179 offset:53248
	v_mfma_f32_16x16x32_bf16 v[80:83], v[132:135], v[240:243], v[80:83]
	v_mfma_f32_16x16x32_bf16 v[76:79], v[140:143], v[240:243], v[76:79]
	v_mfma_f32_16x16x32_bf16 v[72:75], v[190:193], v[240:243], v[72:75]
	v_mfma_f32_16x16x32_bf16 v[68:71], v[198:201], v[240:243], v[68:71]
	ds_read_b128 v[240:243], v179 offset:55296
	v_mfma_f32_16x16x32_bf16 v[128:131], v[136:139], v[218:221], v[128:131]
	v_mfma_f32_16x16x32_bf16 v[124:127], v[144:147], v[218:221], v[124:127]
	v_mfma_f32_16x16x32_bf16 v[120:123], v[194:197], v[218:221], v[120:123]
	v_mfma_f32_16x16x32_bf16 v[116:119], v[202:205], v[218:221], v[116:119]
	ds_read_b128 v[218:221], v179 offset:50176
	v_mfma_f32_16x16x32_bf16 v[112:115], v[136:139], v[228:231], v[112:115]
	v_mfma_f32_16x16x32_bf16 v[108:111], v[144:147], v[228:231], v[108:111]
	v_mfma_f32_16x16x32_bf16 v[104:107], v[194:197], v[228:231], v[104:107]
	v_mfma_f32_16x16x32_bf16 v[100:103], v[202:205], v[228:231], v[100:103]
	ds_read_b128 v[228:231], v179 offset:52224
	v_mfma_f32_16x16x32_bf16 v[96:99], v[136:139], v[236:239], v[96:99]
	v_mfma_f32_16x16x32_bf16 v[92:95], v[144:147], v[236:239], v[92:95]
	v_mfma_f32_16x16x32_bf16 v[88:91], v[194:197], v[236:239], v[88:91]
	v_mfma_f32_16x16x32_bf16 v[84:87], v[202:205], v[236:239], v[84:87]
	ds_read_b128 v[236:239], v179 offset:54272
	v_mfma_f32_16x16x32_bf16 v[80:83], v[136:139], v[244:247], v[80:83]
	v_mfma_f32_16x16x32_bf16 v[76:79], v[144:147], v[244:247], v[76:79]
	v_mfma_f32_16x16x32_bf16 v[72:75], v[194:197], v[244:247], v[72:75]
	v_mfma_f32_16x16x32_bf16 v[68:71], v[202:205], v[244:247], v[68:71]
	ds_read_b128 v[244:247], v179 offset:56320
	s_setprio 0
	s_waitcnt vmcnt(2)
	s_barrier
	s_add_i32 s25, s25, s48
	v_lshl_add_u64 v[174:175], v[174:175], 0, s[94:95]
	s_mov_b32 m0, s25
	global_load_lds_dwordx4 v[174:175], off
	s_add_i32 m0, s25, 0x2000
	s_add_u32 s12, s12, 0x40080
	v_lshl_add_u64 v[174:175], v[182:183], 0, s[94:95]
	s_addc_u32 s13, s13, 0
	s_add_i32 s25, s50, s48
	global_load_lds_dwordx4 v[174:175], off
	v_lshl_add_u64 v[174:175], s[12:13], 0, v[180:181]
	s_mov_b32 m0, s25
	s_nop 0
	global_load_lds_dwordx4 v[174:175], off
	v_lshl_add_u64 v[174:175], s[12:13], 0, v[150:151]
	s_add_i32 m0, s25, 0x2000
	s_nop 0
	global_load_lds_dwordx4 v[174:175], off
	v_lshl_add_u64 v[174:175], v[184:185], 0, s[94:95]
	s_mov_b32 m0, s55
	s_nop 0
	global_load_lds_dwordx4 v[174:175], off
	v_lshl_add_u64 v[174:175], v[210:211], 0, s[94:95]
	s_mov_b32 m0, s58
	s_nop 0
	global_load_lds_dwordx4 v[174:175], off
	s_waitcnt vmcnt(8)
	s_waitcnt lgkmcnt(0)
	s_barrier
	s_setprio 1
	s_waitcnt lgkmcnt(0)
	v_mfma_f32_16x16x32_bf16 v[64:67], v[132:135], v[206:209], v[64:67]
	v_mfma_f32_16x16x32_bf16 v[60:63], v[140:143], v[206:209], v[60:63]
	v_mfma_f32_16x16x32_bf16 v[56:59], v[190:193], v[206:209], v[56:59]
	v_mfma_f32_16x16x32_bf16 v[52:55], v[198:201], v[206:209], v[52:55]
	ds_read_b128 v[206:209], v179
	v_mfma_f32_16x16x32_bf16 v[48:51], v[132:135], v[224:227], v[48:51]
	v_mfma_f32_16x16x32_bf16 v[44:47], v[140:143], v[224:227], v[44:47]
	v_mfma_f32_16x16x32_bf16 v[40:43], v[190:193], v[224:227], v[40:43]
	v_mfma_f32_16x16x32_bf16 v[36:39], v[198:201], v[224:227], v[36:39]
	ds_read_b128 v[224:227], v179 offset:2048
	v_mfma_f32_16x16x32_bf16 v[32:35], v[132:135], v[232:235], v[32:35]
	v_mfma_f32_16x16x32_bf16 v[28:31], v[140:143], v[232:235], v[28:31]
	v_mfma_f32_16x16x32_bf16 v[24:27], v[190:193], v[232:235], v[24:27]
	v_mfma_f32_16x16x32_bf16 v[20:23], v[198:201], v[232:235], v[20:23]
	ds_read_b128 v[232:235], v179 offset:4096
	v_mfma_f32_16x16x32_bf16 v[16:19], v[132:135], v[240:243], v[16:19]
	v_mfma_f32_16x16x32_bf16 v[12:15], v[140:143], v[240:243], v[12:15]
	v_mfma_f32_16x16x32_bf16 v[8:11], v[190:193], v[240:243], v[8:11]
	v_mfma_f32_16x16x32_bf16 v[4:7], v[198:201], v[240:243], v[4:7]
	ds_read_b128 v[240:243], v179 offset:6144
	v_mfma_f32_16x16x32_bf16 v[64:67], v[136:139], v[218:221], v[64:67]
	v_mfma_f32_16x16x32_bf16 v[60:63], v[144:147], v[218:221], v[60:63]
	v_mfma_f32_16x16x32_bf16 v[56:59], v[194:197], v[218:221], v[56:59]
	v_mfma_f32_16x16x32_bf16 v[52:55], v[202:205], v[218:221], v[52:55]
	ds_read_b128 v[218:221], v179 offset:1024
	v_mfma_f32_16x16x32_bf16 v[48:51], v[136:139], v[228:231], v[48:51]
	v_mfma_f32_16x16x32_bf16 v[44:47], v[144:147], v[228:231], v[44:47]
	v_mfma_f32_16x16x32_bf16 v[40:43], v[194:197], v[228:231], v[40:43]
	v_mfma_f32_16x16x32_bf16 v[36:39], v[202:205], v[228:231], v[36:39]
	ds_read_b128 v[228:231], v179 offset:3072
	v_mfma_f32_16x16x32_bf16 v[32:35], v[136:139], v[236:239], v[32:35]
	v_mfma_f32_16x16x32_bf16 v[28:31], v[144:147], v[236:239], v[28:31]
	v_mfma_f32_16x16x32_bf16 v[24:27], v[194:197], v[236:239], v[24:27]
	v_mfma_f32_16x16x32_bf16 v[20:23], v[202:205], v[236:239], v[20:23]
	ds_read_b128 v[236:239], v179 offset:5120
	v_mfma_f32_16x16x32_bf16 v[16:19], v[136:139], v[244:247], v[16:19]
	v_mfma_f32_16x16x32_bf16 v[12:15], v[144:147], v[244:247], v[12:15]
	v_mfma_f32_16x16x32_bf16 v[8:11], v[194:197], v[244:247], v[8:11]
	v_mfma_f32_16x16x32_bf16 v[4:7], v[202:205], v[244:247], v[4:7]
	ds_read_b128 v[244:247], v179 offset:7168
	s_setprio 0
	s_waitcnt vmcnt(6)
	s_barrier
	s_add_i32 s97, s97, 2
	s_add_u32 s10, s10, 0x100
	s_addc_u32 s11, s11, 0
	s_add_u32 s89, s89, 0x100
	s_addc_u32 s90, s90, 0
	s_cmp_gt_u32 s97, 13
	s_cbranch_scc0 .LBB0_231
	s_waitcnt lgkmcnt(0)
	s_and_b64 vcc, exec, s[16:17]
	s_cbranch_vccz .LBB0_234
	s_barrier

.LBB0_292:
	s_add_u32 s97, s44, 0x100
	s_addc_u32 s50, s45, 0
	s_ashr_i32 s17, s16, 31
	s_lshl_b64 s[18:19], s[16:17], 19
	s_add_u32 s18, s42, s18
	s_addc_u32 s19, s43, s19
	s_and_b64 s[26:27], s[8:9], exec
	s_cselect_b32 s17, s19, s37
	s_cselect_b32 vcc_lo, s18, s36
	s_ashr_i32 s15, s14, 31
	s_lshl_b64 s[26:27], s[14:15], 19
	v_readlane_b32 s15, v253, 21
	s_add_u32 s26, s15, s26
	v_readlane_b32 s15, v253, 22
	s_addc_u32 s27, s15, s27
	s_and_b64 s[40:41], s[8:9], exec
	s_cselect_b32 s15, s27, s45
	s_cselect_b32 vcc_hi, s26, s44
	s_add_u32 s40, s36, 0x40080
	s_addc_u32 s41, s37, 0
	v_lshl_add_u64 v[140:141], s[40:41], 0, v[136:137]
	v_lshl_add_u64 v[142:143], s[40:41], 0, v[138:139]
	s_mov_b32 s51, -2
	s_mov_b64 s[44:45], 0
	ds_read_b128 v[194:197], v146
	ds_read_b128 v[198:201], v146 offset:1024
	ds_read_b128 v[202:205], v146 offset:2048
	ds_read_b128 v[206:209], v146 offset:3072
	ds_read_b128 v[218:221], v146 offset:4096
	ds_read_b128 v[224:227], v146 offset:5120
	ds_read_b128 v[228:231], v146 offset:6144
	ds_read_b128 v[232:235], v146 offset:7168
.LBB0_293:
	s_add_u32 s25, s36, s44
	s_addc_u32 s40, s37, s45
	s_add_u32 s25, s25, 0x100
	s_addc_u32 s40, s40, 0
	s_add_u32 s41, s97, s44
	s_addc_u32 s46, s50, s45
	s_add_i32 s70, 0, 0x10000
	s_cmpk_eq_i32 s44, 0x700
	s_cselect_b32 s49, s17, s40
	s_cselect_b32 s48, vcc_lo, s25
	v_add_u32_e32 v147, s70, v145
	s_cselect_b32 s47, s15, s46
	s_cselect_b32 s46, vcc_hi, s41
	s_add_i32 s25, 0, 0x14000
	ds_read_b128 v[152:155], v147
	ds_read_b128 v[156:159], v147 offset:1024
	ds_read_b128 v[160:163], v147 offset:2048
	ds_read_b128 v[164:167], v147 offset:3072
	v_add_u32_e32 v147, s25, v145
	ds_read_b128 v[168:171], v147
	ds_read_b128 v[172:175], v147 offset:1024
	ds_read_b128 v[176:179], v147 offset:2048
	ds_read_b128 v[190:193], v147 offset:3072
	v_lshl_add_u64 v[182:183], v[140:141], 0, s[44:45]
	s_add_i32 m0, s59, 0xc000
	global_load_lds_dwordx4 v[182:183], off
	v_lshl_add_u64 v[182:183], v[142:143], 0, s[44:45]
	s_add_i32 m0, s59, 0xe000
	s_nop 0
	global_load_lds_dwordx4 v[182:183], off
	s_waitcnt vmcnt(8)
	s_waitcnt lgkmcnt(0)
	s_barrier
	s_setprio 1
	s_waitcnt lgkmcnt(0)
	v_mfma_f32_16x16x32_bf16 v[128:131], v[152:155], v[194:197], v[128:131]
	v_mfma_f32_16x16x32_bf16 v[124:127], v[160:163], v[194:197], v[124:127]
	v_mfma_f32_16x16x32_bf16 v[120:123], v[168:171], v[194:197], v[120:123]
	v_mfma_f32_16x16x32_bf16 v[116:119], v[176:179], v[194:197], v[116:119]
	ds_read_b128 v[194:197], v146 offset:16384
	v_mfma_f32_16x16x32_bf16 v[112:115], v[152:155], v[202:205], v[112:115]
	v_mfma_f32_16x16x32_bf16 v[108:111], v[160:163], v[202:205], v[108:111]
	v_mfma_f32_16x16x32_bf16 v[100:103], v[168:171], v[202:205], v[100:103]
	v_mfma_f32_16x16x32_bf16 v[92:95], v[176:179], v[202:205], v[92:95]
	ds_read_b128 v[202:205], v146 offset:18432
	v_mfma_f32_16x16x32_bf16 v[104:107], v[152:155], v[218:221], v[104:107]
	v_mfma_f32_16x16x32_bf16 v[96:99], v[160:163], v[218:221], v[96:99]
	v_mfma_f32_16x16x32_bf16 v[84:87], v[168:171], v[218:221], v[84:87]
	v_mfma_f32_16x16x32_bf16 v[76:79], v[176:179], v[218:221], v[76:79]
	ds_read_b128 v[218:221], v146 offset:20480
	v_mfma_f32_16x16x32_bf16 v[88:91], v[152:155], v[228:231], v[88:91]
	v_mfma_f32_16x16x32_bf16 v[80:83], v[160:163], v[228:231], v[80:83]
	v_mfma_f32_16x16x32_bf16 v[72:75], v[168:171], v[228:231], v[72:75]
	v_mfma_f32_16x16x32_bf16 v[68:71], v[176:179], v[228:231], v[68:71]
	ds_read_b128 v[228:231], v146 offset:22528
	v_mfma_f32_16x16x32_bf16 v[128:131], v[156:159], v[198:201], v[128:131]
	v_mfma_f32_16x16x32_bf16 v[124:127], v[164:167], v[198:201], v[124:127]
	v_mfma_f32_16x16x32_bf16 v[120:123], v[172:175], v[198:201], v[120:123]
	v_mfma_f32_16x16x32_bf16 v[116:119], v[190:193], v[198:201], v[116:119]
	ds_read_b128 v[198:201], v146 offset:17408
	v_mfma_f32_16x16x32_bf16 v[112:115], v[156:159], v[206:209], v[112:115]
	v_mfma_f32_16x16x32_bf16 v[108:111], v[164:167], v[206:209], v[108:111]
	v_mfma_f32_16x16x32_bf16 v[100:103], v[172:175], v[206:209], v[100:103]
	v_mfma_f32_16x16x32_bf16 v[92:95], v[190:193], v[206:209], v[92:95]
	ds_read_b128 v[206:209], v146 offset:19456
	v_mfma_f32_16x16x32_bf16 v[104:107], v[156:159], v[224:227], v[104:107]
	v_mfma_f32_16x16x32_bf16 v[96:99], v[164:167], v[224:227], v[96:99]
	v_mfma_f32_16x16x32_bf16 v[84:87], v[172:175], v[224:227], v[84:87]
	v_mfma_f32_16x16x32_bf16 v[76:79], v[190:193], v[224:227], v[76:79]
	ds_read_b128 v[224:227], v146 offset:21504
	v_mfma_f32_16x16x32_bf16 v[88:91], v[156:159], v[232:235], v[88:91]
	v_mfma_f32_16x16x32_bf16 v[80:83], v[164:167], v[232:235], v[80:83]
	v_mfma_f32_16x16x32_bf16 v[72:75], v[172:175], v[232:235], v[72:75]
	v_mfma_f32_16x16x32_bf16 v[68:71], v[190:193], v[232:235], v[68:71]
	ds_read_b128 v[232:235], v146 offset:23552
	s_setprio 0
	s_waitcnt vmcnt(2)
	s_barrier
	s_add_i32 s40, s70, s58
	v_lshl_add_u64 v[182:183], s[46:47], 0, v[180:181]
	s_mov_b32 m0, s40
	global_load_lds_dwordx4 v[182:183], off
	s_add_i32 m0, s40, 0x2000
	s_add_u32 s40, s46, 0x40000
	v_lshl_add_u64 v[184:185], s[46:47], 0, v[134:135]
	s_addc_u32 s41, s47, 0
	s_add_i32 s25, s25, s58
	global_load_lds_dwordx4 v[184:185], off
	v_lshl_add_u64 v[210:211], s[40:41], 0, v[180:181]
	s_mov_b32 m0, s25
	v_lshl_add_u64 v[236:237], s[48:49], 0, v[132:133]
	global_load_lds_dwordx4 v[210:211], off
	v_lshl_add_u64 v[210:211], s[40:41], 0, v[134:135]
	s_add_i32 m0, s25, 0x2000
	s_nop 0
	global_load_lds_dwordx4 v[210:211], off
	v_lshl_add_u64 v[210:211], s[48:49], 0, v[0:1]
	s_mov_b32 m0, s59
	s_nop 0
	global_load_lds_dwordx4 v[210:211], off
	s_mov_b32 m0, s64
	s_nop 0
	global_load_lds_dwordx4 v[236:237], off
	s_waitcnt vmcnt(8)
	s_waitcnt lgkmcnt(0)
	s_barrier
	s_setprio 1
	s_waitcnt lgkmcnt(0)
	v_mfma_f32_16x16x32_bf16 v[64:67], v[152:155], v[194:197], v[64:67]
	v_mfma_f32_16x16x32_bf16 v[4:7], v[160:163], v[194:197], v[4:7]
	v_mfma_f32_16x16x32_bf16 v[12:15], v[168:171], v[194:197], v[12:15]
	v_mfma_f32_16x16x32_bf16 v[8:11], v[176:179], v[194:197], v[8:11]
	ds_read_b128 v[194:197], v146 offset:32768
	v_mfma_f32_16x16x32_bf16 v[60:63], v[152:155], v[202:205], v[60:63]
	v_mfma_f32_16x16x32_bf16 v[56:59], v[160:163], v[202:205], v[56:59]
	v_mfma_f32_16x16x32_bf16 v[20:23], v[168:171], v[202:205], v[20:23]
	v_mfma_f32_16x16x32_bf16 v[16:19], v[176:179], v[202:205], v[16:19]
	ds_read_b128 v[202:205], v146 offset:34816
	v_mfma_f32_16x16x32_bf16 v[52:55], v[152:155], v[218:221], v[52:55]
	v_mfma_f32_16x16x32_bf16 v[48:51], v[160:163], v[218:221], v[48:51]
	v_mfma_f32_16x16x32_bf16 v[28:31], v[168:171], v[218:221], v[28:31]
	v_mfma_f32_16x16x32_bf16 v[24:27], v[176:179], v[218:221], v[24:27]
	ds_read_b128 v[218:221], v146 offset:36864
	v_mfma_f32_16x16x32_bf16 v[44:47], v[152:155], v[228:231], v[44:47]
	v_mfma_f32_16x16x32_bf16 v[40:43], v[160:163], v[228:231], v[40:43]
	v_mfma_f32_16x16x32_bf16 v[36:39], v[168:171], v[228:231], v[36:39]
	v_mfma_f32_16x16x32_bf16 v[32:35], v[176:179], v[228:231], v[32:35]
	ds_read_b128 v[228:231], v146 offset:38912
	v_mfma_f32_16x16x32_bf16 v[64:67], v[156:159], v[198:201], v[64:67]
	v_mfma_f32_16x16x32_bf16 v[4:7], v[164:167], v[198:201], v[4:7]
	v_mfma_f32_16x16x32_bf16 v[12:15], v[172:175], v[198:201], v[12:15]
	v_mfma_f32_16x16x32_bf16 v[8:11], v[190:193], v[198:201], v[8:11]
	ds_read_b128 v[198:201], v146 offset:33792
	v_mfma_f32_16x16x32_bf16 v[60:63], v[156:159], v[206:209], v[60:63]
	v_mfma_f32_16x16x32_bf16 v[56:59], v[164:167], v[206:209], v[56:59]
	v_mfma_f32_16x16x32_bf16 v[20:23], v[172:175], v[206:209], v[20:23]
	v_mfma_f32_16x16x32_bf16 v[16:19], v[190:193], v[206:209], v[16:19]
	ds_read_b128 v[206:209], v146 offset:35840
	v_mfma_f32_16x16x32_bf16 v[52:55], v[156:159], v[224:227], v[52:55]
	v_mfma_f32_16x16x32_bf16 v[48:51], v[164:167], v[224:227], v[48:51]
	v_mfma_f32_16x16x32_bf16 v[28:31], v[172:175], v[224:227], v[28:31]
	v_mfma_f32_16x16x32_bf16 v[24:27], v[190:193], v[224:227], v[24:27]
	ds_read_b128 v[224:227], v146 offset:37888
	v_mfma_f32_16x16x32_bf16 v[44:47], v[156:159], v[232:235], v[44:47]
	v_mfma_f32_16x16x32_bf16 v[40:43], v[164:167], v[232:235], v[40:43]
	v_mfma_f32_16x16x32_bf16 v[36:39], v[172:175], v[232:235], v[36:39]
	v_mfma_f32_16x16x32_bf16 v[32:35], v[190:193], v[232:235], v[32:35]
	ds_read_b128 v[232:235], v146 offset:39936
	s_setprio 0
	s_waitcnt vmcnt(6)
	s_barrier
	s_add_i32 s25, 0, 0x18000
	v_add_u32_e32 v147, s25, v145
	s_add_i32 s70, 0, 0x1c000
	ds_read_b128 v[152:155], v147
	ds_read_b128 v[156:159], v147 offset:1024
	ds_read_b128 v[160:163], v147 offset:2048
	ds_read_b128 v[164:167], v147 offset:3072
	v_add_u32_e32 v147, s70, v145
	ds_read_b128 v[168:171], v147
	ds_read_b128 v[172:175], v147 offset:1024
	ds_read_b128 v[176:179], v147 offset:2048
	ds_read_b128 v[190:193], v147 offset:3072
	s_add_u32 s40, s48, 0x40000
	s_addc_u32 s41, s49, 0
	s_mov_b32 m0, s65
	v_lshl_add_u64 v[238:239], s[40:41], 0, v[0:1]
	global_load_lds_dwordx4 v[238:239], off
	v_lshl_add_u64 v[238:239], s[40:41], 0, v[132:133]
	s_mov_b32 m0, s68
	s_nop 0
	global_load_lds_dwordx4 v[238:239], off
	s_waitcnt vmcnt(8)
	s_waitcnt lgkmcnt(0)
	s_barrier
	s_setprio 1
	s_waitcnt lgkmcnt(0)
	v_mfma_f32_16x16x32_bf16 v[128:131], v[152:155], v[194:197], v[128:131]
	v_mfma_f32_16x16x32_bf16 v[124:127], v[160:163], v[194:197], v[124:127]
	v_mfma_f32_16x16x32_bf16 v[120:123], v[168:171], v[194:197], v[120:123]
	v_mfma_f32_16x16x32_bf16 v[116:119], v[176:179], v[194:197], v[116:119]
	ds_read_b128 v[194:197], v146 offset:49152
	v_mfma_f32_16x16x32_bf16 v[112:115], v[152:155], v[202:205], v[112:115]
	v_mfma_f32_16x16x32_bf16 v[108:111], v[160:163], v[202:205], v[108:111]
	v_mfma_f32_16x16x32_bf16 v[100:103], v[168:171], v[202:205], v[100:103]
	v_mfma_f32_16x16x32_bf16 v[92:95], v[176:179], v[202:205], v[92:95]
	ds_read_b128 v[202:205], v146 offset:51200
	v_mfma_f32_16x16x32_bf16 v[104:107], v[152:155], v[218:221], v[104:107]
	v_mfma_f32_16x16x32_bf16 v[96:99], v[160:163], v[218:221], v[96:99]
	v_mfma_f32_16x16x32_bf16 v[84:87], v[168:171], v[218:221], v[84:87]
	v_mfma_f32_16x16x32_bf16 v[76:79], v[176:179], v[218:221], v[76:79]
	ds_read_b128 v[218:221], v146 offset:53248
	v_mfma_f32_16x16x32_bf16 v[88:91], v[152:155], v[228:231], v[88:91]
	v_mfma_f32_16x16x32_bf16 v[80:83], v[160:163], v[228:231], v[80:83]
	v_mfma_f32_16x16x32_bf16 v[72:75], v[168:171], v[228:231], v[72:75]
	v_mfma_f32_16x16x32_bf16 v[68:71], v[176:179], v[228:231], v[68:71]
	ds_read_b128 v[228:231], v146 offset:55296
	v_mfma_f32_16x16x32_bf16 v[128:131], v[156:159], v[198:201], v[128:131]
	v_mfma_f32_16x16x32_bf16 v[124:127], v[164:167], v[198:201], v[124:127]
	v_mfma_f32_16x16x32_bf16 v[120:123], v[172:175], v[198:201], v[120:123]
	v_mfma_f32_16x16x32_bf16 v[116:119], v[190:193], v[198:201], v[116:119]
	ds_read_b128 v[198:201], v146 offset:50176
	v_mfma_f32_16x16x32_bf16 v[112:115], v[156:159], v[206:209], v[112:115]
	v_mfma_f32_16x16x32_bf16 v[108:111], v[164:167], v[206:209], v[108:111]
	v_mfma_f32_16x16x32_bf16 v[100:103], v[172:175], v[206:209], v[100:103]
	v_mfma_f32_16x16x32_bf16 v[92:95], v[190:193], v[206:209], v[92:95]
	ds_read_b128 v[206:209], v146 offset:52224
	v_mfma_f32_16x16x32_bf16 v[104:107], v[156:159], v[224:227], v[104:107]
	v_mfma_f32_16x16x32_bf16 v[96:99], v[164:167], v[224:227], v[96:99]
	v_mfma_f32_16x16x32_bf16 v[84:87], v[172:175], v[224:227], v[84:87]
	v_mfma_f32_16x16x32_bf16 v[76:79], v[190:193], v[224:227], v[76:79]
	ds_read_b128 v[224:227], v146 offset:54272
	v_mfma_f32_16x16x32_bf16 v[88:91], v[156:159], v[232:235], v[88:91]
	v_mfma_f32_16x16x32_bf16 v[80:83], v[164:167], v[232:235], v[80:83]
	v_mfma_f32_16x16x32_bf16 v[72:75], v[172:175], v[232:235], v[72:75]
	v_mfma_f32_16x16x32_bf16 v[68:71], v[190:193], v[232:235], v[68:71]
	ds_read_b128 v[232:235], v146 offset:56320
	s_setprio 0
	s_waitcnt vmcnt(2)
	s_barrier
	s_add_i32 s25, s25, s58
	v_lshl_add_u64 v[182:183], v[182:183], 0, s[94:95]
	s_mov_b32 m0, s25
	global_load_lds_dwordx4 v[182:183], off
	s_add_i32 m0, s25, 0x2000
	s_add_u32 s40, s46, 0x40080
	v_lshl_add_u64 v[182:183], v[184:185], 0, s[94:95]
	s_addc_u32 s41, s47, 0
	s_add_i32 s25, s70, s58
	global_load_lds_dwordx4 v[182:183], off
	v_lshl_add_u64 v[182:183], s[40:41], 0, v[180:181]
	s_mov_b32 m0, s25
	s_nop 0
	global_load_lds_dwordx4 v[182:183], off
	v_lshl_add_u64 v[182:183], s[40:41], 0, v[134:135]
	s_add_i32 m0, s25, 0x2000
	s_nop 0
	global_load_lds_dwordx4 v[182:183], off
	v_lshl_add_u64 v[182:183], v[210:211], 0, s[94:95]
	s_mov_b32 m0, s69
	s_nop 0
	global_load_lds_dwordx4 v[182:183], off
	v_lshl_add_u64 v[182:183], v[236:237], 0, s[94:95]
	s_mov_b32 m0, s88
	s_nop 0
	global_load_lds_dwordx4 v[182:183], off
	s_waitcnt vmcnt(8)
	s_waitcnt lgkmcnt(0)
	s_barrier
	s_setprio 1
	s_waitcnt lgkmcnt(0)
	v_mfma_f32_16x16x32_bf16 v[64:67], v[152:155], v[194:197], v[64:67]
	v_mfma_f32_16x16x32_bf16 v[4:7], v[160:163], v[194:197], v[4:7]
	v_mfma_f32_16x16x32_bf16 v[12:15], v[168:171], v[194:197], v[12:15]
	v_mfma_f32_16x16x32_bf16 v[8:11], v[176:179], v[194:197], v[8:11]
	ds_read_b128 v[194:197], v146
	v_mfma_f32_16x16x32_bf16 v[60:63], v[152:155], v[202:205], v[60:63]
	v_mfma_f32_16x16x32_bf16 v[56:59], v[160:163], v[202:205], v[56:59]
	v_mfma_f32_16x16x32_bf16 v[20:23], v[168:171], v[202:205], v[20:23]
	v_mfma_f32_16x16x32_bf16 v[16:19], v[176:179], v[202:205], v[16:19]
	ds_read_b128 v[202:205], v146 offset:2048
	v_mfma_f32_16x16x32_bf16 v[52:55], v[152:155], v[218:221], v[52:55]
	v_mfma_f32_16x16x32_bf16 v[48:51], v[160:163], v[218:221], v[48:51]
	v_mfma_f32_16x16x32_bf16 v[28:31], v[168:171], v[218:221], v[28:31]
	v_mfma_f32_16x16x32_bf16 v[24:27], v[176:179], v[218:221], v[24:27]
	ds_read_b128 v[218:221], v146 offset:4096
	v_mfma_f32_16x16x32_bf16 v[44:47], v[152:155], v[228:231], v[44:47]
	v_mfma_f32_16x16x32_bf16 v[40:43], v[160:163], v[228:231], v[40:43]
	v_mfma_f32_16x16x32_bf16 v[36:39], v[168:171], v[228:231], v[36:39]
	v_mfma_f32_16x16x32_bf16 v[32:35], v[176:179], v[228:231], v[32:35]
	ds_read_b128 v[228:231], v146 offset:6144
	v_mfma_f32_16x16x32_bf16 v[64:67], v[156:159], v[198:201], v[64:67]
	v_mfma_f32_16x16x32_bf16 v[4:7], v[164:167], v[198:201], v[4:7]
	v_mfma_f32_16x16x32_bf16 v[12:15], v[172:175], v[198:201], v[12:15]
	v_mfma_f32_16x16x32_bf16 v[8:11], v[190:193], v[198:201], v[8:11]
	ds_read_b128 v[198:201], v146 offset:1024
	v_mfma_f32_16x16x32_bf16 v[60:63], v[156:159], v[206:209], v[60:63]
	v_mfma_f32_16x16x32_bf16 v[56:59], v[164:167], v[206:209], v[56:59]
	v_mfma_f32_16x16x32_bf16 v[20:23], v[172:175], v[206:209], v[20:23]
	v_mfma_f32_16x16x32_bf16 v[16:19], v[190:193], v[206:209], v[16:19]
	ds_read_b128 v[206:209], v146 offset:3072
	v_mfma_f32_16x16x32_bf16 v[52:55], v[156:159], v[224:227], v[52:55]
	v_mfma_f32_16x16x32_bf16 v[48:51], v[164:167], v[224:227], v[48:51]
	v_mfma_f32_16x16x32_bf16 v[28:31], v[172:175], v[224:227], v[28:31]
	v_mfma_f32_16x16x32_bf16 v[24:27], v[190:193], v[224:227], v[24:27]
	ds_read_b128 v[224:227], v146 offset:5120
	v_mfma_f32_16x16x32_bf16 v[44:47], v[156:159], v[232:235], v[44:47]
	v_mfma_f32_16x16x32_bf16 v[40:43], v[164:167], v[232:235], v[40:43]
	v_mfma_f32_16x16x32_bf16 v[36:39], v[172:175], v[232:235], v[36:39]
	v_mfma_f32_16x16x32_bf16 v[32:35], v[190:193], v[232:235], v[32:35]
	ds_read_b128 v[232:235], v146 offset:7168
	s_setprio 0
	s_waitcnt vmcnt(6)
	s_barrier
	s_add_i32 s51, s51, 2
	s_add_u32 s44, s44, 0x100
	s_addc_u32 s45, s45, 0
	s_cmp_gt_u32 s51, 13
	s_cbranch_scc0 .LBB0_293
	s_waitcnt lgkmcnt(0)
	s_and_b64 vcc, exec, s[12:13]
	s_cbranch_vccz .LBB0_296
	s_barrier

.LBB0_333:
	s_ashr_i32 s19, s18, 31
	s_lshl_b64 s[26:27], s[18:19], 19
	s_add_u32 s26, s84, s26
	s_addc_u32 s27, s85, s27
	s_and_b64 s[36:37], s[8:9], exec
	s_cselect_b32 s19, s27, s45
	s_cselect_b32 s64, s26, s44
	s_ashr_i32 s17, s16, 31
	s_lshl_b64 s[36:37], s[16:17], 19
	v_readlane_b32 s17, v253, 47
	s_add_u32 s36, s17, s36
	v_readlane_b32 s17, v253, 48
	s_addc_u32 s37, s17, s37
	s_and_b64 s[40:41], s[8:9], exec
	s_cselect_b32 s17, s37, s47
	s_cselect_b32 s65, s36, s46
	s_add_u32 s44, s44, 0x40080
	s_addc_u32 s45, s45, 0
	s_add_u32 s68, s46, 0x100
	v_mov_b32_e32 v4, 0
	s_addc_u32 s69, s47, 0
	s_mov_b32 s88, -2
	s_waitcnt lgkmcnt(0)
	v_mov_b32_e32 v5, v4
	v_mov_b32_e32 v6, v4
	v_mov_b32_e32 v7, v4
	v_mov_b32_e32 v8, v4
	v_mov_b32_e32 v9, v4
	v_mov_b32_e32 v10, v4
	v_mov_b32_e32 v11, v4
	v_mov_b32_e32 v20, v4
	v_mov_b32_e32 v21, v4
	v_mov_b32_e32 v22, v4
	v_mov_b32_e32 v23, v4
	v_mov_b32_e32 v24, v4
	v_mov_b32_e32 v25, v4
	v_mov_b32_e32 v26, v4
	v_mov_b32_e32 v27, v4
	v_mov_b32_e32 v36, v4
	v_mov_b32_e32 v37, v4
	v_mov_b32_e32 v38, v4
	v_mov_b32_e32 v39, v4
	v_mov_b32_e32 v40, v4
	v_mov_b32_e32 v41, v4
	v_mov_b32_e32 v42, v4
	v_mov_b32_e32 v43, v4
	v_mov_b32_e32 v52, v4
	v_mov_b32_e32 v53, v4
	v_mov_b32_e32 v54, v4
	v_mov_b32_e32 v55, v4
	v_mov_b32_e32 v56, v4
	v_mov_b32_e32 v57, v4
	v_mov_b32_e32 v58, v4
	v_mov_b32_e32 v59, v4
	v_mov_b32_e32 v12, v4
	v_mov_b32_e32 v13, v4
	v_mov_b32_e32 v14, v4
	v_mov_b32_e32 v15, v4
	v_mov_b32_e32 v16, v4
	v_mov_b32_e32 v17, v4
	v_mov_b32_e32 v18, v4
	v_mov_b32_e32 v19, v4
	v_mov_b32_e32 v28, v4
	v_mov_b32_e32 v29, v4
	v_mov_b32_e32 v30, v4
	v_mov_b32_e32 v31, v4
	v_mov_b32_e32 v32, v4
	v_mov_b32_e32 v33, v4
	v_mov_b32_e32 v34, v4
	v_mov_b32_e32 v35, v4
	v_mov_b32_e32 v44, v4
	v_mov_b32_e32 v45, v4
	v_mov_b32_e32 v46, v4
	v_mov_b32_e32 v47, v4
	v_mov_b32_e32 v48, v4
	v_mov_b32_e32 v49, v4
	v_mov_b32_e32 v50, v4
	v_mov_b32_e32 v51, v4
	v_mov_b32_e32 v60, v4
	v_mov_b32_e32 v61, v4
	v_mov_b32_e32 v62, v4
	v_mov_b32_e32 v63, v4
	v_mov_b32_e32 v64, v4
	v_mov_b32_e32 v65, v4
	v_mov_b32_e32 v66, v4
	v_mov_b32_e32 v67, v4
	v_mov_b32_e32 v68, v4
	v_mov_b32_e32 v69, v4
	v_mov_b32_e32 v70, v4
	v_mov_b32_e32 v71, v4
	v_mov_b32_e32 v72, v4
	v_mov_b32_e32 v73, v4
	v_mov_b32_e32 v74, v4
	v_mov_b32_e32 v75, v4
	v_mov_b32_e32 v84, v4
	v_mov_b32_e32 v85, v4
	v_mov_b32_e32 v86, v4
	v_mov_b32_e32 v87, v4
	v_mov_b32_e32 v88, v4
	v_mov_b32_e32 v89, v4
	v_mov_b32_e32 v90, v4
	v_mov_b32_e32 v91, v4
	v_mov_b32_e32 v100, v4
	v_mov_b32_e32 v101, v4
	v_mov_b32_e32 v102, v4
	v_mov_b32_e32 v103, v4
	v_mov_b32_e32 v104, v4
	v_mov_b32_e32 v105, v4
	v_mov_b32_e32 v106, v4
	v_mov_b32_e32 v107, v4
	v_mov_b32_e32 v116, v4
	v_mov_b32_e32 v117, v4
	v_mov_b32_e32 v118, v4
	v_mov_b32_e32 v119, v4
	v_mov_b32_e32 v120, v4
	v_mov_b32_e32 v121, v4
	v_mov_b32_e32 v122, v4
	v_mov_b32_e32 v123, v4
	v_mov_b32_e32 v76, v4
	v_mov_b32_e32 v77, v4
	v_mov_b32_e32 v78, v4
	v_mov_b32_e32 v79, v4
	v_mov_b32_e32 v80, v4
	v_mov_b32_e32 v81, v4
	v_mov_b32_e32 v82, v4
	v_mov_b32_e32 v83, v4
	v_mov_b32_e32 v92, v4
	v_mov_b32_e32 v93, v4
	v_mov_b32_e32 v94, v4
	v_mov_b32_e32 v95, v4
	v_mov_b32_e32 v96, v4
	v_mov_b32_e32 v97, v4
	v_mov_b32_e32 v98, v4
	v_mov_b32_e32 v99, v4
	v_mov_b32_e32 v108, v4
	v_mov_b32_e32 v109, v4
	v_mov_b32_e32 v110, v4
	v_mov_b32_e32 v111, v4
	v_mov_b32_e32 v112, v4
	v_mov_b32_e32 v113, v4
	v_mov_b32_e32 v114, v4
	v_mov_b32_e32 v115, v4
	v_mov_b32_e32 v124, v4
	v_mov_b32_e32 v125, v4
	v_mov_b32_e32 v126, v4
	v_mov_b32_e32 v127, v4
	v_mov_b32_e32 v128, v4
	v_mov_b32_e32 v129, v4
	v_mov_b32_e32 v130, v4
	v_mov_b32_e32 v131, v4
	ds_read_b128 v[174:177], v194
	ds_read_b128 v[196:199], v194 offset:1024
	ds_read_b128 v[200:203], v194 offset:2048
	ds_read_b128 v[204:207], v194 offset:3072
	ds_read_b128 v[208:211], v194 offset:4096
	ds_read_b128 v[218:221], v194 offset:5120
	ds_read_b128 v[224:227], v194 offset:6144
	ds_read_b128 v[228:231], v194 offset:7168
.LBB0_334:
	s_add_u32 s25, s44, 0xfffc0080
	s_addc_u32 s40, s45, -1
	s_add_i32 s41, 0, 0x10000
	s_cmp_eq_u32 s88, 12
	s_cselect_b32 s49, s19, s40
	s_cselect_b32 s48, s64, s25
	s_cselect_b32 s47, s17, s69
	s_cselect_b32 s46, s65, s68
	s_add_i32 s25, 0, 0x14000
	v_add_u32_e32 v144, s41, v187
	v_add_u32_e32 v170, s25, v187
	ds_read_b128 v[132:135], v144
	ds_read_b128 v[136:139], v144 offset:1024
	ds_read_b128 v[140:143], v144 offset:2048
	ds_read_b128 v[144:147], v144 offset:3072
	ds_read_b128 v[148:151], v170
	ds_read_b128 v[152:155], v170 offset:1024
	ds_read_b128 v[156:159], v170 offset:2048
	ds_read_b128 v[170:173], v170 offset:3072
	v_lshl_add_u64 v[178:179], s[44:45], 0, v[166:167]
	s_add_i32 m0, s51, 0xc000
	global_load_lds_dwordx4 v[178:179], off
	v_lshl_add_u64 v[178:179], s[44:45], 0, v[168:169]
	s_add_i32 m0, s51, 0xe000
	s_nop 0
	global_load_lds_dwordx4 v[178:179], off
	s_waitcnt vmcnt(8)
	s_waitcnt lgkmcnt(0)
	s_barrier
	s_setprio 1
	s_waitcnt lgkmcnt(0)
	v_mfma_f32_16x16x32_bf16 v[128:131], v[132:135], v[174:177], v[128:131]
	v_mfma_f32_16x16x32_bf16 v[124:127], v[140:143], v[174:177], v[124:127]
	v_mfma_f32_16x16x32_bf16 v[120:123], v[148:151], v[174:177], v[120:123]
	v_mfma_f32_16x16x32_bf16 v[116:119], v[156:159], v[174:177], v[116:119]
	ds_read_b128 v[174:177], v194 offset:16384
	v_mfma_f32_16x16x32_bf16 v[112:115], v[132:135], v[200:203], v[112:115]
	v_mfma_f32_16x16x32_bf16 v[108:111], v[140:143], v[200:203], v[108:111]
	v_mfma_f32_16x16x32_bf16 v[104:107], v[148:151], v[200:203], v[104:107]
	v_mfma_f32_16x16x32_bf16 v[100:103], v[156:159], v[200:203], v[100:103]
	ds_read_b128 v[200:203], v194 offset:18432
	v_mfma_f32_16x16x32_bf16 v[96:99], v[132:135], v[208:211], v[96:99]
	v_mfma_f32_16x16x32_bf16 v[92:95], v[140:143], v[208:211], v[92:95]
	v_mfma_f32_16x16x32_bf16 v[88:91], v[148:151], v[208:211], v[88:91]
	v_mfma_f32_16x16x32_bf16 v[84:87], v[156:159], v[208:211], v[84:87]
	ds_read_b128 v[208:211], v194 offset:20480
	v_mfma_f32_16x16x32_bf16 v[80:83], v[132:135], v[224:227], v[80:83]
	v_mfma_f32_16x16x32_bf16 v[76:79], v[140:143], v[224:227], v[76:79]
	v_mfma_f32_16x16x32_bf16 v[72:75], v[148:151], v[224:227], v[72:75]
	v_mfma_f32_16x16x32_bf16 v[68:71], v[156:159], v[224:227], v[68:71]
	ds_read_b128 v[224:227], v194 offset:22528
	v_mfma_f32_16x16x32_bf16 v[128:131], v[136:139], v[196:199], v[128:131]
	v_mfma_f32_16x16x32_bf16 v[124:127], v[144:147], v[196:199], v[124:127]
	v_mfma_f32_16x16x32_bf16 v[120:123], v[152:155], v[196:199], v[120:123]
	v_mfma_f32_16x16x32_bf16 v[116:119], v[170:173], v[196:199], v[116:119]
	ds_read_b128 v[196:199], v194 offset:17408
	v_mfma_f32_16x16x32_bf16 v[112:115], v[136:139], v[204:207], v[112:115]
	v_mfma_f32_16x16x32_bf16 v[108:111], v[144:147], v[204:207], v[108:111]
	v_mfma_f32_16x16x32_bf16 v[104:107], v[152:155], v[204:207], v[104:107]
	v_mfma_f32_16x16x32_bf16 v[100:103], v[170:173], v[204:207], v[100:103]
	ds_read_b128 v[204:207], v194 offset:19456
	v_mfma_f32_16x16x32_bf16 v[96:99], v[136:139], v[218:221], v[96:99]
	v_mfma_f32_16x16x32_bf16 v[92:95], v[144:147], v[218:221], v[92:95]
	v_mfma_f32_16x16x32_bf16 v[88:91], v[152:155], v[218:221], v[88:91]
	v_mfma_f32_16x16x32_bf16 v[84:87], v[170:173], v[218:221], v[84:87]
	ds_read_b128 v[218:221], v194 offset:21504
	v_mfma_f32_16x16x32_bf16 v[80:83], v[136:139], v[228:231], v[80:83]
	v_mfma_f32_16x16x32_bf16 v[76:79], v[144:147], v[228:231], v[76:79]
	v_mfma_f32_16x16x32_bf16 v[72:75], v[152:155], v[228:231], v[72:75]
	v_mfma_f32_16x16x32_bf16 v[68:71], v[170:173], v[228:231], v[68:71]
	ds_read_b128 v[228:231], v194 offset:23552
	s_setprio 0
	s_waitcnt vmcnt(2)
	s_barrier
	s_add_i32 s40, s41, s50
	v_lshl_add_u64 v[178:179], s[46:47], 0, v[162:163]
	s_mov_b32 m0, s40
	global_load_lds_dwordx4 v[178:179], off
	s_add_i32 m0, s40, 0x2000
	s_add_u32 s40, s46, 0x40000
	v_lshl_add_u64 v[182:183], s[46:47], 0, v[0:1]
	s_addc_u32 s41, s47, 0
	s_add_i32 s25, s25, s50
	global_load_lds_dwordx4 v[182:183], off
	v_lshl_add_u64 v[184:185], s[40:41], 0, v[162:163]
	s_mov_b32 m0, s25
	v_lshl_add_u64 v[190:191], s[48:49], 0, v[160:161]
	global_load_lds_dwordx4 v[184:185], off
	v_lshl_add_u64 v[184:185], s[40:41], 0, v[0:1]
	s_add_i32 m0, s25, 0x2000
	s_nop 0
	global_load_lds_dwordx4 v[184:185], off
	v_lshl_add_u64 v[184:185], s[48:49], 0, v[164:165]
	s_mov_b32 m0, s51
	s_nop 0
	global_load_lds_dwordx4 v[184:185], off
	s_mov_b32 m0, s52
	s_nop 0
	global_load_lds_dwordx4 v[190:191], off
	s_waitcnt vmcnt(8)
	s_waitcnt lgkmcnt(0)
	s_barrier
	s_setprio 1
	s_waitcnt lgkmcnt(0)
	v_mfma_f32_16x16x32_bf16 v[64:67], v[132:135], v[174:177], v[64:67]
	v_mfma_f32_16x16x32_bf16 v[60:63], v[140:143], v[174:177], v[60:63]
	v_mfma_f32_16x16x32_bf16 v[56:59], v[148:151], v[174:177], v[56:59]
	v_mfma_f32_16x16x32_bf16 v[52:55], v[156:159], v[174:177], v[52:55]
	ds_read_b128 v[174:177], v194 offset:32768
	v_mfma_f32_16x16x32_bf16 v[48:51], v[132:135], v[200:203], v[48:51]
	v_mfma_f32_16x16x32_bf16 v[44:47], v[140:143], v[200:203], v[44:47]
	v_mfma_f32_16x16x32_bf16 v[40:43], v[148:151], v[200:203], v[40:43]
	v_mfma_f32_16x16x32_bf16 v[36:39], v[156:159], v[200:203], v[36:39]
	ds_read_b128 v[200:203], v194 offset:34816
	v_mfma_f32_16x16x32_bf16 v[32:35], v[132:135], v[208:211], v[32:35]
	v_mfma_f32_16x16x32_bf16 v[28:31], v[140:143], v[208:211], v[28:31]
	v_mfma_f32_16x16x32_bf16 v[24:27], v[148:151], v[208:211], v[24:27]
	v_mfma_f32_16x16x32_bf16 v[20:23], v[156:159], v[208:211], v[20:23]
	ds_read_b128 v[208:211], v194 offset:36864
	v_mfma_f32_16x16x32_bf16 v[16:19], v[132:135], v[224:227], v[16:19]
	v_mfma_f32_16x16x32_bf16 v[12:15], v[140:143], v[224:227], v[12:15]
	v_mfma_f32_16x16x32_bf16 v[8:11], v[148:151], v[224:227], v[8:11]
	v_mfma_f32_16x16x32_bf16 v[4:7], v[156:159], v[224:227], v[4:7]
	ds_read_b128 v[224:227], v194 offset:38912
	v_mfma_f32_16x16x32_bf16 v[64:67], v[136:139], v[196:199], v[64:67]
	v_mfma_f32_16x16x32_bf16 v[60:63], v[144:147], v[196:199], v[60:63]
	v_mfma_f32_16x16x32_bf16 v[56:59], v[152:155], v[196:199], v[56:59]
	v_mfma_f32_16x16x32_bf16 v[52:55], v[170:173], v[196:199], v[52:55]
	ds_read_b128 v[196:199], v194 offset:33792
	v_mfma_f32_16x16x32_bf16 v[48:51], v[136:139], v[204:207], v[48:51]
	v_mfma_f32_16x16x32_bf16 v[44:47], v[144:147], v[204:207], v[44:47]
	v_mfma_f32_16x16x32_bf16 v[40:43], v[152:155], v[204:207], v[40:43]
	v_mfma_f32_16x16x32_bf16 v[36:39], v[170:173], v[204:207], v[36:39]
	ds_read_b128 v[204:207], v194 offset:35840
	v_mfma_f32_16x16x32_bf16 v[32:35], v[136:139], v[218:221], v[32:35]
	v_mfma_f32_16x16x32_bf16 v[28:31], v[144:147], v[218:221], v[28:31]
	v_mfma_f32_16x16x32_bf16 v[24:27], v[152:155], v[218:221], v[24:27]
	v_mfma_f32_16x16x32_bf16 v[20:23], v[170:173], v[218:221], v[20:23]
	ds_read_b128 v[218:221], v194 offset:37888
	v_mfma_f32_16x16x32_bf16 v[16:19], v[136:139], v[228:231], v[16:19]
	v_mfma_f32_16x16x32_bf16 v[12:15], v[144:147], v[228:231], v[12:15]
	v_mfma_f32_16x16x32_bf16 v[8:11], v[152:155], v[228:231], v[8:11]
	v_mfma_f32_16x16x32_bf16 v[4:7], v[170:173], v[228:231], v[4:7]
	ds_read_b128 v[228:231], v194 offset:39936
	s_setprio 0
	s_waitcnt vmcnt(6)
	s_barrier
	s_add_i32 s25, 0, 0x18000
	s_add_i32 s70, 0, 0x1c000
	v_add_u32_e32 v144, s25, v187
	v_add_u32_e32 v170, s70, v187
	ds_read_b128 v[132:135], v144
	ds_read_b128 v[136:139], v144 offset:1024
	ds_read_b128 v[140:143], v144 offset:2048
	ds_read_b128 v[144:147], v144 offset:3072
	ds_read_b128 v[148:151], v170
	ds_read_b128 v[152:155], v170 offset:1024
	ds_read_b128 v[156:159], v170 offset:2048
	ds_read_b128 v[170:173], v170 offset:3072
	s_add_u32 s40, s48, 0x40000
	s_addc_u32 s41, s49, 0
	s_mov_b32 m0, s53
	v_lshl_add_u64 v[232:233], s[40:41], 0, v[164:165]
	global_load_lds_dwordx4 v[232:233], off
	v_lshl_add_u64 v[232:233], s[40:41], 0, v[160:161]
	s_mov_b32 m0, s54
	s_nop 0
	global_load_lds_dwordx4 v[232:233], off
	s_waitcnt vmcnt(8)
	s_waitcnt lgkmcnt(0)
	s_barrier
	s_setprio 1
	s_waitcnt lgkmcnt(0)
	v_mfma_f32_16x16x32_bf16 v[128:131], v[132:135], v[174:177], v[128:131]
	v_mfma_f32_16x16x32_bf16 v[124:127], v[140:143], v[174:177], v[124:127]
	v_mfma_f32_16x16x32_bf16 v[120:123], v[148:151], v[174:177], v[120:123]
	v_mfma_f32_16x16x32_bf16 v[116:119], v[156:159], v[174:177], v[116:119]
	ds_read_b128 v[174:177], v194 offset:49152
	v_mfma_f32_16x16x32_bf16 v[112:115], v[132:135], v[200:203], v[112:115]
	v_mfma_f32_16x16x32_bf16 v[108:111], v[140:143], v[200:203], v[108:111]
	v_mfma_f32_16x16x32_bf16 v[104:107], v[148:151], v[200:203], v[104:107]
	v_mfma_f32_16x16x32_bf16 v[100:103], v[156:159], v[200:203], v[100:103]
	ds_read_b128 v[200:203], v194 offset:51200
	v_mfma_f32_16x16x32_bf16 v[96:99], v[132:135], v[208:211], v[96:99]
	v_mfma_f32_16x16x32_bf16 v[92:95], v[140:143], v[208:211], v[92:95]
	v_mfma_f32_16x16x32_bf16 v[88:91], v[148:151], v[208:211], v[88:91]
	v_mfma_f32_16x16x32_bf16 v[84:87], v[156:159], v[208:211], v[84:87]
	ds_read_b128 v[208:211], v194 offset:53248
	v_mfma_f32_16x16x32_bf16 v[80:83], v[132:135], v[224:227], v[80:83]
	v_mfma_f32_16x16x32_bf16 v[76:79], v[140:143], v[224:227], v[76:79]
	v_mfma_f32_16x16x32_bf16 v[72:75], v[148:151], v[224:227], v[72:75]
	v_mfma_f32_16x16x32_bf16 v[68:71], v[156:159], v[224:227], v[68:71]
	ds_read_b128 v[224:227], v194 offset:55296
	v_mfma_f32_16x16x32_bf16 v[128:131], v[136:139], v[196:199], v[128:131]
	v_mfma_f32_16x16x32_bf16 v[124:127], v[144:147], v[196:199], v[124:127]
	v_mfma_f32_16x16x32_bf16 v[120:123], v[152:155], v[196:199], v[120:123]
	v_mfma_f32_16x16x32_bf16 v[116:119], v[170:173], v[196:199], v[116:119]
	ds_read_b128 v[196:199], v194 offset:50176
	v_mfma_f32_16x16x32_bf16 v[112:115], v[136:139], v[204:207], v[112:115]
	v_mfma_f32_16x16x32_bf16 v[108:111], v[144:147], v[204:207], v[108:111]
	v_mfma_f32_16x16x32_bf16 v[104:107], v[152:155], v[204:207], v[104:107]
	v_mfma_f32_16x16x32_bf16 v[100:103], v[170:173], v[204:207], v[100:103]
	ds_read_b128 v[204:207], v194 offset:52224
	v_mfma_f32_16x16x32_bf16 v[96:99], v[136:139], v[218:221], v[96:99]
	v_mfma_f32_16x16x32_bf16 v[92:95], v[144:147], v[218:221], v[92:95]
	v_mfma_f32_16x16x32_bf16 v[88:91], v[152:155], v[218:221], v[88:91]
	v_mfma_f32_16x16x32_bf16 v[84:87], v[170:173], v[218:221], v[84:87]
	ds_read_b128 v[218:221], v194 offset:54272
	v_mfma_f32_16x16x32_bf16 v[80:83], v[136:139], v[228:231], v[80:83]
	v_mfma_f32_16x16x32_bf16 v[76:79], v[144:147], v[228:231], v[76:79]
	v_mfma_f32_16x16x32_bf16 v[72:75], v[152:155], v[228:231], v[72:75]
	v_mfma_f32_16x16x32_bf16 v[68:71], v[170:173], v[228:231], v[68:71]
	ds_read_b128 v[228:231], v194 offset:56320
	s_setprio 0
	s_waitcnt vmcnt(2)
	s_barrier
	s_add_i32 s25, s25, s50
	v_lshl_add_u64 v[178:179], v[178:179], 0, s[94:95]
	s_mov_b32 m0, s25
	global_load_lds_dwordx4 v[178:179], off
	s_add_i32 m0, s25, 0x2000
	s_add_u32 s40, s46, 0x40080
	v_lshl_add_u64 v[178:179], v[182:183], 0, s[94:95]
	s_addc_u32 s41, s47, 0
	s_add_i32 s25, s70, s50
	global_load_lds_dwordx4 v[178:179], off
	v_lshl_add_u64 v[178:179], s[40:41], 0, v[162:163]
	s_mov_b32 m0, s25
	s_nop 0
	global_load_lds_dwordx4 v[178:179], off
	v_lshl_add_u64 v[178:179], s[40:41], 0, v[0:1]
	s_add_i32 m0, s25, 0x2000
	s_nop 0
	global_load_lds_dwordx4 v[178:179], off
	v_lshl_add_u64 v[178:179], v[184:185], 0, s[94:95]
	s_mov_b32 m0, s55
	s_nop 0
	global_load_lds_dwordx4 v[178:179], off
	v_lshl_add_u64 v[178:179], v[190:191], 0, s[94:95]
	s_mov_b32 m0, s58
	s_nop 0
	global_load_lds_dwordx4 v[178:179], off
	s_waitcnt vmcnt(8)
	s_waitcnt lgkmcnt(0)
	s_barrier
	s_setprio 1
	s_waitcnt lgkmcnt(0)
	v_mfma_f32_16x16x32_bf16 v[64:67], v[132:135], v[174:177], v[64:67]
	v_mfma_f32_16x16x32_bf16 v[60:63], v[140:143], v[174:177], v[60:63]
	v_mfma_f32_16x16x32_bf16 v[56:59], v[148:151], v[174:177], v[56:59]
	v_mfma_f32_16x16x32_bf16 v[52:55], v[156:159], v[174:177], v[52:55]
	ds_read_b128 v[174:177], v194
	v_mfma_f32_16x16x32_bf16 v[48:51], v[132:135], v[200:203], v[48:51]
	v_mfma_f32_16x16x32_bf16 v[44:47], v[140:143], v[200:203], v[44:47]
	v_mfma_f32_16x16x32_bf16 v[40:43], v[148:151], v[200:203], v[40:43]
	v_mfma_f32_16x16x32_bf16 v[36:39], v[156:159], v[200:203], v[36:39]
	ds_read_b128 v[200:203], v194 offset:2048
	v_mfma_f32_16x16x32_bf16 v[32:35], v[132:135], v[208:211], v[32:35]
	v_mfma_f32_16x16x32_bf16 v[28:31], v[140:143], v[208:211], v[28:31]
	v_mfma_f32_16x16x32_bf16 v[24:27], v[148:151], v[208:211], v[24:27]
	v_mfma_f32_16x16x32_bf16 v[20:23], v[156:159], v[208:211], v[20:23]
	ds_read_b128 v[208:211], v194 offset:4096
	v_mfma_f32_16x16x32_bf16 v[16:19], v[132:135], v[224:227], v[16:19]
	v_mfma_f32_16x16x32_bf16 v[12:15], v[140:143], v[224:227], v[12:15]
	v_mfma_f32_16x16x32_bf16 v[8:11], v[148:151], v[224:227], v[8:11]
	v_mfma_f32_16x16x32_bf16 v[4:7], v[156:159], v[224:227], v[4:7]
	ds_read_b128 v[224:227], v194 offset:6144
	v_mfma_f32_16x16x32_bf16 v[64:67], v[136:139], v[196:199], v[64:67]
	v_mfma_f32_16x16x32_bf16 v[60:63], v[144:147], v[196:199], v[60:63]
	v_mfma_f32_16x16x32_bf16 v[56:59], v[152:155], v[196:199], v[56:59]
	v_mfma_f32_16x16x32_bf16 v[52:55], v[170:173], v[196:199], v[52:55]
	ds_read_b128 v[196:199], v194 offset:1024
	v_mfma_f32_16x16x32_bf16 v[48:51], v[136:139], v[204:207], v[48:51]
	v_mfma_f32_16x16x32_bf16 v[44:47], v[144:147], v[204:207], v[44:47]
	v_mfma_f32_16x16x32_bf16 v[40:43], v[152:155], v[204:207], v[40:43]
	v_mfma_f32_16x16x32_bf16 v[36:39], v[170:173], v[204:207], v[36:39]
	ds_read_b128 v[204:207], v194 offset:3072
	v_mfma_f32_16x16x32_bf16 v[32:35], v[136:139], v[218:221], v[32:35]
	v_mfma_f32_16x16x32_bf16 v[28:31], v[144:147], v[218:221], v[28:31]
	v_mfma_f32_16x16x32_bf16 v[24:27], v[152:155], v[218:221], v[24:27]
	v_mfma_f32_16x16x32_bf16 v[20:23], v[170:173], v[218:221], v[20:23]
	ds_read_b128 v[218:221], v194 offset:5120
	v_mfma_f32_16x16x32_bf16 v[16:19], v[136:139], v[228:231], v[16:19]
	v_mfma_f32_16x16x32_bf16 v[12:15], v[144:147], v[228:231], v[12:15]
	v_mfma_f32_16x16x32_bf16 v[8:11], v[152:155], v[228:231], v[8:11]
	v_mfma_f32_16x16x32_bf16 v[4:7], v[170:173], v[228:231], v[4:7]
	ds_read_b128 v[228:231], v194 offset:7168
	s_setprio 0
	s_waitcnt vmcnt(6)
	s_barrier
	s_add_i32 s88, s88, 2
	s_add_u32 s44, s44, 0x100
	s_addc_u32 s45, s45, 0
	s_add_u32 s68, s68, 0x100
	s_addc_u32 s69, s69, 0
	s_cmp_gt_u32 s88, 13
	s_cbranch_scc0 .LBB0_334
	s_waitcnt lgkmcnt(0)
	s_and_b64 vcc, exec, s[12:13]
	s_cbranch_vccz .LBB0_337
	s_barrier

.LBB0_594:
	s_add_u32 s69, s36, 0x100
	v_mov_b32_e32 v4, 0
	s_addc_u32 s88, s37, 0
	s_mov_b32 s89, -2
	v_mov_b32_e32 v5, v4
	v_mov_b32_e32 v6, v4
	v_mov_b32_e32 v7, v4
	v_mov_b32_e32 v8, v4
	v_mov_b32_e32 v9, v4
	v_mov_b32_e32 v10, v4
	v_mov_b32_e32 v11, v4
	v_mov_b32_e32 v16, v4
	v_mov_b32_e32 v17, v4
	v_mov_b32_e32 v18, v4
	v_mov_b32_e32 v19, v4
	v_mov_b32_e32 v24, v4
	v_mov_b32_e32 v25, v4
	v_mov_b32_e32 v26, v4
	v_mov_b32_e32 v27, v4
	v_mov_b32_e32 v32, v4
	v_mov_b32_e32 v33, v4
	v_mov_b32_e32 v34, v4
	v_mov_b32_e32 v35, v4
	v_mov_b32_e32 v40, v4
	v_mov_b32_e32 v41, v4
	v_mov_b32_e32 v42, v4
	v_mov_b32_e32 v43, v4
	v_mov_b32_e32 v48, v4
	v_mov_b32_e32 v49, v4
	v_mov_b32_e32 v50, v4
	v_mov_b32_e32 v51, v4
	v_mov_b32_e32 v56, v4
	v_mov_b32_e32 v57, v4
	v_mov_b32_e32 v58, v4
	v_mov_b32_e32 v59, v4
	v_mov_b32_e32 v12, v4
	v_mov_b32_e32 v13, v4
	v_mov_b32_e32 v14, v4
	v_mov_b32_e32 v15, v4
	v_mov_b32_e32 v20, v4
	v_mov_b32_e32 v21, v4
	v_mov_b32_e32 v22, v4
	v_mov_b32_e32 v23, v4
	v_mov_b32_e32 v28, v4
	v_mov_b32_e32 v29, v4
	v_mov_b32_e32 v30, v4
	v_mov_b32_e32 v31, v4
	v_mov_b32_e32 v36, v4
	v_mov_b32_e32 v37, v4
	v_mov_b32_e32 v38, v4
	v_mov_b32_e32 v39, v4
	v_mov_b32_e32 v44, v4
	v_mov_b32_e32 v45, v4
	v_mov_b32_e32 v46, v4
	v_mov_b32_e32 v47, v4
	v_mov_b32_e32 v52, v4
	v_mov_b32_e32 v53, v4
	v_mov_b32_e32 v54, v4
	v_mov_b32_e32 v55, v4
	v_mov_b32_e32 v60, v4
	v_mov_b32_e32 v61, v4
	v_mov_b32_e32 v62, v4
	v_mov_b32_e32 v63, v4
	v_mov_b32_e32 v64, v4
	v_mov_b32_e32 v65, v4
	v_mov_b32_e32 v66, v4
	v_mov_b32_e32 v67, v4
	v_mov_b32_e32 v68, v4
	v_mov_b32_e32 v69, v4
	v_mov_b32_e32 v70, v4
	v_mov_b32_e32 v71, v4
	v_mov_b32_e32 v72, v4
	v_mov_b32_e32 v73, v4
	v_mov_b32_e32 v74, v4
	v_mov_b32_e32 v75, v4
	v_mov_b32_e32 v80, v4
	v_mov_b32_e32 v81, v4
	v_mov_b32_e32 v82, v4
	v_mov_b32_e32 v83, v4
	v_mov_b32_e32 v88, v4
	v_mov_b32_e32 v89, v4
	v_mov_b32_e32 v90, v4
	v_mov_b32_e32 v91, v4
	v_mov_b32_e32 v100, v4
	v_mov_b32_e32 v101, v4
	v_mov_b32_e32 v102, v4
	v_mov_b32_e32 v103, v4
	v_mov_b32_e32 v104, v4
	v_mov_b32_e32 v105, v4
	v_mov_b32_e32 v106, v4
	v_mov_b32_e32 v107, v4
	v_mov_b32_e32 v108, v4
	v_mov_b32_e32 v109, v4
	v_mov_b32_e32 v110, v4
	v_mov_b32_e32 v111, v4
	v_mov_b32_e32 v112, v4
	v_mov_b32_e32 v113, v4
	v_mov_b32_e32 v114, v4
	v_mov_b32_e32 v115, v4
	v_mov_b32_e32 v76, v4
	v_mov_b32_e32 v77, v4
	v_mov_b32_e32 v78, v4
	v_mov_b32_e32 v79, v4
	v_mov_b32_e32 v84, v4
	v_mov_b32_e32 v85, v4
	v_mov_b32_e32 v86, v4
	v_mov_b32_e32 v87, v4
	v_mov_b32_e32 v92, v4
	v_mov_b32_e32 v93, v4
	v_mov_b32_e32 v94, v4
	v_mov_b32_e32 v95, v4
	v_mov_b32_e32 v96, v4
	v_mov_b32_e32 v97, v4
	v_mov_b32_e32 v98, v4
	v_mov_b32_e32 v99, v4
	v_mov_b32_e32 v116, v4
	v_mov_b32_e32 v117, v4
	v_mov_b32_e32 v118, v4
	v_mov_b32_e32 v119, v4
	v_mov_b32_e32 v120, v4
	v_mov_b32_e32 v121, v4
	v_mov_b32_e32 v122, v4
	v_mov_b32_e32 v123, v4
	v_mov_b32_e32 v124, v4
	v_mov_b32_e32 v125, v4
	v_mov_b32_e32 v126, v4
	v_mov_b32_e32 v127, v4
	v_mov_b32_e32 v128, v4
	v_mov_b32_e32 v129, v4
	v_mov_b32_e32 v130, v4
	v_mov_b32_e32 v131, v4
	ds_read_b128 v[190:193], v172
	ds_read_b128 v[194:197], v172 offset:1024
	ds_read_b128 v[198:201], v172 offset:2048
	ds_read_b128 v[202:205], v172 offset:3072
	ds_read_b128 v[206:209], v172 offset:4096
	ds_read_b128 v[218:221], v172 offset:5120
	ds_read_b128 v[224:227], v172 offset:6144
	ds_read_b128 v[228:231], v172 offset:7168
.LBB0_595:
	s_add_u32 s36, s26, 0x100
	s_addc_u32 s37, s27, 0
	s_add_i32 s40, 0, 0x10000
	s_cmp_eq_u32 s89, 40
	s_cselect_b32 s47, s9, s37
	s_cselect_b32 s46, s8, s36
	s_cselect_b32 s45, s19, s88
	s_cselect_b32 s44, s18, s69
	s_add_i32 s41, 0, 0x14000
	v_add_u32_e32 v144, s40, v170
	v_add_u32_e32 v168, s41, v170
	ds_read_b128 v[132:135], v144
	ds_read_b128 v[136:139], v144 offset:1024
	ds_read_b128 v[140:143], v144 offset:2048
	ds_read_b128 v[144:147], v144 offset:3072
	ds_read_b128 v[148:151], v168
	ds_read_b128 v[160:163], v168 offset:1024
	ds_read_b128 v[164:167], v168 offset:2048
	ds_read_b128 v[174:177], v168 offset:3072
	v_lshl_add_u64 v[168:169], s[26:27], 0, v[156:157]
	s_add_i32 m0, s49, 0xc000
	global_load_lds_dwordx4 v[168:169], off
	v_lshl_add_u64 v[168:169], s[26:27], 0, v[158:159]
	s_add_i32 m0, s49, 0xe000
	s_nop 0
	global_load_lds_dwordx4 v[168:169], off
	s_waitcnt vmcnt(8)
	s_waitcnt lgkmcnt(0)
	s_barrier
	s_setprio 1
	s_waitcnt lgkmcnt(0)
	v_mfma_f32_16x16x32_bf16 v[128:131], v[132:135], v[190:193], v[128:131]
	v_mfma_f32_16x16x32_bf16 v[124:127], v[140:143], v[190:193], v[124:127]
	v_mfma_f32_16x16x32_bf16 v[112:115], v[148:151], v[190:193], v[112:115]
	v_mfma_f32_16x16x32_bf16 v[108:111], v[164:167], v[190:193], v[108:111]
	ds_read_b128 v[190:193], v172 offset:16384
	v_mfma_f32_16x16x32_bf16 v[120:123], v[132:135], v[198:201], v[120:123]
	v_mfma_f32_16x16x32_bf16 v[116:119], v[140:143], v[198:201], v[116:119]
	v_mfma_f32_16x16x32_bf16 v[104:107], v[148:151], v[198:201], v[104:107]
	v_mfma_f32_16x16x32_bf16 v[100:103], v[164:167], v[198:201], v[100:103]
	ds_read_b128 v[198:201], v172 offset:18432
	v_mfma_f32_16x16x32_bf16 v[96:99], v[132:135], v[206:209], v[96:99]
	v_mfma_f32_16x16x32_bf16 v[92:95], v[140:143], v[206:209], v[92:95]
	v_mfma_f32_16x16x32_bf16 v[88:91], v[148:151], v[206:209], v[88:91]
	v_mfma_f32_16x16x32_bf16 v[80:83], v[164:167], v[206:209], v[80:83]
	ds_read_b128 v[206:209], v172 offset:20480
	v_mfma_f32_16x16x32_bf16 v[84:87], v[132:135], v[224:227], v[84:87]
	v_mfma_f32_16x16x32_bf16 v[76:79], v[140:143], v[224:227], v[76:79]
	v_mfma_f32_16x16x32_bf16 v[72:75], v[148:151], v[224:227], v[72:75]
	v_mfma_f32_16x16x32_bf16 v[68:71], v[164:167], v[224:227], v[68:71]
	ds_read_b128 v[224:227], v172 offset:22528
	v_mfma_f32_16x16x32_bf16 v[128:131], v[136:139], v[194:197], v[128:131]
	v_mfma_f32_16x16x32_bf16 v[124:127], v[144:147], v[194:197], v[124:127]
	v_mfma_f32_16x16x32_bf16 v[112:115], v[160:163], v[194:197], v[112:115]
	v_mfma_f32_16x16x32_bf16 v[108:111], v[174:177], v[194:197], v[108:111]
	ds_read_b128 v[194:197], v172 offset:17408
	v_mfma_f32_16x16x32_bf16 v[120:123], v[136:139], v[202:205], v[120:123]
	v_mfma_f32_16x16x32_bf16 v[116:119], v[144:147], v[202:205], v[116:119]
	v_mfma_f32_16x16x32_bf16 v[104:107], v[160:163], v[202:205], v[104:107]
	v_mfma_f32_16x16x32_bf16 v[100:103], v[174:177], v[202:205], v[100:103]
	ds_read_b128 v[202:205], v172 offset:19456
	v_mfma_f32_16x16x32_bf16 v[96:99], v[136:139], v[218:221], v[96:99]
	v_mfma_f32_16x16x32_bf16 v[92:95], v[144:147], v[218:221], v[92:95]
	v_mfma_f32_16x16x32_bf16 v[88:91], v[160:163], v[218:221], v[88:91]
	v_mfma_f32_16x16x32_bf16 v[80:83], v[174:177], v[218:221], v[80:83]
	ds_read_b128 v[218:221], v172 offset:21504
	v_mfma_f32_16x16x32_bf16 v[84:87], v[136:139], v[228:231], v[84:87]
	v_mfma_f32_16x16x32_bf16 v[76:79], v[144:147], v[228:231], v[76:79]
	v_mfma_f32_16x16x32_bf16 v[72:75], v[160:163], v[228:231], v[72:75]
	v_mfma_f32_16x16x32_bf16 v[68:71], v[174:177], v[228:231], v[68:71]
	ds_read_b128 v[228:231], v172 offset:23552
	s_setprio 0
	s_waitcnt vmcnt(2)
	s_barrier
	s_add_i32 s26, s40, s48
	v_lshl_add_u64 v[168:169], s[44:45], 0, v[180:181]
	s_mov_b32 m0, s26
	global_load_lds_dwordx4 v[168:169], off
	s_add_i32 m0, s26, 0x2000
	s_add_u32 s26, s44, 0xb0000
	v_lshl_add_u64 v[178:179], s[44:45], 0, v[0:1]
	s_addc_u32 s27, s45, 0
	s_add_i32 s40, s41, s48
	global_load_lds_dwordx4 v[178:179], off
	v_lshl_add_u64 v[182:183], s[26:27], 0, v[180:181]
	s_mov_b32 m0, s40
	v_lshl_add_u64 v[184:185], s[46:47], 0, v[152:153]
	global_load_lds_dwordx4 v[182:183], off
	v_lshl_add_u64 v[182:183], s[26:27], 0, v[0:1]
	s_add_i32 m0, s40, 0x2000
	s_nop 0
	global_load_lds_dwordx4 v[182:183], off
	v_lshl_add_u64 v[182:183], s[46:47], 0, v[154:155]
	s_mov_b32 m0, s49
	s_nop 0
	global_load_lds_dwordx4 v[182:183], off
	s_mov_b32 m0, s50
	s_nop 0
	global_load_lds_dwordx4 v[184:185], off
	s_waitcnt vmcnt(8)
	s_waitcnt lgkmcnt(0)
	s_barrier
	s_setprio 1
	s_waitcnt lgkmcnt(0)
	v_mfma_f32_16x16x32_bf16 v[64:67], v[132:135], v[190:193], v[64:67]
	v_mfma_f32_16x16x32_bf16 v[60:63], v[140:143], v[190:193], v[60:63]
	v_mfma_f32_16x16x32_bf16 v[56:59], v[148:151], v[190:193], v[56:59]
	v_mfma_f32_16x16x32_bf16 v[48:51], v[164:167], v[190:193], v[48:51]
	ds_read_b128 v[190:193], v172 offset:32768
	v_mfma_f32_16x16x32_bf16 v[52:55], v[132:135], v[198:201], v[52:55]
	v_mfma_f32_16x16x32_bf16 v[44:47], v[140:143], v[198:201], v[44:47]
	v_mfma_f32_16x16x32_bf16 v[40:43], v[148:151], v[198:201], v[40:43]
	v_mfma_f32_16x16x32_bf16 v[32:35], v[164:167], v[198:201], v[32:35]
	ds_read_b128 v[198:201], v172 offset:34816
	v_mfma_f32_16x16x32_bf16 v[36:39], v[132:135], v[206:209], v[36:39]
	v_mfma_f32_16x16x32_bf16 v[28:31], v[140:143], v[206:209], v[28:31]
	v_mfma_f32_16x16x32_bf16 v[24:27], v[148:151], v[206:209], v[24:27]
	v_mfma_f32_16x16x32_bf16 v[16:19], v[164:167], v[206:209], v[16:19]
	ds_read_b128 v[206:209], v172 offset:36864
	v_mfma_f32_16x16x32_bf16 v[20:23], v[132:135], v[224:227], v[20:23]
	v_mfma_f32_16x16x32_bf16 v[12:15], v[140:143], v[224:227], v[12:15]
	v_mfma_f32_16x16x32_bf16 v[8:11], v[148:151], v[224:227], v[8:11]
	v_mfma_f32_16x16x32_bf16 v[4:7], v[164:167], v[224:227], v[4:7]
	ds_read_b128 v[224:227], v172 offset:38912
	v_mfma_f32_16x16x32_bf16 v[64:67], v[136:139], v[194:197], v[64:67]
	v_mfma_f32_16x16x32_bf16 v[60:63], v[144:147], v[194:197], v[60:63]
	v_mfma_f32_16x16x32_bf16 v[56:59], v[160:163], v[194:197], v[56:59]
	v_mfma_f32_16x16x32_bf16 v[48:51], v[174:177], v[194:197], v[48:51]
	ds_read_b128 v[194:197], v172 offset:33792
	v_mfma_f32_16x16x32_bf16 v[52:55], v[136:139], v[202:205], v[52:55]
	v_mfma_f32_16x16x32_bf16 v[44:47], v[144:147], v[202:205], v[44:47]
	v_mfma_f32_16x16x32_bf16 v[40:43], v[160:163], v[202:205], v[40:43]
	v_mfma_f32_16x16x32_bf16 v[32:35], v[174:177], v[202:205], v[32:35]
	ds_read_b128 v[202:205], v172 offset:35840
	v_mfma_f32_16x16x32_bf16 v[36:39], v[136:139], v[218:221], v[36:39]
	v_mfma_f32_16x16x32_bf16 v[28:31], v[144:147], v[218:221], v[28:31]
	v_mfma_f32_16x16x32_bf16 v[24:27], v[160:163], v[218:221], v[24:27]
	v_mfma_f32_16x16x32_bf16 v[16:19], v[174:177], v[218:221], v[16:19]
	ds_read_b128 v[218:221], v172 offset:37888
	v_mfma_f32_16x16x32_bf16 v[20:23], v[136:139], v[228:231], v[20:23]
	v_mfma_f32_16x16x32_bf16 v[12:15], v[144:147], v[228:231], v[12:15]
	v_mfma_f32_16x16x32_bf16 v[8:11], v[160:163], v[228:231], v[8:11]
	v_mfma_f32_16x16x32_bf16 v[4:7], v[174:177], v[228:231], v[4:7]
	ds_read_b128 v[228:231], v172 offset:39936
	s_setprio 0
	s_waitcnt vmcnt(6)
	s_barrier
	s_add_i32 s40, 0, 0x18000
	s_add_i32 s41, 0, 0x1c000
	v_add_u32_e32 v144, s40, v170
	v_add_u32_e32 v173, s41, v170
	ds_read_b128 v[132:135], v144
	ds_read_b128 v[136:139], v144 offset:1024
	ds_read_b128 v[140:143], v144 offset:2048
	ds_read_b128 v[144:147], v144 offset:3072
	ds_read_b128 v[148:151], v173
	ds_read_b128 v[160:163], v173 offset:1024
	ds_read_b128 v[164:167], v173 offset:2048
	ds_read_b128 v[174:177], v173 offset:3072
	s_add_u32 s26, s46, 0xb0000
	s_addc_u32 s27, s47, 0
	s_mov_b32 m0, s51
	v_lshl_add_u64 v[210:211], s[26:27], 0, v[154:155]
	global_load_lds_dwordx4 v[210:211], off
	v_lshl_add_u64 v[210:211], s[26:27], 0, v[152:153]
	s_mov_b32 m0, s53
	s_nop 0
	global_load_lds_dwordx4 v[210:211], off
	s_waitcnt vmcnt(8)
	s_waitcnt lgkmcnt(0)
	s_barrier
	s_setprio 1
	s_waitcnt lgkmcnt(0)
	v_mfma_f32_16x16x32_bf16 v[128:131], v[132:135], v[190:193], v[128:131]
	v_mfma_f32_16x16x32_bf16 v[124:127], v[140:143], v[190:193], v[124:127]
	v_mfma_f32_16x16x32_bf16 v[112:115], v[148:151], v[190:193], v[112:115]
	v_mfma_f32_16x16x32_bf16 v[108:111], v[164:167], v[190:193], v[108:111]
	ds_read_b128 v[190:193], v172 offset:49152
	v_mfma_f32_16x16x32_bf16 v[120:123], v[132:135], v[198:201], v[120:123]
	v_mfma_f32_16x16x32_bf16 v[116:119], v[140:143], v[198:201], v[116:119]
	v_mfma_f32_16x16x32_bf16 v[104:107], v[148:151], v[198:201], v[104:107]
	v_mfma_f32_16x16x32_bf16 v[100:103], v[164:167], v[198:201], v[100:103]
	ds_read_b128 v[198:201], v172 offset:51200
	v_mfma_f32_16x16x32_bf16 v[96:99], v[132:135], v[206:209], v[96:99]
	v_mfma_f32_16x16x32_bf16 v[92:95], v[140:143], v[206:209], v[92:95]
	v_mfma_f32_16x16x32_bf16 v[88:91], v[148:151], v[206:209], v[88:91]
	v_mfma_f32_16x16x32_bf16 v[80:83], v[164:167], v[206:209], v[80:83]
	ds_read_b128 v[206:209], v172 offset:53248
	v_mfma_f32_16x16x32_bf16 v[84:87], v[132:135], v[224:227], v[84:87]
	v_mfma_f32_16x16x32_bf16 v[76:79], v[140:143], v[224:227], v[76:79]
	v_mfma_f32_16x16x32_bf16 v[72:75], v[148:151], v[224:227], v[72:75]
	v_mfma_f32_16x16x32_bf16 v[68:71], v[164:167], v[224:227], v[68:71]
	ds_read_b128 v[224:227], v172 offset:55296
	v_mfma_f32_16x16x32_bf16 v[128:131], v[136:139], v[194:197], v[128:131]
	v_mfma_f32_16x16x32_bf16 v[124:127], v[144:147], v[194:197], v[124:127]
	v_mfma_f32_16x16x32_bf16 v[112:115], v[160:163], v[194:197], v[112:115]
	v_mfma_f32_16x16x32_bf16 v[108:111], v[174:177], v[194:197], v[108:111]
	ds_read_b128 v[194:197], v172 offset:50176
	v_mfma_f32_16x16x32_bf16 v[120:123], v[136:139], v[202:205], v[120:123]
	v_mfma_f32_16x16x32_bf16 v[116:119], v[144:147], v[202:205], v[116:119]
	v_mfma_f32_16x16x32_bf16 v[104:107], v[160:163], v[202:205], v[104:107]
	v_mfma_f32_16x16x32_bf16 v[100:103], v[174:177], v[202:205], v[100:103]
	ds_read_b128 v[202:205], v172 offset:52224
	v_mfma_f32_16x16x32_bf16 v[96:99], v[136:139], v[218:221], v[96:99]
	v_mfma_f32_16x16x32_bf16 v[92:95], v[144:147], v[218:221], v[92:95]
	v_mfma_f32_16x16x32_bf16 v[88:91], v[160:163], v[218:221], v[88:91]
	v_mfma_f32_16x16x32_bf16 v[80:83], v[174:177], v[218:221], v[80:83]
	ds_read_b128 v[218:221], v172 offset:54272
	v_mfma_f32_16x16x32_bf16 v[84:87], v[136:139], v[228:231], v[84:87]
	v_mfma_f32_16x16x32_bf16 v[76:79], v[144:147], v[228:231], v[76:79]
	v_mfma_f32_16x16x32_bf16 v[72:75], v[160:163], v[228:231], v[72:75]
	v_mfma_f32_16x16x32_bf16 v[68:71], v[174:177], v[228:231], v[68:71]
	ds_read_b128 v[228:231], v172 offset:56320
	s_setprio 0
	s_waitcnt vmcnt(2)
	s_barrier
	s_add_i32 s26, s40, s48
	v_lshl_add_u64 v[168:169], v[168:169], 0, s[94:95]
	s_mov_b32 m0, s26
	global_load_lds_dwordx4 v[168:169], off
	s_add_i32 m0, s26, 0x2000
	s_add_u32 s26, s44, 0xb0080
	v_lshl_add_u64 v[168:169], v[178:179], 0, s[94:95]
	s_addc_u32 s27, s45, 0
	s_add_i32 s40, s41, s48
	global_load_lds_dwordx4 v[168:169], off
	v_lshl_add_u64 v[168:169], s[26:27], 0, v[180:181]
	s_mov_b32 m0, s40
	s_nop 0
	global_load_lds_dwordx4 v[168:169], off
	v_lshl_add_u64 v[168:169], s[26:27], 0, v[0:1]
	s_add_i32 m0, s40, 0x2000
	s_nop 0
	global_load_lds_dwordx4 v[168:169], off
	v_lshl_add_u64 v[168:169], v[182:183], 0, s[94:95]
	s_mov_b32 m0, s54
	s_nop 0
	global_load_lds_dwordx4 v[168:169], off
	v_lshl_add_u64 v[168:169], v[184:185], 0, s[94:95]
	s_mov_b32 m0, s55
	s_nop 0
	global_load_lds_dwordx4 v[168:169], off
	s_waitcnt vmcnt(8)
	s_waitcnt lgkmcnt(0)
	s_barrier
	s_setprio 1
	s_waitcnt lgkmcnt(0)
	v_mfma_f32_16x16x32_bf16 v[64:67], v[132:135], v[190:193], v[64:67]
	v_mfma_f32_16x16x32_bf16 v[60:63], v[140:143], v[190:193], v[60:63]
	v_mfma_f32_16x16x32_bf16 v[56:59], v[148:151], v[190:193], v[56:59]
	v_mfma_f32_16x16x32_bf16 v[48:51], v[164:167], v[190:193], v[48:51]
	ds_read_b128 v[190:193], v172
	v_mfma_f32_16x16x32_bf16 v[52:55], v[132:135], v[198:201], v[52:55]
	v_mfma_f32_16x16x32_bf16 v[44:47], v[140:143], v[198:201], v[44:47]
	v_mfma_f32_16x16x32_bf16 v[40:43], v[148:151], v[198:201], v[40:43]
	v_mfma_f32_16x16x32_bf16 v[32:35], v[164:167], v[198:201], v[32:35]
	ds_read_b128 v[198:201], v172 offset:2048
	v_mfma_f32_16x16x32_bf16 v[36:39], v[132:135], v[206:209], v[36:39]
	v_mfma_f32_16x16x32_bf16 v[28:31], v[140:143], v[206:209], v[28:31]
	v_mfma_f32_16x16x32_bf16 v[24:27], v[148:151], v[206:209], v[24:27]
	v_mfma_f32_16x16x32_bf16 v[16:19], v[164:167], v[206:209], v[16:19]
	ds_read_b128 v[206:209], v172 offset:4096
	v_mfma_f32_16x16x32_bf16 v[20:23], v[132:135], v[224:227], v[20:23]
	v_mfma_f32_16x16x32_bf16 v[12:15], v[140:143], v[224:227], v[12:15]
	v_mfma_f32_16x16x32_bf16 v[8:11], v[148:151], v[224:227], v[8:11]
	v_mfma_f32_16x16x32_bf16 v[4:7], v[164:167], v[224:227], v[4:7]
	ds_read_b128 v[224:227], v172 offset:6144
	v_mfma_f32_16x16x32_bf16 v[64:67], v[136:139], v[194:197], v[64:67]
	v_mfma_f32_16x16x32_bf16 v[60:63], v[144:147], v[194:197], v[60:63]
	v_mfma_f32_16x16x32_bf16 v[56:59], v[160:163], v[194:197], v[56:59]
	v_mfma_f32_16x16x32_bf16 v[48:51], v[174:177], v[194:197], v[48:51]
	ds_read_b128 v[194:197], v172 offset:1024
	v_mfma_f32_16x16x32_bf16 v[52:55], v[136:139], v[202:205], v[52:55]
	v_mfma_f32_16x16x32_bf16 v[44:47], v[144:147], v[202:205], v[44:47]
	v_mfma_f32_16x16x32_bf16 v[40:43], v[160:163], v[202:205], v[40:43]
	v_mfma_f32_16x16x32_bf16 v[32:35], v[174:177], v[202:205], v[32:35]
	ds_read_b128 v[202:205], v172 offset:3072
	v_mfma_f32_16x16x32_bf16 v[36:39], v[136:139], v[218:221], v[36:39]
	v_mfma_f32_16x16x32_bf16 v[28:31], v[144:147], v[218:221], v[28:31]
	v_mfma_f32_16x16x32_bf16 v[24:27], v[160:163], v[218:221], v[24:27]
	v_mfma_f32_16x16x32_bf16 v[16:19], v[174:177], v[218:221], v[16:19]
	ds_read_b128 v[218:221], v172 offset:5120
	v_mfma_f32_16x16x32_bf16 v[20:23], v[136:139], v[228:231], v[20:23]
	v_mfma_f32_16x16x32_bf16 v[12:15], v[144:147], v[228:231], v[12:15]
	v_mfma_f32_16x16x32_bf16 v[8:11], v[160:163], v[228:231], v[8:11]
	v_mfma_f32_16x16x32_bf16 v[4:7], v[174:177], v[228:231], v[4:7]
	ds_read_b128 v[228:231], v172 offset:7168
	s_setprio 0
	s_waitcnt vmcnt(6)
	s_barrier
	s_add_i32 s89, s89, 2
	s_add_u32 s69, s69, 0x100
	s_addc_u32 s88, s88, 0
	s_cmp_gt_u32 s89, 41
	s_mov_b64 s[26:27], s[36:37]
	s_cbranch_scc0 .LBB0_595
	s_waitcnt lgkmcnt(0)
	s_and_b64 vcc, exec, s[16:17]
	s_cbranch_vccz .LBB0_598
	s_barrier

.LBB0_623:
	s_add_u32 s89, s46, 0x100
	v_mov_b32_e32 v4, 0
	s_addc_u32 s90, s47, 0
	s_mov_b32 s97, -2
	s_waitcnt lgkmcnt(0)
	v_mov_b32_e32 v5, v4
	v_mov_b32_e32 v6, v4
	v_mov_b32_e32 v7, v4
	v_mov_b32_e32 v8, v4
	v_mov_b32_e32 v9, v4
	v_mov_b32_e32 v10, v4
	v_mov_b32_e32 v11, v4
	v_mov_b32_e32 v20, v4
	v_mov_b32_e32 v21, v4
	v_mov_b32_e32 v22, v4
	v_mov_b32_e32 v23, v4
	v_mov_b32_e32 v24, v4
	v_mov_b32_e32 v25, v4
	v_mov_b32_e32 v26, v4
	v_mov_b32_e32 v27, v4
	v_mov_b32_e32 v36, v4
	v_mov_b32_e32 v37, v4
	v_mov_b32_e32 v38, v4
	v_mov_b32_e32 v39, v4
	v_mov_b32_e32 v40, v4
	v_mov_b32_e32 v41, v4
	v_mov_b32_e32 v42, v4
	v_mov_b32_e32 v43, v4
	v_mov_b32_e32 v52, v4
	v_mov_b32_e32 v53, v4
	v_mov_b32_e32 v54, v4
	v_mov_b32_e32 v55, v4
	v_mov_b32_e32 v56, v4
	v_mov_b32_e32 v57, v4
	v_mov_b32_e32 v58, v4
	v_mov_b32_e32 v59, v4
	v_mov_b32_e32 v12, v4
	v_mov_b32_e32 v13, v4
	v_mov_b32_e32 v14, v4
	v_mov_b32_e32 v15, v4
	v_mov_b32_e32 v16, v4
	v_mov_b32_e32 v17, v4
	v_mov_b32_e32 v18, v4
	v_mov_b32_e32 v19, v4
	v_mov_b32_e32 v28, v4
	v_mov_b32_e32 v29, v4
	v_mov_b32_e32 v30, v4
	v_mov_b32_e32 v31, v4
	v_mov_b32_e32 v32, v4
	v_mov_b32_e32 v33, v4
	v_mov_b32_e32 v34, v4
	v_mov_b32_e32 v35, v4
	v_mov_b32_e32 v44, v4
	v_mov_b32_e32 v45, v4
	v_mov_b32_e32 v46, v4
	v_mov_b32_e32 v47, v4
	v_mov_b32_e32 v48, v4
	v_mov_b32_e32 v49, v4
	v_mov_b32_e32 v50, v4
	v_mov_b32_e32 v51, v4
	v_mov_b32_e32 v60, v4
	v_mov_b32_e32 v61, v4
	v_mov_b32_e32 v62, v4
	v_mov_b32_e32 v63, v4
	v_mov_b32_e32 v64, v4
	v_mov_b32_e32 v65, v4
	v_mov_b32_e32 v66, v4
	v_mov_b32_e32 v67, v4
	v_mov_b32_e32 v68, v4
	v_mov_b32_e32 v69, v4
	v_mov_b32_e32 v70, v4
	v_mov_b32_e32 v71, v4
	v_mov_b32_e32 v72, v4
	v_mov_b32_e32 v73, v4
	v_mov_b32_e32 v74, v4
	v_mov_b32_e32 v75, v4
	v_mov_b32_e32 v84, v4
	v_mov_b32_e32 v85, v4
	v_mov_b32_e32 v86, v4
	v_mov_b32_e32 v87, v4
	v_mov_b32_e32 v88, v4
	v_mov_b32_e32 v89, v4
	v_mov_b32_e32 v90, v4
	v_mov_b32_e32 v91, v4
	v_mov_b32_e32 v100, v4
	v_mov_b32_e32 v101, v4
	v_mov_b32_e32 v102, v4
	v_mov_b32_e32 v103, v4
	v_mov_b32_e32 v104, v4
	v_mov_b32_e32 v105, v4
	v_mov_b32_e32 v106, v4
	v_mov_b32_e32 v107, v4
	v_mov_b32_e32 v116, v4
	v_mov_b32_e32 v117, v4
	v_mov_b32_e32 v118, v4
	v_mov_b32_e32 v119, v4
	v_mov_b32_e32 v120, v4
	v_mov_b32_e32 v121, v4
	v_mov_b32_e32 v122, v4
	v_mov_b32_e32 v123, v4
	v_mov_b32_e32 v76, v4
	v_mov_b32_e32 v77, v4
	v_mov_b32_e32 v78, v4
	v_mov_b32_e32 v79, v4
	v_mov_b32_e32 v80, v4
	v_mov_b32_e32 v81, v4
	v_mov_b32_e32 v82, v4
	v_mov_b32_e32 v83, v4
	v_mov_b32_e32 v92, v4
	v_mov_b32_e32 v93, v4
	v_mov_b32_e32 v94, v4
	v_mov_b32_e32 v95, v4
	v_mov_b32_e32 v96, v4
	v_mov_b32_e32 v97, v4
	v_mov_b32_e32 v98, v4
	v_mov_b32_e32 v99, v4
	v_mov_b32_e32 v108, v4
	v_mov_b32_e32 v109, v4
	v_mov_b32_e32 v110, v4
	v_mov_b32_e32 v111, v4
	v_mov_b32_e32 v112, v4
	v_mov_b32_e32 v113, v4
	v_mov_b32_e32 v114, v4
	v_mov_b32_e32 v115, v4
	v_mov_b32_e32 v124, v4
	v_mov_b32_e32 v125, v4
	v_mov_b32_e32 v126, v4
	v_mov_b32_e32 v127, v4
	v_mov_b32_e32 v128, v4
	v_mov_b32_e32 v129, v4
	v_mov_b32_e32 v130, v4
	v_mov_b32_e32 v131, v4
	ds_read_b128 v[174:177], v194
	ds_read_b128 v[196:199], v194 offset:1024
	ds_read_b128 v[200:203], v194 offset:2048
	ds_read_b128 v[204:207], v194 offset:3072
	ds_read_b128 v[208:211], v194 offset:4096
	ds_read_b128 v[218:221], v194 offset:5120
	ds_read_b128 v[224:227], v194 offset:6144
	ds_read_b128 v[228:231], v194 offset:7168
.LBB0_624:
	s_add_u32 s46, s44, 0x100
	s_addc_u32 s47, s45, 0
	s_add_i32 s40, 0, 0x10000
	s_cmp_eq_u32 s97, 40
	s_cselect_b32 s51, s13, s47
	s_cselect_b32 s50, s12, s46
	s_cselect_b32 s49, s37, s90
	s_cselect_b32 s48, s36, s89
	s_add_i32 s70, 0, 0x14000
	v_add_u32_e32 v144, s40, v187
	v_add_u32_e32 v170, s70, v187
	ds_read_b128 v[132:135], v144
	ds_read_b128 v[136:139], v144 offset:1024
	ds_read_b128 v[140:143], v144 offset:2048
	ds_read_b128 v[144:147], v144 offset:3072
	ds_read_b128 v[148:151], v170
	ds_read_b128 v[152:155], v170 offset:1024
	ds_read_b128 v[156:159], v170 offset:2048
	ds_read_b128 v[170:173], v170 offset:3072
	v_lshl_add_u64 v[178:179], s[44:45], 0, v[166:167]
	s_add_i32 m0, s54, 0xc000
	global_load_lds_dwordx4 v[178:179], off
	v_lshl_add_u64 v[178:179], s[44:45], 0, v[168:169]
	s_add_i32 m0, s54, 0xe000
	s_nop 0
	global_load_lds_dwordx4 v[178:179], off
	s_waitcnt vmcnt(8)
	s_waitcnt lgkmcnt(0)
	s_barrier
	s_setprio 1
	s_waitcnt lgkmcnt(0)
	v_mfma_f32_16x16x32_bf16 v[128:131], v[132:135], v[174:177], v[128:131]
	v_mfma_f32_16x16x32_bf16 v[124:127], v[140:143], v[174:177], v[124:127]
	v_mfma_f32_16x16x32_bf16 v[120:123], v[148:151], v[174:177], v[120:123]
	v_mfma_f32_16x16x32_bf16 v[116:119], v[156:159], v[174:177], v[116:119]
	ds_read_b128 v[174:177], v194 offset:16384
	v_mfma_f32_16x16x32_bf16 v[112:115], v[132:135], v[200:203], v[112:115]
	v_mfma_f32_16x16x32_bf16 v[108:111], v[140:143], v[200:203], v[108:111]
	v_mfma_f32_16x16x32_bf16 v[104:107], v[148:151], v[200:203], v[104:107]
	v_mfma_f32_16x16x32_bf16 v[100:103], v[156:159], v[200:203], v[100:103]
	ds_read_b128 v[200:203], v194 offset:18432
	v_mfma_f32_16x16x32_bf16 v[96:99], v[132:135], v[208:211], v[96:99]
	v_mfma_f32_16x16x32_bf16 v[92:95], v[140:143], v[208:211], v[92:95]
	v_mfma_f32_16x16x32_bf16 v[88:91], v[148:151], v[208:211], v[88:91]
	v_mfma_f32_16x16x32_bf16 v[84:87], v[156:159], v[208:211], v[84:87]
	ds_read_b128 v[208:211], v194 offset:20480
	v_mfma_f32_16x16x32_bf16 v[80:83], v[132:135], v[224:227], v[80:83]
	v_mfma_f32_16x16x32_bf16 v[76:79], v[140:143], v[224:227], v[76:79]
	v_mfma_f32_16x16x32_bf16 v[72:75], v[148:151], v[224:227], v[72:75]
	v_mfma_f32_16x16x32_bf16 v[68:71], v[156:159], v[224:227], v[68:71]
	ds_read_b128 v[224:227], v194 offset:22528
	v_mfma_f32_16x16x32_bf16 v[128:131], v[136:139], v[196:199], v[128:131]
	v_mfma_f32_16x16x32_bf16 v[124:127], v[144:147], v[196:199], v[124:127]
	v_mfma_f32_16x16x32_bf16 v[120:123], v[152:155], v[196:199], v[120:123]
	v_mfma_f32_16x16x32_bf16 v[116:119], v[170:173], v[196:199], v[116:119]
	ds_read_b128 v[196:199], v194 offset:17408
	v_mfma_f32_16x16x32_bf16 v[112:115], v[136:139], v[204:207], v[112:115]
	v_mfma_f32_16x16x32_bf16 v[108:111], v[144:147], v[204:207], v[108:111]
	v_mfma_f32_16x16x32_bf16 v[104:107], v[152:155], v[204:207], v[104:107]
	v_mfma_f32_16x16x32_bf16 v[100:103], v[170:173], v[204:207], v[100:103]
	ds_read_b128 v[204:207], v194 offset:19456
	v_mfma_f32_16x16x32_bf16 v[96:99], v[136:139], v[218:221], v[96:99]
	v_mfma_f32_16x16x32_bf16 v[92:95], v[144:147], v[218:221], v[92:95]
	v_mfma_f32_16x16x32_bf16 v[88:91], v[152:155], v[218:221], v[88:91]
	v_mfma_f32_16x16x32_bf16 v[84:87], v[170:173], v[218:221], v[84:87]
	ds_read_b128 v[218:221], v194 offset:21504
	v_mfma_f32_16x16x32_bf16 v[80:83], v[136:139], v[228:231], v[80:83]
	v_mfma_f32_16x16x32_bf16 v[76:79], v[144:147], v[228:231], v[76:79]
	v_mfma_f32_16x16x32_bf16 v[72:75], v[152:155], v[228:231], v[72:75]
	v_mfma_f32_16x16x32_bf16 v[68:71], v[170:173], v[228:231], v[68:71]
	ds_read_b128 v[228:231], v194 offset:23552
	s_setprio 0
	s_waitcnt vmcnt(2)
	s_barrier
	s_add_i32 s40, s40, s53
	v_lshl_add_u64 v[178:179], s[48:49], 0, v[162:163]
	s_mov_b32 m0, s40
	global_load_lds_dwordx4 v[178:179], off
	s_add_i32 m0, s40, 0x2000
	s_add_u32 s40, s48, 0xb0000
	v_lshl_add_u64 v[182:183], s[48:49], 0, v[0:1]
	s_addc_u32 s41, s49, 0
	s_add_i32 s44, s70, s53
	global_load_lds_dwordx4 v[182:183], off
	v_lshl_add_u64 v[184:185], s[40:41], 0, v[162:163]
	s_mov_b32 m0, s44
	v_lshl_add_u64 v[190:191], s[50:51], 0, v[160:161]
	global_load_lds_dwordx4 v[184:185], off
	v_lshl_add_u64 v[184:185], s[40:41], 0, v[0:1]
	s_add_i32 m0, s44, 0x2000
	s_nop 0
	global_load_lds_dwordx4 v[184:185], off
	v_lshl_add_u64 v[184:185], s[50:51], 0, v[164:165]
	s_mov_b32 m0, s54
	s_nop 0
	global_load_lds_dwordx4 v[184:185], off
	s_mov_b32 m0, s55
	s_nop 0
	global_load_lds_dwordx4 v[190:191], off
	s_waitcnt vmcnt(8)
	s_waitcnt lgkmcnt(0)
	s_barrier
	s_setprio 1
	s_waitcnt lgkmcnt(0)
	v_mfma_f32_16x16x32_bf16 v[64:67], v[132:135], v[174:177], v[64:67]
	v_mfma_f32_16x16x32_bf16 v[60:63], v[140:143], v[174:177], v[60:63]
	v_mfma_f32_16x16x32_bf16 v[56:59], v[148:151], v[174:177], v[56:59]
	v_mfma_f32_16x16x32_bf16 v[52:55], v[156:159], v[174:177], v[52:55]
	ds_read_b128 v[174:177], v194 offset:32768
	v_mfma_f32_16x16x32_bf16 v[48:51], v[132:135], v[200:203], v[48:51]
	v_mfma_f32_16x16x32_bf16 v[44:47], v[140:143], v[200:203], v[44:47]
	v_mfma_f32_16x16x32_bf16 v[40:43], v[148:151], v[200:203], v[40:43]
	v_mfma_f32_16x16x32_bf16 v[36:39], v[156:159], v[200:203], v[36:39]
	ds_read_b128 v[200:203], v194 offset:34816
	v_mfma_f32_16x16x32_bf16 v[32:35], v[132:135], v[208:211], v[32:35]
	v_mfma_f32_16x16x32_bf16 v[28:31], v[140:143], v[208:211], v[28:31]
	v_mfma_f32_16x16x32_bf16 v[24:27], v[148:151], v[208:211], v[24:27]
	v_mfma_f32_16x16x32_bf16 v[20:23], v[156:159], v[208:211], v[20:23]
	ds_read_b128 v[208:211], v194 offset:36864
	v_mfma_f32_16x16x32_bf16 v[16:19], v[132:135], v[224:227], v[16:19]
	v_mfma_f32_16x16x32_bf16 v[12:15], v[140:143], v[224:227], v[12:15]
	v_mfma_f32_16x16x32_bf16 v[8:11], v[148:151], v[224:227], v[8:11]
	v_mfma_f32_16x16x32_bf16 v[4:7], v[156:159], v[224:227], v[4:7]
	ds_read_b128 v[224:227], v194 offset:38912
	v_mfma_f32_16x16x32_bf16 v[64:67], v[136:139], v[196:199], v[64:67]
	v_mfma_f32_16x16x32_bf16 v[60:63], v[144:147], v[196:199], v[60:63]
	v_mfma_f32_16x16x32_bf16 v[56:59], v[152:155], v[196:199], v[56:59]
	v_mfma_f32_16x16x32_bf16 v[52:55], v[170:173], v[196:199], v[52:55]
	ds_read_b128 v[196:199], v194 offset:33792
	v_mfma_f32_16x16x32_bf16 v[48:51], v[136:139], v[204:207], v[48:51]
	v_mfma_f32_16x16x32_bf16 v[44:47], v[144:147], v[204:207], v[44:47]
	v_mfma_f32_16x16x32_bf16 v[40:43], v[152:155], v[204:207], v[40:43]
	v_mfma_f32_16x16x32_bf16 v[36:39], v[170:173], v[204:207], v[36:39]
	ds_read_b128 v[204:207], v194 offset:35840
	v_mfma_f32_16x16x32_bf16 v[32:35], v[136:139], v[218:221], v[32:35]
	v_mfma_f32_16x16x32_bf16 v[28:31], v[144:147], v[218:221], v[28:31]
	v_mfma_f32_16x16x32_bf16 v[24:27], v[152:155], v[218:221], v[24:27]
	v_mfma_f32_16x16x32_bf16 v[20:23], v[170:173], v[218:221], v[20:23]
	ds_read_b128 v[218:221], v194 offset:37888
	v_mfma_f32_16x16x32_bf16 v[16:19], v[136:139], v[228:231], v[16:19]
	v_mfma_f32_16x16x32_bf16 v[12:15], v[144:147], v[228:231], v[12:15]
	v_mfma_f32_16x16x32_bf16 v[8:11], v[152:155], v[228:231], v[8:11]
	v_mfma_f32_16x16x32_bf16 v[4:7], v[170:173], v[228:231], v[4:7]
	ds_read_b128 v[228:231], v194 offset:39936
	s_setprio 0
	s_waitcnt vmcnt(6)
	s_barrier
	s_add_i32 s44, 0, 0x18000
	s_add_i32 s45, 0, 0x1c000
	v_add_u32_e32 v144, s44, v187
	v_add_u32_e32 v170, s45, v187
	ds_read_b128 v[132:135], v144
	ds_read_b128 v[136:139], v144 offset:1024
	ds_read_b128 v[140:143], v144 offset:2048
	ds_read_b128 v[144:147], v144 offset:3072
	ds_read_b128 v[148:151], v170
	ds_read_b128 v[152:155], v170 offset:1024
	ds_read_b128 v[156:159], v170 offset:2048
	ds_read_b128 v[170:173], v170 offset:3072
	s_add_u32 s40, s50, 0xb0000
	s_addc_u32 s41, s51, 0
	s_mov_b32 m0, s58
	v_lshl_add_u64 v[232:233], s[40:41], 0, v[164:165]
	global_load_lds_dwordx4 v[232:233], off
	v_lshl_add_u64 v[232:233], s[40:41], 0, v[160:161]
	s_mov_b32 m0, s59
	s_nop 0
	global_load_lds_dwordx4 v[232:233], off
	s_waitcnt vmcnt(8)
	s_waitcnt lgkmcnt(0)
	s_barrier
	s_setprio 1
	s_waitcnt lgkmcnt(0)
	v_mfma_f32_16x16x32_bf16 v[128:131], v[132:135], v[174:177], v[128:131]
	v_mfma_f32_16x16x32_bf16 v[124:127], v[140:143], v[174:177], v[124:127]
	v_mfma_f32_16x16x32_bf16 v[120:123], v[148:151], v[174:177], v[120:123]
	v_mfma_f32_16x16x32_bf16 v[116:119], v[156:159], v[174:177], v[116:119]
	ds_read_b128 v[174:177], v194 offset:49152
	v_mfma_f32_16x16x32_bf16 v[112:115], v[132:135], v[200:203], v[112:115]
	v_mfma_f32_16x16x32_bf16 v[108:111], v[140:143], v[200:203], v[108:111]
	v_mfma_f32_16x16x32_bf16 v[104:107], v[148:151], v[200:203], v[104:107]
	v_mfma_f32_16x16x32_bf16 v[100:103], v[156:159], v[200:203], v[100:103]
	ds_read_b128 v[200:203], v194 offset:51200
	v_mfma_f32_16x16x32_bf16 v[96:99], v[132:135], v[208:211], v[96:99]
	v_mfma_f32_16x16x32_bf16 v[92:95], v[140:143], v[208:211], v[92:95]
	v_mfma_f32_16x16x32_bf16 v[88:91], v[148:151], v[208:211], v[88:91]
	v_mfma_f32_16x16x32_bf16 v[84:87], v[156:159], v[208:211], v[84:87]
	ds_read_b128 v[208:211], v194 offset:53248
	v_mfma_f32_16x16x32_bf16 v[80:83], v[132:135], v[224:227], v[80:83]
	v_mfma_f32_16x16x32_bf16 v[76:79], v[140:143], v[224:227], v[76:79]
	v_mfma_f32_16x16x32_bf16 v[72:75], v[148:151], v[224:227], v[72:75]
	v_mfma_f32_16x16x32_bf16 v[68:71], v[156:159], v[224:227], v[68:71]
	ds_read_b128 v[224:227], v194 offset:55296
	v_mfma_f32_16x16x32_bf16 v[128:131], v[136:139], v[196:199], v[128:131]
	v_mfma_f32_16x16x32_bf16 v[124:127], v[144:147], v[196:199], v[124:127]
	v_mfma_f32_16x16x32_bf16 v[120:123], v[152:155], v[196:199], v[120:123]
	v_mfma_f32_16x16x32_bf16 v[116:119], v[170:173], v[196:199], v[116:119]
	ds_read_b128 v[196:199], v194 offset:50176
	v_mfma_f32_16x16x32_bf16 v[112:115], v[136:139], v[204:207], v[112:115]
	v_mfma_f32_16x16x32_bf16 v[108:111], v[144:147], v[204:207], v[108:111]
	v_mfma_f32_16x16x32_bf16 v[104:107], v[152:155], v[204:207], v[104:107]
	v_mfma_f32_16x16x32_bf16 v[100:103], v[170:173], v[204:207], v[100:103]
	ds_read_b128 v[204:207], v194 offset:52224
	v_mfma_f32_16x16x32_bf16 v[96:99], v[136:139], v[218:221], v[96:99]
	v_mfma_f32_16x16x32_bf16 v[92:95], v[144:147], v[218:221], v[92:95]
	v_mfma_f32_16x16x32_bf16 v[88:91], v[152:155], v[218:221], v[88:91]
	v_mfma_f32_16x16x32_bf16 v[84:87], v[170:173], v[218:221], v[84:87]
	ds_read_b128 v[218:221], v194 offset:54272
	v_mfma_f32_16x16x32_bf16 v[80:83], v[136:139], v[228:231], v[80:83]
	v_mfma_f32_16x16x32_bf16 v[76:79], v[144:147], v[228:231], v[76:79]
	v_mfma_f32_16x16x32_bf16 v[72:75], v[152:155], v[228:231], v[72:75]
	v_mfma_f32_16x16x32_bf16 v[68:71], v[170:173], v[228:231], v[68:71]
	ds_read_b128 v[228:231], v194 offset:56320
	s_setprio 0
	s_waitcnt vmcnt(2)
	s_barrier
	s_add_i32 s40, s44, s53
	v_lshl_add_u64 v[178:179], v[178:179], 0, s[94:95]
	s_mov_b32 m0, s40
	global_load_lds_dwordx4 v[178:179], off
	s_add_i32 m0, s40, 0x2000
	s_add_u32 s40, s48, 0xb0080
	v_lshl_add_u64 v[178:179], v[182:183], 0, s[94:95]
	s_addc_u32 s41, s49, 0
	s_add_i32 s44, s45, s53
	global_load_lds_dwordx4 v[178:179], off
	v_lshl_add_u64 v[178:179], s[40:41], 0, v[162:163]
	s_mov_b32 m0, s44
	s_nop 0
	global_load_lds_dwordx4 v[178:179], off
	v_lshl_add_u64 v[178:179], s[40:41], 0, v[0:1]
	s_add_i32 m0, s44, 0x2000
	s_nop 0
	global_load_lds_dwordx4 v[178:179], off
	v_lshl_add_u64 v[178:179], v[184:185], 0, s[94:95]
	s_mov_b32 m0, s64
	s_nop 0
	global_load_lds_dwordx4 v[178:179], off
	v_lshl_add_u64 v[178:179], v[190:191], 0, s[94:95]
	s_mov_b32 m0, s65
	s_nop 0
	global_load_lds_dwordx4 v[178:179], off
	s_waitcnt vmcnt(8)
	s_waitcnt lgkmcnt(0)
	s_barrier
	s_setprio 1
	s_waitcnt lgkmcnt(0)
	v_mfma_f32_16x16x32_bf16 v[64:67], v[132:135], v[174:177], v[64:67]
	v_mfma_f32_16x16x32_bf16 v[60:63], v[140:143], v[174:177], v[60:63]
	v_mfma_f32_16x16x32_bf16 v[56:59], v[148:151], v[174:177], v[56:59]
	v_mfma_f32_16x16x32_bf16 v[52:55], v[156:159], v[174:177], v[52:55]
	ds_read_b128 v[174:177], v194
	v_mfma_f32_16x16x32_bf16 v[48:51], v[132:135], v[200:203], v[48:51]
	v_mfma_f32_16x16x32_bf16 v[44:47], v[140:143], v[200:203], v[44:47]
	v_mfma_f32_16x16x32_bf16 v[40:43], v[148:151], v[200:203], v[40:43]
	v_mfma_f32_16x16x32_bf16 v[36:39], v[156:159], v[200:203], v[36:39]
	ds_read_b128 v[200:203], v194 offset:2048
	v_mfma_f32_16x16x32_bf16 v[32:35], v[132:135], v[208:211], v[32:35]
	v_mfma_f32_16x16x32_bf16 v[28:31], v[140:143], v[208:211], v[28:31]
	v_mfma_f32_16x16x32_bf16 v[24:27], v[148:151], v[208:211], v[24:27]
	v_mfma_f32_16x16x32_bf16 v[20:23], v[156:159], v[208:211], v[20:23]
	ds_read_b128 v[208:211], v194 offset:4096
	v_mfma_f32_16x16x32_bf16 v[16:19], v[132:135], v[224:227], v[16:19]
	v_mfma_f32_16x16x32_bf16 v[12:15], v[140:143], v[224:227], v[12:15]
	v_mfma_f32_16x16x32_bf16 v[8:11], v[148:151], v[224:227], v[8:11]
	v_mfma_f32_16x16x32_bf16 v[4:7], v[156:159], v[224:227], v[4:7]
	ds_read_b128 v[224:227], v194 offset:6144
	v_mfma_f32_16x16x32_bf16 v[64:67], v[136:139], v[196:199], v[64:67]
	v_mfma_f32_16x16x32_bf16 v[60:63], v[144:147], v[196:199], v[60:63]
	v_mfma_f32_16x16x32_bf16 v[56:59], v[152:155], v[196:199], v[56:59]
	v_mfma_f32_16x16x32_bf16 v[52:55], v[170:173], v[196:199], v[52:55]
	ds_read_b128 v[196:199], v194 offset:1024
	v_mfma_f32_16x16x32_bf16 v[48:51], v[136:139], v[204:207], v[48:51]
	v_mfma_f32_16x16x32_bf16 v[44:47], v[144:147], v[204:207], v[44:47]
	v_mfma_f32_16x16x32_bf16 v[40:43], v[152:155], v[204:207], v[40:43]
	v_mfma_f32_16x16x32_bf16 v[36:39], v[170:173], v[204:207], v[36:39]
	ds_read_b128 v[204:207], v194 offset:3072
	v_mfma_f32_16x16x32_bf16 v[32:35], v[136:139], v[218:221], v[32:35]
	v_mfma_f32_16x16x32_bf16 v[28:31], v[144:147], v[218:221], v[28:31]
	v_mfma_f32_16x16x32_bf16 v[24:27], v[152:155], v[218:221], v[24:27]
	v_mfma_f32_16x16x32_bf16 v[20:23], v[170:173], v[218:221], v[20:23]
	ds_read_b128 v[218:221], v194 offset:5120
	v_mfma_f32_16x16x32_bf16 v[16:19], v[136:139], v[228:231], v[16:19]
	v_mfma_f32_16x16x32_bf16 v[12:15], v[144:147], v[228:231], v[12:15]
	v_mfma_f32_16x16x32_bf16 v[8:11], v[152:155], v[228:231], v[8:11]
	v_mfma_f32_16x16x32_bf16 v[4:7], v[170:173], v[228:231], v[4:7]
	ds_read_b128 v[228:231], v194 offset:7168
	s_setprio 0
	s_waitcnt vmcnt(6)
	s_barrier
	s_add_i32 s97, s97, 2
	s_add_u32 s89, s89, 0x100
	s_addc_u32 s90, s90, 0
	s_cmp_gt_u32 s97, 41
	s_mov_b64 s[44:45], s[46:47]
	s_cbranch_scc0 .LBB0_624
	s_waitcnt lgkmcnt(0)
	s_and_b64 vcc, exec, s[18:19]
	s_cbranch_vccz .LBB0_627
	s_barrier

.LBB0_667:
	s_add_u32 s65, s36, 0x100
	v_mov_b32_e32 v4, 0
	s_addc_u32 s68, s37, 0
	s_mov_b32 s69, -2
	s_waitcnt lgkmcnt(0)
	v_mov_b32_e32 v5, v4
	v_mov_b32_e32 v6, v4
	v_mov_b32_e32 v7, v4
	v_mov_b32_e32 v8, v4
	v_mov_b32_e32 v9, v4
	v_mov_b32_e32 v10, v4
	v_mov_b32_e32 v11, v4
	v_mov_b32_e32 v20, v4
	v_mov_b32_e32 v21, v4
	v_mov_b32_e32 v22, v4
	v_mov_b32_e32 v23, v4
	v_mov_b32_e32 v24, v4
	v_mov_b32_e32 v25, v4
	v_mov_b32_e32 v26, v4
	v_mov_b32_e32 v27, v4
	v_mov_b32_e32 v36, v4
	v_mov_b32_e32 v37, v4
	v_mov_b32_e32 v38, v4
	v_mov_b32_e32 v39, v4
	v_mov_b32_e32 v40, v4
	v_mov_b32_e32 v41, v4
	v_mov_b32_e32 v42, v4
	v_mov_b32_e32 v43, v4
	v_mov_b32_e32 v52, v4
	v_mov_b32_e32 v53, v4
	v_mov_b32_e32 v54, v4
	v_mov_b32_e32 v55, v4
	v_mov_b32_e32 v56, v4
	v_mov_b32_e32 v57, v4
	v_mov_b32_e32 v58, v4
	v_mov_b32_e32 v59, v4
	v_mov_b32_e32 v12, v4
	v_mov_b32_e32 v13, v4
	v_mov_b32_e32 v14, v4
	v_mov_b32_e32 v15, v4
	v_mov_b32_e32 v16, v4
	v_mov_b32_e32 v17, v4
	v_mov_b32_e32 v18, v4
	v_mov_b32_e32 v19, v4
	v_mov_b32_e32 v28, v4
	v_mov_b32_e32 v29, v4
	v_mov_b32_e32 v30, v4
	v_mov_b32_e32 v31, v4
	v_mov_b32_e32 v32, v4
	v_mov_b32_e32 v33, v4
	v_mov_b32_e32 v34, v4
	v_mov_b32_e32 v35, v4
	v_mov_b32_e32 v44, v4
	v_mov_b32_e32 v45, v4
	v_mov_b32_e32 v46, v4
	v_mov_b32_e32 v47, v4
	v_mov_b32_e32 v48, v4
	v_mov_b32_e32 v49, v4
	v_mov_b32_e32 v50, v4
	v_mov_b32_e32 v51, v4
	v_mov_b32_e32 v60, v4
	v_mov_b32_e32 v61, v4
	v_mov_b32_e32 v62, v4
	v_mov_b32_e32 v63, v4
	v_mov_b32_e32 v64, v4
	v_mov_b32_e32 v65, v4
	v_mov_b32_e32 v66, v4
	v_mov_b32_e32 v67, v4
	v_mov_b32_e32 v68, v4
	v_mov_b32_e32 v69, v4
	v_mov_b32_e32 v70, v4
	v_mov_b32_e32 v71, v4
	v_mov_b32_e32 v72, v4
	v_mov_b32_e32 v73, v4
	v_mov_b32_e32 v74, v4
	v_mov_b32_e32 v75, v4
	v_mov_b32_e32 v84, v4
	v_mov_b32_e32 v85, v4
	v_mov_b32_e32 v86, v4
	v_mov_b32_e32 v87, v4
	v_mov_b32_e32 v88, v4
	v_mov_b32_e32 v89, v4
	v_mov_b32_e32 v90, v4
	v_mov_b32_e32 v91, v4
	v_mov_b32_e32 v100, v4
	v_mov_b32_e32 v101, v4
	v_mov_b32_e32 v102, v4
	v_mov_b32_e32 v103, v4
	v_mov_b32_e32 v104, v4
	v_mov_b32_e32 v105, v4
	v_mov_b32_e32 v106, v4
	v_mov_b32_e32 v107, v4
	v_mov_b32_e32 v116, v4
	v_mov_b32_e32 v117, v4
	v_mov_b32_e32 v118, v4
	v_mov_b32_e32 v119, v4
	v_mov_b32_e32 v120, v4
	v_mov_b32_e32 v121, v4
	v_mov_b32_e32 v122, v4
	v_mov_b32_e32 v123, v4
	v_mov_b32_e32 v76, v4
	v_mov_b32_e32 v77, v4
	v_mov_b32_e32 v78, v4
	v_mov_b32_e32 v79, v4
	v_mov_b32_e32 v80, v4
	v_mov_b32_e32 v81, v4
	v_mov_b32_e32 v82, v4
	v_mov_b32_e32 v83, v4
	v_mov_b32_e32 v92, v4
	v_mov_b32_e32 v93, v4
	v_mov_b32_e32 v94, v4
	v_mov_b32_e32 v95, v4
	v_mov_b32_e32 v96, v4
	v_mov_b32_e32 v97, v4
	v_mov_b32_e32 v98, v4
	v_mov_b32_e32 v99, v4
	v_mov_b32_e32 v108, v4
	v_mov_b32_e32 v109, v4
	v_mov_b32_e32 v110, v4
	v_mov_b32_e32 v111, v4
	v_mov_b32_e32 v112, v4
	v_mov_b32_e32 v113, v4
	v_mov_b32_e32 v114, v4
	v_mov_b32_e32 v115, v4
	v_mov_b32_e32 v124, v4
	v_mov_b32_e32 v125, v4
	v_mov_b32_e32 v126, v4
	v_mov_b32_e32 v127, v4
	v_mov_b32_e32 v128, v4
	v_mov_b32_e32 v129, v4
	v_mov_b32_e32 v130, v4
	v_mov_b32_e32 v131, v4
	ds_read_b128 v[164:167], v229
	ds_read_b128 v[168:171], v229 offset:1024
	ds_read_b128 v[172:175], v229 offset:2048
	ds_read_b128 v[176:179], v229 offset:3072
	ds_read_b128 v[200:203], v229 offset:4096
	ds_read_b128 v[204:207], v229 offset:5120
	ds_read_b128 v[208:211], v229 offset:6144
	ds_read_b128 v[218:221], v229 offset:7168
.LBB0_668:
	s_add_u32 s36, s26, 0x100
	s_addc_u32 s37, s27, 0
	s_add_i32 s40, 0, 0x10000
	s_cmp_eq_u32 s69, 40
	s_cselect_b32 s47, s11, s37
	s_cselect_b32 s46, s10, s36
	s_cselect_b32 s45, s19, s68
	s_cselect_b32 s44, s18, s65
	s_add_i32 s41, 0, 0x14000
	v_add_u32_e32 v144, s40, v187
	v_add_u32_e32 v160, s41, v187
	ds_read_b128 v[132:135], v144
	ds_read_b128 v[136:139], v144 offset:1024
	ds_read_b128 v[140:143], v144 offset:2048
	ds_read_b128 v[144:147], v144 offset:3072
	ds_read_b128 v[148:151], v160
	ds_read_b128 v[152:155], v160 offset:1024
	ds_read_b128 v[156:159], v160 offset:2048
	ds_read_b128 v[160:163], v160 offset:3072
	v_lshl_add_u64 v[182:183], s[26:27], 0, v[196:197]
	s_add_i32 m0, s49, 0xc000
	global_load_lds_dwordx4 v[182:183], off
	v_lshl_add_u64 v[182:183], s[26:27], 0, v[198:199]
	s_add_i32 m0, s49, 0xe000
	s_nop 0
	global_load_lds_dwordx4 v[182:183], off
	s_waitcnt vmcnt(8)
	s_waitcnt lgkmcnt(0)
	s_barrier
	s_setprio 1
	s_waitcnt lgkmcnt(0)
	v_mfma_f32_16x16x32_bf16 v[128:131], v[132:135], v[164:167], v[128:131]
	v_mfma_f32_16x16x32_bf16 v[124:127], v[140:143], v[164:167], v[124:127]
	v_mfma_f32_16x16x32_bf16 v[120:123], v[148:151], v[164:167], v[120:123]
	v_mfma_f32_16x16x32_bf16 v[116:119], v[156:159], v[164:167], v[116:119]
	ds_read_b128 v[164:167], v229 offset:16384
	v_mfma_f32_16x16x32_bf16 v[112:115], v[132:135], v[172:175], v[112:115]
	v_mfma_f32_16x16x32_bf16 v[108:111], v[140:143], v[172:175], v[108:111]
	v_mfma_f32_16x16x32_bf16 v[104:107], v[148:151], v[172:175], v[104:107]
	v_mfma_f32_16x16x32_bf16 v[100:103], v[156:159], v[172:175], v[100:103]
	ds_read_b128 v[172:175], v229 offset:18432
	v_mfma_f32_16x16x32_bf16 v[96:99], v[132:135], v[200:203], v[96:99]
	v_mfma_f32_16x16x32_bf16 v[92:95], v[140:143], v[200:203], v[92:95]
	v_mfma_f32_16x16x32_bf16 v[88:91], v[148:151], v[200:203], v[88:91]
	v_mfma_f32_16x16x32_bf16 v[84:87], v[156:159], v[200:203], v[84:87]
	ds_read_b128 v[200:203], v229 offset:20480
	v_mfma_f32_16x16x32_bf16 v[80:83], v[132:135], v[208:211], v[80:83]
	v_mfma_f32_16x16x32_bf16 v[76:79], v[140:143], v[208:211], v[76:79]
	v_mfma_f32_16x16x32_bf16 v[72:75], v[148:151], v[208:211], v[72:75]
	v_mfma_f32_16x16x32_bf16 v[68:71], v[156:159], v[208:211], v[68:71]
	ds_read_b128 v[208:211], v229 offset:22528
	v_mfma_f32_16x16x32_bf16 v[128:131], v[136:139], v[168:171], v[128:131]
	v_mfma_f32_16x16x32_bf16 v[124:127], v[144:147], v[168:171], v[124:127]
	v_mfma_f32_16x16x32_bf16 v[120:123], v[152:155], v[168:171], v[120:123]
	v_mfma_f32_16x16x32_bf16 v[116:119], v[160:163], v[168:171], v[116:119]
	ds_read_b128 v[168:171], v229 offset:17408
	v_mfma_f32_16x16x32_bf16 v[112:115], v[136:139], v[176:179], v[112:115]
	v_mfma_f32_16x16x32_bf16 v[108:111], v[144:147], v[176:179], v[108:111]
	v_mfma_f32_16x16x32_bf16 v[104:107], v[152:155], v[176:179], v[104:107]
	v_mfma_f32_16x16x32_bf16 v[100:103], v[160:163], v[176:179], v[100:103]
	ds_read_b128 v[176:179], v229 offset:19456
	v_mfma_f32_16x16x32_bf16 v[96:99], v[136:139], v[204:207], v[96:99]
	v_mfma_f32_16x16x32_bf16 v[92:95], v[144:147], v[204:207], v[92:95]
	v_mfma_f32_16x16x32_bf16 v[88:91], v[152:155], v[204:207], v[88:91]
	v_mfma_f32_16x16x32_bf16 v[84:87], v[160:163], v[204:207], v[84:87]
	ds_read_b128 v[204:207], v229 offset:21504
	v_mfma_f32_16x16x32_bf16 v[80:83], v[136:139], v[218:221], v[80:83]
	v_mfma_f32_16x16x32_bf16 v[76:79], v[144:147], v[218:221], v[76:79]
	v_mfma_f32_16x16x32_bf16 v[72:75], v[152:155], v[218:221], v[72:75]
	v_mfma_f32_16x16x32_bf16 v[68:71], v[160:163], v[218:221], v[68:71]
	ds_read_b128 v[218:221], v229 offset:23552
	s_setprio 0
	s_waitcnt vmcnt(2)
	s_barrier
	s_add_i32 s26, s40, s48
	v_lshl_add_u64 v[182:183], s[44:45], 0, v[192:193]
	s_mov_b32 m0, s26
	global_load_lds_dwordx4 v[182:183], off
	s_add_i32 m0, s26, 0x2000
	s_add_u32 s26, s44, 0xb0000
	v_lshl_add_u64 v[184:185], s[44:45], 0, v[0:1]
	s_addc_u32 s27, s45, 0
	s_add_i32 s40, s41, s48
	global_load_lds_dwordx4 v[184:185], off
	v_lshl_add_u64 v[224:225], s[26:27], 0, v[192:193]
	s_mov_b32 m0, s40
	v_lshl_add_u64 v[230:231], s[46:47], 0, v[190:191]
	global_load_lds_dwordx4 v[224:225], off
	v_lshl_add_u64 v[224:225], s[26:27], 0, v[0:1]
	s_add_i32 m0, s40, 0x2000
	s_nop 0
	global_load_lds_dwordx4 v[224:225], off
	v_lshl_add_u64 v[224:225], s[46:47], 0, v[194:195]
	s_mov_b32 m0, s49
	s_nop 0
	global_load_lds_dwordx4 v[224:225], off
	s_mov_b32 m0, s50
	s_nop 0
	global_load_lds_dwordx4 v[230:231], off
	s_waitcnt vmcnt(8)
	s_waitcnt lgkmcnt(0)
	s_barrier
	s_setprio 1
	s_waitcnt lgkmcnt(0)
	v_mfma_f32_16x16x32_bf16 v[64:67], v[132:135], v[164:167], v[64:67]
	v_mfma_f32_16x16x32_bf16 v[60:63], v[140:143], v[164:167], v[60:63]
	v_mfma_f32_16x16x32_bf16 v[56:59], v[148:151], v[164:167], v[56:59]
	v_mfma_f32_16x16x32_bf16 v[52:55], v[156:159], v[164:167], v[52:55]
	ds_read_b128 v[164:167], v229 offset:32768
	v_mfma_f32_16x16x32_bf16 v[48:51], v[132:135], v[172:175], v[48:51]
	v_mfma_f32_16x16x32_bf16 v[44:47], v[140:143], v[172:175], v[44:47]
	v_mfma_f32_16x16x32_bf16 v[40:43], v[148:151], v[172:175], v[40:43]
	v_mfma_f32_16x16x32_bf16 v[36:39], v[156:159], v[172:175], v[36:39]
	ds_read_b128 v[172:175], v229 offset:34816
	v_mfma_f32_16x16x32_bf16 v[32:35], v[132:135], v[200:203], v[32:35]
	v_mfma_f32_16x16x32_bf16 v[28:31], v[140:143], v[200:203], v[28:31]
	v_mfma_f32_16x16x32_bf16 v[24:27], v[148:151], v[200:203], v[24:27]
	v_mfma_f32_16x16x32_bf16 v[20:23], v[156:159], v[200:203], v[20:23]
	ds_read_b128 v[200:203], v229 offset:36864
	v_mfma_f32_16x16x32_bf16 v[16:19], v[132:135], v[208:211], v[16:19]
	v_mfma_f32_16x16x32_bf16 v[12:15], v[140:143], v[208:211], v[12:15]
	v_mfma_f32_16x16x32_bf16 v[8:11], v[148:151], v[208:211], v[8:11]
	v_mfma_f32_16x16x32_bf16 v[4:7], v[156:159], v[208:211], v[4:7]
	ds_read_b128 v[208:211], v229 offset:38912
	v_mfma_f32_16x16x32_bf16 v[64:67], v[136:139], v[168:171], v[64:67]
	v_mfma_f32_16x16x32_bf16 v[60:63], v[144:147], v[168:171], v[60:63]
	v_mfma_f32_16x16x32_bf16 v[56:59], v[152:155], v[168:171], v[56:59]
	v_mfma_f32_16x16x32_bf16 v[52:55], v[160:163], v[168:171], v[52:55]
	ds_read_b128 v[168:171], v229 offset:33792
	v_mfma_f32_16x16x32_bf16 v[48:51], v[136:139], v[176:179], v[48:51]
	v_mfma_f32_16x16x32_bf16 v[44:47], v[144:147], v[176:179], v[44:47]
	v_mfma_f32_16x16x32_bf16 v[40:43], v[152:155], v[176:179], v[40:43]
	v_mfma_f32_16x16x32_bf16 v[36:39], v[160:163], v[176:179], v[36:39]
	ds_read_b128 v[176:179], v229 offset:35840
	v_mfma_f32_16x16x32_bf16 v[32:35], v[136:139], v[204:207], v[32:35]
	v_mfma_f32_16x16x32_bf16 v[28:31], v[144:147], v[204:207], v[28:31]
	v_mfma_f32_16x16x32_bf16 v[24:27], v[152:155], v[204:207], v[24:27]
	v_mfma_f32_16x16x32_bf16 v[20:23], v[160:163], v[204:207], v[20:23]
	ds_read_b128 v[204:207], v229 offset:37888
	v_mfma_f32_16x16x32_bf16 v[16:19], v[136:139], v[218:221], v[16:19]
	v_mfma_f32_16x16x32_bf16 v[12:15], v[144:147], v[218:221], v[12:15]
	v_mfma_f32_16x16x32_bf16 v[8:11], v[152:155], v[218:221], v[8:11]
	v_mfma_f32_16x16x32_bf16 v[4:7], v[160:163], v[218:221], v[4:7]
	ds_read_b128 v[218:221], v229 offset:39936
	s_setprio 0
	s_waitcnt vmcnt(6)
	s_barrier
	s_add_i32 s40, 0, 0x18000
	s_add_i32 s41, 0, 0x1c000
	v_add_u32_e32 v144, s40, v187
	v_add_u32_e32 v160, s41, v187
	ds_read_b128 v[132:135], v144
	ds_read_b128 v[136:139], v144 offset:1024
	ds_read_b128 v[140:143], v144 offset:2048
	ds_read_b128 v[144:147], v144 offset:3072
	ds_read_b128 v[148:151], v160
	ds_read_b128 v[152:155], v160 offset:1024
	ds_read_b128 v[156:159], v160 offset:2048
	ds_read_b128 v[160:163], v160 offset:3072
	s_add_u32 s26, s46, 0xb0000
	s_addc_u32 s27, s47, 0
	s_mov_b32 m0, s51
	v_lshl_add_u64 v[232:233], s[26:27], 0, v[194:195]
	global_load_lds_dwordx4 v[232:233], off
	v_lshl_add_u64 v[232:233], s[26:27], 0, v[190:191]
	s_mov_b32 m0, s53
	s_nop 0
	global_load_lds_dwordx4 v[232:233], off
	s_waitcnt vmcnt(8)
	s_waitcnt lgkmcnt(0)
	s_barrier
	s_setprio 1
	s_waitcnt lgkmcnt(0)
	v_mfma_f32_16x16x32_bf16 v[128:131], v[132:135], v[164:167], v[128:131]
	v_mfma_f32_16x16x32_bf16 v[124:127], v[140:143], v[164:167], v[124:127]
	v_mfma_f32_16x16x32_bf16 v[120:123], v[148:151], v[164:167], v[120:123]
	v_mfma_f32_16x16x32_bf16 v[116:119], v[156:159], v[164:167], v[116:119]
	ds_read_b128 v[164:167], v229 offset:49152
	v_mfma_f32_16x16x32_bf16 v[112:115], v[132:135], v[172:175], v[112:115]
	v_mfma_f32_16x16x32_bf16 v[108:111], v[140:143], v[172:175], v[108:111]
	v_mfma_f32_16x16x32_bf16 v[104:107], v[148:151], v[172:175], v[104:107]
	v_mfma_f32_16x16x32_bf16 v[100:103], v[156:159], v[172:175], v[100:103]
	ds_read_b128 v[172:175], v229 offset:51200
	v_mfma_f32_16x16x32_bf16 v[96:99], v[132:135], v[200:203], v[96:99]
	v_mfma_f32_16x16x32_bf16 v[92:95], v[140:143], v[200:203], v[92:95]
	v_mfma_f32_16x16x32_bf16 v[88:91], v[148:151], v[200:203], v[88:91]
	v_mfma_f32_16x16x32_bf16 v[84:87], v[156:159], v[200:203], v[84:87]
	ds_read_b128 v[200:203], v229 offset:53248
	v_mfma_f32_16x16x32_bf16 v[80:83], v[132:135], v[208:211], v[80:83]
	v_mfma_f32_16x16x32_bf16 v[76:79], v[140:143], v[208:211], v[76:79]
	v_mfma_f32_16x16x32_bf16 v[72:75], v[148:151], v[208:211], v[72:75]
	v_mfma_f32_16x16x32_bf16 v[68:71], v[156:159], v[208:211], v[68:71]
	ds_read_b128 v[208:211], v229 offset:55296
	v_mfma_f32_16x16x32_bf16 v[128:131], v[136:139], v[168:171], v[128:131]
	v_mfma_f32_16x16x32_bf16 v[124:127], v[144:147], v[168:171], v[124:127]
	v_mfma_f32_16x16x32_bf16 v[120:123], v[152:155], v[168:171], v[120:123]
	v_mfma_f32_16x16x32_bf16 v[116:119], v[160:163], v[168:171], v[116:119]
	ds_read_b128 v[168:171], v229 offset:50176
	v_mfma_f32_16x16x32_bf16 v[112:115], v[136:139], v[176:179], v[112:115]
	v_mfma_f32_16x16x32_bf16 v[108:111], v[144:147], v[176:179], v[108:111]
	v_mfma_f32_16x16x32_bf16 v[104:107], v[152:155], v[176:179], v[104:107]
	v_mfma_f32_16x16x32_bf16 v[100:103], v[160:163], v[176:179], v[100:103]
	ds_read_b128 v[176:179], v229 offset:52224
	v_mfma_f32_16x16x32_bf16 v[96:99], v[136:139], v[204:207], v[96:99]
	v_mfma_f32_16x16x32_bf16 v[92:95], v[144:147], v[204:207], v[92:95]
	v_mfma_f32_16x16x32_bf16 v[88:91], v[152:155], v[204:207], v[88:91]
	v_mfma_f32_16x16x32_bf16 v[84:87], v[160:163], v[204:207], v[84:87]
	ds_read_b128 v[204:207], v229 offset:54272
	v_mfma_f32_16x16x32_bf16 v[80:83], v[136:139], v[218:221], v[80:83]
	v_mfma_f32_16x16x32_bf16 v[76:79], v[144:147], v[218:221], v[76:79]
	v_mfma_f32_16x16x32_bf16 v[72:75], v[152:155], v[218:221], v[72:75]
	v_mfma_f32_16x16x32_bf16 v[68:71], v[160:163], v[218:221], v[68:71]
	ds_read_b128 v[218:221], v229 offset:56320
	s_setprio 0
	s_waitcnt vmcnt(2)
	s_barrier
	s_add_i32 s26, s40, s48
	v_lshl_add_u64 v[182:183], v[182:183], 0, s[94:95]
	s_mov_b32 m0, s26
	global_load_lds_dwordx4 v[182:183], off
	s_add_i32 m0, s26, 0x2000
	s_add_u32 s26, s44, 0xb0080
	v_lshl_add_u64 v[182:183], v[184:185], 0, s[94:95]
	s_addc_u32 s27, s45, 0
	s_add_i32 s40, s41, s48
	global_load_lds_dwordx4 v[182:183], off
	v_lshl_add_u64 v[182:183], s[26:27], 0, v[192:193]
	s_mov_b32 m0, s40
	s_nop 0
	global_load_lds_dwordx4 v[182:183], off
	v_lshl_add_u64 v[182:183], s[26:27], 0, v[0:1]
	s_add_i32 m0, s40, 0x2000
	s_nop 0
	global_load_lds_dwordx4 v[182:183], off
	v_lshl_add_u64 v[182:183], v[224:225], 0, s[94:95]
	s_mov_b32 m0, s54
	s_nop 0
	global_load_lds_dwordx4 v[182:183], off
	v_lshl_add_u64 v[182:183], v[230:231], 0, s[94:95]
	s_mov_b32 m0, s55
	s_nop 0
	global_load_lds_dwordx4 v[182:183], off
	s_waitcnt vmcnt(8)
	s_waitcnt lgkmcnt(0)
	s_barrier
	s_setprio 1
	s_waitcnt lgkmcnt(0)
	v_mfma_f32_16x16x32_bf16 v[64:67], v[132:135], v[164:167], v[64:67]
	v_mfma_f32_16x16x32_bf16 v[60:63], v[140:143], v[164:167], v[60:63]
	v_mfma_f32_16x16x32_bf16 v[56:59], v[148:151], v[164:167], v[56:59]
	v_mfma_f32_16x16x32_bf16 v[52:55], v[156:159], v[164:167], v[52:55]
	ds_read_b128 v[164:167], v229
	v_mfma_f32_16x16x32_bf16 v[48:51], v[132:135], v[172:175], v[48:51]
	v_mfma_f32_16x16x32_bf16 v[44:47], v[140:143], v[172:175], v[44:47]
	v_mfma_f32_16x16x32_bf16 v[40:43], v[148:151], v[172:175], v[40:43]
	v_mfma_f32_16x16x32_bf16 v[36:39], v[156:159], v[172:175], v[36:39]
	ds_read_b128 v[172:175], v229 offset:2048
	v_mfma_f32_16x16x32_bf16 v[32:35], v[132:135], v[200:203], v[32:35]
	v_mfma_f32_16x16x32_bf16 v[28:31], v[140:143], v[200:203], v[28:31]
	v_mfma_f32_16x16x32_bf16 v[24:27], v[148:151], v[200:203], v[24:27]
	v_mfma_f32_16x16x32_bf16 v[20:23], v[156:159], v[200:203], v[20:23]
	ds_read_b128 v[200:203], v229 offset:4096
	v_mfma_f32_16x16x32_bf16 v[16:19], v[132:135], v[208:211], v[16:19]
	v_mfma_f32_16x16x32_bf16 v[12:15], v[140:143], v[208:211], v[12:15]
	v_mfma_f32_16x16x32_bf16 v[8:11], v[148:151], v[208:211], v[8:11]
	v_mfma_f32_16x16x32_bf16 v[4:7], v[156:159], v[208:211], v[4:7]
	ds_read_b128 v[208:211], v229 offset:6144
	v_mfma_f32_16x16x32_bf16 v[64:67], v[136:139], v[168:171], v[64:67]
	v_mfma_f32_16x16x32_bf16 v[60:63], v[144:147], v[168:171], v[60:63]
	v_mfma_f32_16x16x32_bf16 v[56:59], v[152:155], v[168:171], v[56:59]
	v_mfma_f32_16x16x32_bf16 v[52:55], v[160:163], v[168:171], v[52:55]
	ds_read_b128 v[168:171], v229 offset:1024
	v_mfma_f32_16x16x32_bf16 v[48:51], v[136:139], v[176:179], v[48:51]
	v_mfma_f32_16x16x32_bf16 v[44:47], v[144:147], v[176:179], v[44:47]
	v_mfma_f32_16x16x32_bf16 v[40:43], v[152:155], v[176:179], v[40:43]
	v_mfma_f32_16x16x32_bf16 v[36:39], v[160:163], v[176:179], v[36:39]
	ds_read_b128 v[176:179], v229 offset:3072
	v_mfma_f32_16x16x32_bf16 v[32:35], v[136:139], v[204:207], v[32:35]
	v_mfma_f32_16x16x32_bf16 v[28:31], v[144:147], v[204:207], v[28:31]
	v_mfma_f32_16x16x32_bf16 v[24:27], v[152:155], v[204:207], v[24:27]
	v_mfma_f32_16x16x32_bf16 v[20:23], v[160:163], v[204:207], v[20:23]
	ds_read_b128 v[204:207], v229 offset:5120
	v_mfma_f32_16x16x32_bf16 v[16:19], v[136:139], v[218:221], v[16:19]
	v_mfma_f32_16x16x32_bf16 v[12:15], v[144:147], v[218:221], v[12:15]
	v_mfma_f32_16x16x32_bf16 v[8:11], v[152:155], v[218:221], v[8:11]
	v_mfma_f32_16x16x32_bf16 v[4:7], v[160:163], v[218:221], v[4:7]
	ds_read_b128 v[218:221], v229 offset:7168
	s_setprio 0
	s_waitcnt vmcnt(6)
	s_barrier
	s_add_i32 s69, s69, 2
	s_add_u32 s65, s65, 0x100
	s_addc_u32 s68, s68, 0
	s_cmp_gt_u32 s69, 41
	s_mov_b64 s[26:27], s[36:37]
	s_cbranch_scc0 .LBB0_668
	s_waitcnt lgkmcnt(0)
	s_and_b64 vcc, exec, s[14:15]
	s_cbranch_vccz .LBB0_671
	s_barrier
